# GEMM main loops: back edge rotated (counter, pointer bumps and exit test moved in front of the loop-back barrier; only the branch follows it)
# speedup vs baseline: 1.0034x; 1.0001x over previous
.LBB1_93:
	s_ashr_i32 s19, s18, 31
	s_lshl_b64 s[20:21], s[18:19], 19
	s_add_u32 s20, s33, s20
	s_addc_u32 s21, s34, s21
	s_and_b64 s[22:23], s[0:1], exec
	s_cselect_b32 s5, s21, s27
	s_cselect_b32 s19, s20, s26
	s_ashr_i32 s17, s16, 31
	s_lshl_b64 s[22:23], s[16:17], 19
	s_add_u32 s22, s35, s22
	s_addc_u32 s23, s36, s23
	s_and_b64 s[30:31], s[0:1], exec
	s_cselect_b32 s17, s23, s29
	s_cselect_b32 s25, s22, s28
	s_add_u32 s26, s26, 0x40080
	s_addc_u32 s27, s27, 0
	s_add_u32 s52, s28, 0x100
	s_addc_u32 s53, s29, 0
	s_mov_b32 s54, -2
	ds_read_b128 v[148:151], v153
	ds_read_b128 v[156:159], v153 offset:1024
	ds_read_b128 v[160:163], v153 offset:2048
	ds_read_b128 v[164:167], v153 offset:3072
	ds_read_b128 v[168:171], v154
	ds_read_b128 v[172:175], v154 offset:1024
	ds_read_b128 v[176:179], v154 offset:2048
	ds_read_b128 v[180:183], v154 offset:3072
	s_add_u32 s28, s26, 0xfffc0080
	s_addc_u32 s29, s27, -1
	s_cmp_eq_u32 s54, 12
	s_cselect_b32 s31, s5, s29
	s_cselect_b32 s30, s19, s28
	s_cselect_b32 s29, s17, s53
	s_cselect_b32 s28, s25, s52
	v_lshl_add_u64 v[216:217], s[26:27], 0, v[140:141]
	s_add_i32 m0, s38, 0xc000
	ds_read_b128 v[184:187], v155
	ds_read_b128 v[188:191], v155 offset:1024
	ds_read_b128 v[192:195], v155 offset:2048
	ds_read_b128 v[196:199], v155 offset:3072
	ds_read_b128 v[200:203], v155 offset:4096
	ds_read_b128 v[204:207], v155 offset:5120
	ds_read_b128 v[208:211], v155 offset:6144
	ds_read_b128 v[212:215], v155 offset:7168
	global_load_lds_dwordx4 v[216:217], off
	v_lshl_add_u64 v[216:217], s[26:27], 0, v[142:143]
	s_add_i32 m0, s38, 0xe000
	s_nop 0
	global_load_lds_dwordx4 v[216:217], off
	s_waitcnt vmcnt(8)
	s_waitcnt lgkmcnt(0)
	s_barrier
	s_waitcnt lgkmcnt(0)
	v_mfma_f32_16x16x32_bf16 v[124:127], v[148:151], v[184:187], 0
	v_mfma_f32_16x16x32_bf16 v[120:123], v[160:163], v[184:187], 0
	v_mfma_f32_16x16x32_bf16 v[108:111], v[148:151], v[192:195], 0
	v_mfma_f32_16x16x32_bf16 v[104:107], v[160:163], v[192:195], 0
	v_mfma_f32_16x16x32_bf16 v[92:95], v[148:151], v[200:203], 0
	v_mfma_f32_16x16x32_bf16 v[88:91], v[160:163], v[200:203], 0
	v_mfma_f32_16x16x32_bf16 v[76:79], v[148:151], v[208:211], 0
	v_mfma_f32_16x16x32_bf16 v[72:75], v[160:163], v[208:211], 0
	v_mfma_f32_16x16x32_bf16 v[124:127], v[156:159], v[188:191], v[124:127]
	v_mfma_f32_16x16x32_bf16 v[120:123], v[164:167], v[188:191], v[120:123]
	v_mfma_f32_16x16x32_bf16 v[108:111], v[156:159], v[196:199], v[108:111]
	v_mfma_f32_16x16x32_bf16 v[104:107], v[164:167], v[196:199], v[104:107]
	v_mfma_f32_16x16x32_bf16 v[92:95], v[156:159], v[204:207], v[92:95]
	v_mfma_f32_16x16x32_bf16 v[88:91], v[164:167], v[204:207], v[88:91]
	v_mfma_f32_16x16x32_bf16 v[76:79], v[156:159], v[212:215], v[76:79]
	v_mfma_f32_16x16x32_bf16 v[72:75], v[164:167], v[212:215], v[72:75]
	v_mfma_f32_16x16x32_bf16 v[116:119], v[168:171], v[184:187], 0
	v_mfma_f32_16x16x32_bf16 v[112:115], v[176:179], v[184:187], 0
	v_mfma_f32_16x16x32_bf16 v[100:103], v[168:171], v[192:195], 0
	v_mfma_f32_16x16x32_bf16 v[96:99], v[176:179], v[192:195], 0
	v_mfma_f32_16x16x32_bf16 v[84:87], v[168:171], v[200:203], 0
	v_mfma_f32_16x16x32_bf16 v[80:83], v[176:179], v[200:203], 0
	v_mfma_f32_16x16x32_bf16 v[68:71], v[168:171], v[208:211], 0
	v_mfma_f32_16x16x32_bf16 v[64:67], v[176:179], v[208:211], 0
	v_mfma_f32_16x16x32_bf16 v[116:119], v[172:175], v[188:191], v[116:119]
	v_mfma_f32_16x16x32_bf16 v[112:115], v[180:183], v[188:191], v[112:115]
	v_mfma_f32_16x16x32_bf16 v[100:103], v[172:175], v[196:199], v[100:103]
	v_mfma_f32_16x16x32_bf16 v[96:99], v[180:183], v[196:199], v[96:99]
	v_mfma_f32_16x16x32_bf16 v[84:87], v[172:175], v[204:207], v[84:87]
	v_mfma_f32_16x16x32_bf16 v[80:83], v[180:183], v[204:207], v[80:83]
	v_mfma_f32_16x16x32_bf16 v[68:71], v[172:175], v[212:215], v[68:71]
	v_mfma_f32_16x16x32_bf16 v[64:67], v[180:183], v[212:215], v[64:67]
	s_barrier
	s_add_i32 s55, s48, s37
	v_lshl_add_u64 v[216:217], s[28:29], 0, v[130:131]
	s_mov_b32 m0, s55
	ds_read_b128 v[184:187], v155 offset:16384
	ds_read_b128 v[188:191], v155 offset:17408
	ds_read_b128 v[192:195], v155 offset:18432
	ds_read_b128 v[196:199], v155 offset:19456
	ds_read_b128 v[200:203], v155 offset:20480
	ds_read_b128 v[204:207], v155 offset:21504
	ds_read_b128 v[208:211], v155 offset:22528
	ds_read_b128 v[212:215], v155 offset:23552
	global_load_lds_dwordx4 v[216:217], off
	s_add_i32 m0, s55, 0x2000
	s_add_u32 s56, s28, 0x40000
	v_lshl_add_u64 v[218:219], s[28:29], 0, v[134:135]
	s_addc_u32 s57, s29, 0
	s_add_i32 s55, s49, s37
	global_load_lds_dwordx4 v[218:219], off
	v_lshl_add_u64 v[220:221], s[56:57], 0, v[130:131]
	s_mov_b32 m0, s55
	v_lshl_add_u64 v[222:223], s[30:31], 0, v[132:133]
	global_load_lds_dwordx4 v[220:221], off
	v_lshl_add_u64 v[220:221], s[56:57], 0, v[134:135]
	s_add_i32 m0, s55, 0x2000
	s_nop 0
	global_load_lds_dwordx4 v[220:221], off
	v_lshl_add_u64 v[220:221], s[30:31], 0, v[128:129]
	s_mov_b32 m0, s38
	s_nop 0
	global_load_lds_dwordx4 v[220:221], off
	s_mov_b32 m0, s39
	s_nop 0
	global_load_lds_dwordx4 v[222:223], off
	s_waitcnt vmcnt(8)
	s_waitcnt lgkmcnt(0)
	s_barrier
	s_waitcnt lgkmcnt(0)
	v_mfma_f32_16x16x32_bf16 v[60:63], v[148:151], v[184:187], 0
	v_mfma_f32_16x16x32_bf16 v[56:59], v[160:163], v[184:187], 0
	v_mfma_f32_16x16x32_bf16 v[44:47], v[148:151], v[192:195], 0
	v_mfma_f32_16x16x32_bf16 v[40:43], v[160:163], v[192:195], 0
	v_mfma_f32_16x16x32_bf16 v[28:31], v[148:151], v[200:203], 0
	v_mfma_f32_16x16x32_bf16 v[24:27], v[160:163], v[200:203], 0
	v_mfma_f32_16x16x32_bf16 v[12:15], v[148:151], v[208:211], 0
	v_mfma_f32_16x16x32_bf16 v[8:11], v[160:163], v[208:211], 0
	v_mfma_f32_16x16x32_bf16 v[60:63], v[156:159], v[188:191], v[60:63]
	v_mfma_f32_16x16x32_bf16 v[56:59], v[164:167], v[188:191], v[56:59]
	v_mfma_f32_16x16x32_bf16 v[44:47], v[156:159], v[196:199], v[44:47]
	v_mfma_f32_16x16x32_bf16 v[40:43], v[164:167], v[196:199], v[40:43]
	v_mfma_f32_16x16x32_bf16 v[28:31], v[156:159], v[204:207], v[28:31]
	v_mfma_f32_16x16x32_bf16 v[24:27], v[164:167], v[204:207], v[24:27]
	v_mfma_f32_16x16x32_bf16 v[12:15], v[156:159], v[212:215], v[12:15]
	v_mfma_f32_16x16x32_bf16 v[8:11], v[164:167], v[212:215], v[8:11]
	v_mfma_f32_16x16x32_bf16 v[52:55], v[168:171], v[184:187], 0
	v_mfma_f32_16x16x32_bf16 v[48:51], v[176:179], v[184:187], 0
	v_mfma_f32_16x16x32_bf16 v[36:39], v[168:171], v[192:195], 0
	v_mfma_f32_16x16x32_bf16 v[32:35], v[176:179], v[192:195], 0
	v_mfma_f32_16x16x32_bf16 v[20:23], v[168:171], v[200:203], 0
	v_mfma_f32_16x16x32_bf16 v[16:19], v[176:179], v[200:203], 0
	v_mfma_f32_16x16x32_bf16 v[4:7], v[168:171], v[208:211], 0
	v_mfma_f32_16x16x32_bf16 v[0:3], v[176:179], v[208:211], 0
	v_mfma_f32_16x16x32_bf16 v[52:55], v[172:175], v[188:191], v[52:55]
	v_mfma_f32_16x16x32_bf16 v[48:51], v[180:183], v[188:191], v[48:51]
	v_mfma_f32_16x16x32_bf16 v[36:39], v[172:175], v[196:199], v[36:39]
	v_mfma_f32_16x16x32_bf16 v[32:35], v[180:183], v[196:199], v[32:35]
	v_mfma_f32_16x16x32_bf16 v[20:23], v[172:175], v[204:207], v[20:23]
	v_mfma_f32_16x16x32_bf16 v[16:19], v[180:183], v[204:207], v[16:19]
	v_mfma_f32_16x16x32_bf16 v[4:7], v[172:175], v[212:215], v[4:7]
	v_mfma_f32_16x16x32_bf16 v[0:3], v[180:183], v[212:215], v[0:3]
	s_barrier
	s_add_i32 s55, 0, 0x18000
	s_add_i32 s56, 0, 0x1c000
	v_add_u32_e32 v164, s55, v152
	v_add_u32_e32 v180, s56, v152
	ds_read_b128 v[148:151], v164
	ds_read_b128 v[156:159], v164 offset:1024
	ds_read_b128 v[160:163], v164 offset:2048
	ds_read_b128 v[164:167], v164 offset:3072
	ds_read_b128 v[168:171], v180
	ds_read_b128 v[172:175], v180 offset:1024
	ds_read_b128 v[176:179], v180 offset:2048
	ds_read_b128 v[180:183], v180 offset:3072
	s_add_u32 s30, s30, 0x40000
	s_addc_u32 s31, s31, 0
	s_mov_b32 m0, s40
	v_lshl_add_u64 v[224:225], s[30:31], 0, v[128:129]
	ds_read_b128 v[184:187], v155 offset:32768
	ds_read_b128 v[188:191], v155 offset:33792
	ds_read_b128 v[192:195], v155 offset:34816
	ds_read_b128 v[196:199], v155 offset:35840
	ds_read_b128 v[200:203], v155 offset:36864
	ds_read_b128 v[204:207], v155 offset:37888
	ds_read_b128 v[208:211], v155 offset:38912
	ds_read_b128 v[212:215], v155 offset:39936
	global_load_lds_dwordx4 v[224:225], off
	v_lshl_add_u64 v[224:225], s[30:31], 0, v[132:133]
	s_mov_b32 m0, s41
	s_nop 0
	global_load_lds_dwordx4 v[224:225], off
	s_waitcnt vmcnt(8)
	s_waitcnt lgkmcnt(0)
	s_barrier
	s_waitcnt lgkmcnt(0)
	v_mfma_f32_16x16x32_bf16 v[124:127], v[148:151], v[184:187], v[124:127]
	v_mfma_f32_16x16x32_bf16 v[120:123], v[160:163], v[184:187], v[120:123]
	v_mfma_f32_16x16x32_bf16 v[108:111], v[148:151], v[192:195], v[108:111]
	v_mfma_f32_16x16x32_bf16 v[104:107], v[160:163], v[192:195], v[104:107]
	v_mfma_f32_16x16x32_bf16 v[92:95], v[148:151], v[200:203], v[92:95]
	v_mfma_f32_16x16x32_bf16 v[88:91], v[160:163], v[200:203], v[88:91]
	v_mfma_f32_16x16x32_bf16 v[76:79], v[148:151], v[208:211], v[76:79]
	v_mfma_f32_16x16x32_bf16 v[72:75], v[160:163], v[208:211], v[72:75]
	v_mfma_f32_16x16x32_bf16 v[124:127], v[156:159], v[188:191], v[124:127]
	v_mfma_f32_16x16x32_bf16 v[120:123], v[164:167], v[188:191], v[120:123]
	v_mfma_f32_16x16x32_bf16 v[108:111], v[156:159], v[196:199], v[108:111]
	v_mfma_f32_16x16x32_bf16 v[104:107], v[164:167], v[196:199], v[104:107]
	v_mfma_f32_16x16x32_bf16 v[92:95], v[156:159], v[204:207], v[92:95]
	v_mfma_f32_16x16x32_bf16 v[88:91], v[164:167], v[204:207], v[88:91]
	v_mfma_f32_16x16x32_bf16 v[76:79], v[156:159], v[212:215], v[76:79]
	v_mfma_f32_16x16x32_bf16 v[72:75], v[164:167], v[212:215], v[72:75]
	v_mfma_f32_16x16x32_bf16 v[116:119], v[168:171], v[184:187], v[116:119]
	v_mfma_f32_16x16x32_bf16 v[112:115], v[176:179], v[184:187], v[112:115]
	v_mfma_f32_16x16x32_bf16 v[100:103], v[168:171], v[192:195], v[100:103]
	v_mfma_f32_16x16x32_bf16 v[96:99], v[176:179], v[192:195], v[96:99]
	v_mfma_f32_16x16x32_bf16 v[84:87], v[168:171], v[200:203], v[84:87]
	v_mfma_f32_16x16x32_bf16 v[80:83], v[176:179], v[200:203], v[80:83]
	v_mfma_f32_16x16x32_bf16 v[68:71], v[168:171], v[208:211], v[68:71]
	v_mfma_f32_16x16x32_bf16 v[64:67], v[176:179], v[208:211], v[64:67]
	v_mfma_f32_16x16x32_bf16 v[116:119], v[172:175], v[188:191], v[116:119]
	v_mfma_f32_16x16x32_bf16 v[112:115], v[180:183], v[188:191], v[112:115]
	v_mfma_f32_16x16x32_bf16 v[100:103], v[172:175], v[196:199], v[100:103]
	v_mfma_f32_16x16x32_bf16 v[96:99], v[180:183], v[196:199], v[96:99]
	v_mfma_f32_16x16x32_bf16 v[84:87], v[172:175], v[204:207], v[84:87]
	v_mfma_f32_16x16x32_bf16 v[80:83], v[180:183], v[204:207], v[80:83]
	v_mfma_f32_16x16x32_bf16 v[68:71], v[172:175], v[212:215], v[68:71]
	v_mfma_f32_16x16x32_bf16 v[64:67], v[180:183], v[212:215], v[64:67]
	s_barrier
	s_add_i32 s30, s55, s37
	v_lshl_add_u64 v[216:217], v[216:217], 0, s[12:13]
	s_mov_b32 m0, s30
	ds_read_b128 v[184:187], v155 offset:49152
	ds_read_b128 v[188:191], v155 offset:50176
	ds_read_b128 v[192:195], v155 offset:51200
	ds_read_b128 v[196:199], v155 offset:52224
	ds_read_b128 v[200:203], v155 offset:53248
	ds_read_b128 v[204:207], v155 offset:54272
	ds_read_b128 v[208:211], v155 offset:55296
	ds_read_b128 v[212:215], v155 offset:56320
	global_load_lds_dwordx4 v[216:217], off
	s_add_i32 m0, s30, 0x2000
	s_add_u32 s28, s28, 0x40080
	v_lshl_add_u64 v[216:217], v[218:219], 0, s[12:13]
	s_addc_u32 s29, s29, 0
	s_add_i32 s30, s56, s37
	global_load_lds_dwordx4 v[216:217], off
	v_lshl_add_u64 v[216:217], s[28:29], 0, v[130:131]
	s_mov_b32 m0, s30
	s_nop 0
	global_load_lds_dwordx4 v[216:217], off
	v_lshl_add_u64 v[216:217], s[28:29], 0, v[134:135]
	s_add_i32 m0, s30, 0x2000
	s_nop 0
	global_load_lds_dwordx4 v[216:217], off
	v_lshl_add_u64 v[216:217], v[220:221], 0, s[12:13]
	s_mov_b32 m0, s43
	s_nop 0
	global_load_lds_dwordx4 v[216:217], off
	v_lshl_add_u64 v[216:217], v[222:223], 0, s[12:13]
	s_mov_b32 m0, s44
	s_nop 0
	global_load_lds_dwordx4 v[216:217], off
	s_waitcnt vmcnt(8)
	s_waitcnt lgkmcnt(0)
	s_barrier
	s_waitcnt lgkmcnt(0)
	v_mfma_f32_16x16x32_bf16 v[60:63], v[148:151], v[184:187], v[60:63]
	v_mfma_f32_16x16x32_bf16 v[56:59], v[160:163], v[184:187], v[56:59]
	v_mfma_f32_16x16x32_bf16 v[44:47], v[148:151], v[192:195], v[44:47]
	v_mfma_f32_16x16x32_bf16 v[40:43], v[160:163], v[192:195], v[40:43]
	v_mfma_f32_16x16x32_bf16 v[28:31], v[148:151], v[200:203], v[28:31]
	v_mfma_f32_16x16x32_bf16 v[24:27], v[160:163], v[200:203], v[24:27]
	v_mfma_f32_16x16x32_bf16 v[12:15], v[148:151], v[208:211], v[12:15]
	v_mfma_f32_16x16x32_bf16 v[8:11], v[160:163], v[208:211], v[8:11]
	v_mfma_f32_16x16x32_bf16 v[60:63], v[156:159], v[188:191], v[60:63]
	v_mfma_f32_16x16x32_bf16 v[56:59], v[164:167], v[188:191], v[56:59]
	v_mfma_f32_16x16x32_bf16 v[44:47], v[156:159], v[196:199], v[44:47]
	v_mfma_f32_16x16x32_bf16 v[40:43], v[164:167], v[196:199], v[40:43]
	v_mfma_f32_16x16x32_bf16 v[28:31], v[156:159], v[204:207], v[28:31]
	v_mfma_f32_16x16x32_bf16 v[24:27], v[164:167], v[204:207], v[24:27]
	v_mfma_f32_16x16x32_bf16 v[12:15], v[156:159], v[212:215], v[12:15]
	v_mfma_f32_16x16x32_bf16 v[8:11], v[164:167], v[212:215], v[8:11]
	v_mfma_f32_16x16x32_bf16 v[52:55], v[168:171], v[184:187], v[52:55]
	v_mfma_f32_16x16x32_bf16 v[48:51], v[176:179], v[184:187], v[48:51]
	v_mfma_f32_16x16x32_bf16 v[36:39], v[168:171], v[192:195], v[36:39]
	v_mfma_f32_16x16x32_bf16 v[32:35], v[176:179], v[192:195], v[32:35]
	v_mfma_f32_16x16x32_bf16 v[20:23], v[168:171], v[200:203], v[20:23]
	v_mfma_f32_16x16x32_bf16 v[16:19], v[176:179], v[200:203], v[16:19]
	v_mfma_f32_16x16x32_bf16 v[4:7], v[168:171], v[208:211], v[4:7]
	v_mfma_f32_16x16x32_bf16 v[0:3], v[176:179], v[208:211], v[0:3]
	v_mfma_f32_16x16x32_bf16 v[52:55], v[172:175], v[188:191], v[52:55]
	v_mfma_f32_16x16x32_bf16 v[48:51], v[180:183], v[188:191], v[48:51]
	v_mfma_f32_16x16x32_bf16 v[36:39], v[172:175], v[196:199], v[36:39]
	v_mfma_f32_16x16x32_bf16 v[32:35], v[180:183], v[196:199], v[32:35]
	v_mfma_f32_16x16x32_bf16 v[20:23], v[172:175], v[204:207], v[20:23]
	v_mfma_f32_16x16x32_bf16 v[16:19], v[180:183], v[204:207], v[16:19]
	v_mfma_f32_16x16x32_bf16 v[4:7], v[172:175], v[212:215], v[4:7]
	v_mfma_f32_16x16x32_bf16 v[0:3], v[180:183], v[212:215], v[0:3]
	s_add_i32 s54, s54, 2
	s_add_u32 s26, s26, 0x100
	s_addc_u32 s27, s27, 0
	s_add_u32 s52, s52, 0x100
	s_addc_u32 s53, s53, 0
	s_cmp_gt_u32 s54, 13
	s_barrier
.LBB1_94:
	ds_read_b128 v[148:151], v153
	ds_read_b128 v[156:159], v153 offset:1024
	ds_read_b128 v[160:163], v153 offset:2048
	ds_read_b128 v[164:167], v153 offset:3072
	ds_read_b128 v[168:171], v154
	ds_read_b128 v[172:175], v154 offset:1024
	ds_read_b128 v[176:179], v154 offset:2048
	ds_read_b128 v[180:183], v154 offset:3072
	s_add_u32 s28, s26, 0xfffc0080
	s_addc_u32 s29, s27, -1
	s_cmp_eq_u32 s54, 12
	s_cselect_b32 s31, s5, s29
	s_cselect_b32 s30, s19, s28
	s_cselect_b32 s29, s17, s53
	s_cselect_b32 s28, s25, s52
	v_lshl_add_u64 v[216:217], s[26:27], 0, v[140:141]
	s_add_i32 m0, s38, 0xc000
	ds_read_b128 v[184:187], v155
	ds_read_b128 v[188:191], v155 offset:1024
	ds_read_b128 v[192:195], v155 offset:2048
	ds_read_b128 v[196:199], v155 offset:3072
	ds_read_b128 v[200:203], v155 offset:4096
	ds_read_b128 v[204:207], v155 offset:5120
	ds_read_b128 v[208:211], v155 offset:6144
	ds_read_b128 v[212:215], v155 offset:7168
	global_load_lds_dwordx4 v[216:217], off
	v_lshl_add_u64 v[216:217], s[26:27], 0, v[142:143]
	s_add_i32 m0, s38, 0xe000
	s_nop 0
	global_load_lds_dwordx4 v[216:217], off
	s_waitcnt vmcnt(8)
	s_waitcnt lgkmcnt(0)
	s_barrier
	s_waitcnt lgkmcnt(0)
	v_mfma_f32_16x16x32_bf16 v[124:127], v[148:151], v[184:187], v[124:127]
	v_mfma_f32_16x16x32_bf16 v[120:123], v[160:163], v[184:187], v[120:123]
	v_mfma_f32_16x16x32_bf16 v[108:111], v[148:151], v[192:195], v[108:111]
	v_mfma_f32_16x16x32_bf16 v[104:107], v[160:163], v[192:195], v[104:107]
	v_mfma_f32_16x16x32_bf16 v[92:95], v[148:151], v[200:203], v[92:95]
	v_mfma_f32_16x16x32_bf16 v[88:91], v[160:163], v[200:203], v[88:91]
	v_mfma_f32_16x16x32_bf16 v[76:79], v[148:151], v[208:211], v[76:79]
	v_mfma_f32_16x16x32_bf16 v[72:75], v[160:163], v[208:211], v[72:75]
	v_mfma_f32_16x16x32_bf16 v[124:127], v[156:159], v[188:191], v[124:127]
	v_mfma_f32_16x16x32_bf16 v[120:123], v[164:167], v[188:191], v[120:123]
	v_mfma_f32_16x16x32_bf16 v[108:111], v[156:159], v[196:199], v[108:111]
	v_mfma_f32_16x16x32_bf16 v[104:107], v[164:167], v[196:199], v[104:107]
	v_mfma_f32_16x16x32_bf16 v[92:95], v[156:159], v[204:207], v[92:95]
	v_mfma_f32_16x16x32_bf16 v[88:91], v[164:167], v[204:207], v[88:91]
	v_mfma_f32_16x16x32_bf16 v[76:79], v[156:159], v[212:215], v[76:79]
	v_mfma_f32_16x16x32_bf16 v[72:75], v[164:167], v[212:215], v[72:75]
	v_mfma_f32_16x16x32_bf16 v[116:119], v[168:171], v[184:187], v[116:119]
	v_mfma_f32_16x16x32_bf16 v[112:115], v[176:179], v[184:187], v[112:115]
	v_mfma_f32_16x16x32_bf16 v[100:103], v[168:171], v[192:195], v[100:103]
	v_mfma_f32_16x16x32_bf16 v[96:99], v[176:179], v[192:195], v[96:99]
	v_mfma_f32_16x16x32_bf16 v[84:87], v[168:171], v[200:203], v[84:87]
	v_mfma_f32_16x16x32_bf16 v[80:83], v[176:179], v[200:203], v[80:83]
	v_mfma_f32_16x16x32_bf16 v[68:71], v[168:171], v[208:211], v[68:71]
	v_mfma_f32_16x16x32_bf16 v[64:67], v[176:179], v[208:211], v[64:67]
	v_mfma_f32_16x16x32_bf16 v[116:119], v[172:175], v[188:191], v[116:119]
	v_mfma_f32_16x16x32_bf16 v[112:115], v[180:183], v[188:191], v[112:115]
	v_mfma_f32_16x16x32_bf16 v[100:103], v[172:175], v[196:199], v[100:103]
	v_mfma_f32_16x16x32_bf16 v[96:99], v[180:183], v[196:199], v[96:99]
	v_mfma_f32_16x16x32_bf16 v[84:87], v[172:175], v[204:207], v[84:87]
	v_mfma_f32_16x16x32_bf16 v[80:83], v[180:183], v[204:207], v[80:83]
	v_mfma_f32_16x16x32_bf16 v[68:71], v[172:175], v[212:215], v[68:71]
	v_mfma_f32_16x16x32_bf16 v[64:67], v[180:183], v[212:215], v[64:67]
	s_barrier
	s_add_i32 s55, s48, s37
	v_lshl_add_u64 v[216:217], s[28:29], 0, v[130:131]
	s_mov_b32 m0, s55
	ds_read_b128 v[184:187], v155 offset:16384
	ds_read_b128 v[188:191], v155 offset:17408
	ds_read_b128 v[192:195], v155 offset:18432
	ds_read_b128 v[196:199], v155 offset:19456
	ds_read_b128 v[200:203], v155 offset:20480
	ds_read_b128 v[204:207], v155 offset:21504
	ds_read_b128 v[208:211], v155 offset:22528
	ds_read_b128 v[212:215], v155 offset:23552
	global_load_lds_dwordx4 v[216:217], off
	s_add_i32 m0, s55, 0x2000
	s_add_u32 s56, s28, 0x40000
	v_lshl_add_u64 v[218:219], s[28:29], 0, v[134:135]
	s_addc_u32 s57, s29, 0
	s_add_i32 s55, s49, s37
	global_load_lds_dwordx4 v[218:219], off
	v_lshl_add_u64 v[220:221], s[56:57], 0, v[130:131]
	s_mov_b32 m0, s55
	v_lshl_add_u64 v[222:223], s[30:31], 0, v[132:133]
	global_load_lds_dwordx4 v[220:221], off
	v_lshl_add_u64 v[220:221], s[56:57], 0, v[134:135]
	s_add_i32 m0, s55, 0x2000
	s_nop 0
	global_load_lds_dwordx4 v[220:221], off
	v_lshl_add_u64 v[220:221], s[30:31], 0, v[128:129]
	s_mov_b32 m0, s38
	s_nop 0
	global_load_lds_dwordx4 v[220:221], off
	s_mov_b32 m0, s39
	s_nop 0
	global_load_lds_dwordx4 v[222:223], off
	s_waitcnt vmcnt(8)
	s_waitcnt lgkmcnt(0)
	s_barrier
	s_waitcnt lgkmcnt(0)
	v_mfma_f32_16x16x32_bf16 v[60:63], v[148:151], v[184:187], v[60:63]
	v_mfma_f32_16x16x32_bf16 v[56:59], v[160:163], v[184:187], v[56:59]
	v_mfma_f32_16x16x32_bf16 v[44:47], v[148:151], v[192:195], v[44:47]
	v_mfma_f32_16x16x32_bf16 v[40:43], v[160:163], v[192:195], v[40:43]
	v_mfma_f32_16x16x32_bf16 v[28:31], v[148:151], v[200:203], v[28:31]
	v_mfma_f32_16x16x32_bf16 v[24:27], v[160:163], v[200:203], v[24:27]
	v_mfma_f32_16x16x32_bf16 v[12:15], v[148:151], v[208:211], v[12:15]
	v_mfma_f32_16x16x32_bf16 v[8:11], v[160:163], v[208:211], v[8:11]
	v_mfma_f32_16x16x32_bf16 v[60:63], v[156:159], v[188:191], v[60:63]
	v_mfma_f32_16x16x32_bf16 v[56:59], v[164:167], v[188:191], v[56:59]
	v_mfma_f32_16x16x32_bf16 v[44:47], v[156:159], v[196:199], v[44:47]
	v_mfma_f32_16x16x32_bf16 v[40:43], v[164:167], v[196:199], v[40:43]
	v_mfma_f32_16x16x32_bf16 v[28:31], v[156:159], v[204:207], v[28:31]
	v_mfma_f32_16x16x32_bf16 v[24:27], v[164:167], v[204:207], v[24:27]
	v_mfma_f32_16x16x32_bf16 v[12:15], v[156:159], v[212:215], v[12:15]
	v_mfma_f32_16x16x32_bf16 v[8:11], v[164:167], v[212:215], v[8:11]
	v_mfma_f32_16x16x32_bf16 v[52:55], v[168:171], v[184:187], v[52:55]
	v_mfma_f32_16x16x32_bf16 v[48:51], v[176:179], v[184:187], v[48:51]
	v_mfma_f32_16x16x32_bf16 v[36:39], v[168:171], v[192:195], v[36:39]
	v_mfma_f32_16x16x32_bf16 v[32:35], v[176:179], v[192:195], v[32:35]
	v_mfma_f32_16x16x32_bf16 v[20:23], v[168:171], v[200:203], v[20:23]
	v_mfma_f32_16x16x32_bf16 v[16:19], v[176:179], v[200:203], v[16:19]
	v_mfma_f32_16x16x32_bf16 v[4:7], v[168:171], v[208:211], v[4:7]
	v_mfma_f32_16x16x32_bf16 v[0:3], v[176:179], v[208:211], v[0:3]
	v_mfma_f32_16x16x32_bf16 v[52:55], v[172:175], v[188:191], v[52:55]
	v_mfma_f32_16x16x32_bf16 v[48:51], v[180:183], v[188:191], v[48:51]
	v_mfma_f32_16x16x32_bf16 v[36:39], v[172:175], v[196:199], v[36:39]
	v_mfma_f32_16x16x32_bf16 v[32:35], v[180:183], v[196:199], v[32:35]
	v_mfma_f32_16x16x32_bf16 v[20:23], v[172:175], v[204:207], v[20:23]
	v_mfma_f32_16x16x32_bf16 v[16:19], v[180:183], v[204:207], v[16:19]
	v_mfma_f32_16x16x32_bf16 v[4:7], v[172:175], v[212:215], v[4:7]
	v_mfma_f32_16x16x32_bf16 v[0:3], v[180:183], v[212:215], v[0:3]
	s_barrier
	s_add_i32 s55, 0, 0x18000
	s_add_i32 s56, 0, 0x1c000
	v_add_u32_e32 v164, s55, v152
	v_add_u32_e32 v180, s56, v152
	ds_read_b128 v[148:151], v164
	ds_read_b128 v[156:159], v164 offset:1024
	ds_read_b128 v[160:163], v164 offset:2048
	ds_read_b128 v[164:167], v164 offset:3072
	ds_read_b128 v[168:171], v180
	ds_read_b128 v[172:175], v180 offset:1024
	ds_read_b128 v[176:179], v180 offset:2048
	ds_read_b128 v[180:183], v180 offset:3072
	s_add_u32 s30, s30, 0x40000
	s_addc_u32 s31, s31, 0
	s_mov_b32 m0, s40
	v_lshl_add_u64 v[224:225], s[30:31], 0, v[128:129]
	ds_read_b128 v[184:187], v155 offset:32768
	ds_read_b128 v[188:191], v155 offset:33792
	ds_read_b128 v[192:195], v155 offset:34816
	ds_read_b128 v[196:199], v155 offset:35840
	ds_read_b128 v[200:203], v155 offset:36864
	ds_read_b128 v[204:207], v155 offset:37888
	ds_read_b128 v[208:211], v155 offset:38912
	ds_read_b128 v[212:215], v155 offset:39936
	global_load_lds_dwordx4 v[224:225], off
	v_lshl_add_u64 v[224:225], s[30:31], 0, v[132:133]
	s_mov_b32 m0, s41
	s_nop 0
	global_load_lds_dwordx4 v[224:225], off
	s_waitcnt vmcnt(8)
	s_waitcnt lgkmcnt(0)
	s_barrier
	s_waitcnt lgkmcnt(0)
	v_mfma_f32_16x16x32_bf16 v[124:127], v[148:151], v[184:187], v[124:127]
	v_mfma_f32_16x16x32_bf16 v[120:123], v[160:163], v[184:187], v[120:123]
	v_mfma_f32_16x16x32_bf16 v[108:111], v[148:151], v[192:195], v[108:111]
	v_mfma_f32_16x16x32_bf16 v[104:107], v[160:163], v[192:195], v[104:107]
	v_mfma_f32_16x16x32_bf16 v[92:95], v[148:151], v[200:203], v[92:95]
	v_mfma_f32_16x16x32_bf16 v[88:91], v[160:163], v[200:203], v[88:91]
	v_mfma_f32_16x16x32_bf16 v[76:79], v[148:151], v[208:211], v[76:79]
	v_mfma_f32_16x16x32_bf16 v[72:75], v[160:163], v[208:211], v[72:75]
	v_mfma_f32_16x16x32_bf16 v[124:127], v[156:159], v[188:191], v[124:127]
	v_mfma_f32_16x16x32_bf16 v[120:123], v[164:167], v[188:191], v[120:123]
	v_mfma_f32_16x16x32_bf16 v[108:111], v[156:159], v[196:199], v[108:111]
	v_mfma_f32_16x16x32_bf16 v[104:107], v[164:167], v[196:199], v[104:107]
	v_mfma_f32_16x16x32_bf16 v[92:95], v[156:159], v[204:207], v[92:95]
	v_mfma_f32_16x16x32_bf16 v[88:91], v[164:167], v[204:207], v[88:91]
	v_mfma_f32_16x16x32_bf16 v[76:79], v[156:159], v[212:215], v[76:79]
	v_mfma_f32_16x16x32_bf16 v[72:75], v[164:167], v[212:215], v[72:75]
	v_mfma_f32_16x16x32_bf16 v[116:119], v[168:171], v[184:187], v[116:119]
	v_mfma_f32_16x16x32_bf16 v[112:115], v[176:179], v[184:187], v[112:115]
	v_mfma_f32_16x16x32_bf16 v[100:103], v[168:171], v[192:195], v[100:103]
	v_mfma_f32_16x16x32_bf16 v[96:99], v[176:179], v[192:195], v[96:99]
	v_mfma_f32_16x16x32_bf16 v[84:87], v[168:171], v[200:203], v[84:87]
	v_mfma_f32_16x16x32_bf16 v[80:83], v[176:179], v[200:203], v[80:83]
	v_mfma_f32_16x16x32_bf16 v[68:71], v[168:171], v[208:211], v[68:71]
	v_mfma_f32_16x16x32_bf16 v[64:67], v[176:179], v[208:211], v[64:67]
	v_mfma_f32_16x16x32_bf16 v[116:119], v[172:175], v[188:191], v[116:119]
	v_mfma_f32_16x16x32_bf16 v[112:115], v[180:183], v[188:191], v[112:115]
	v_mfma_f32_16x16x32_bf16 v[100:103], v[172:175], v[196:199], v[100:103]
	v_mfma_f32_16x16x32_bf16 v[96:99], v[180:183], v[196:199], v[96:99]
	v_mfma_f32_16x16x32_bf16 v[84:87], v[172:175], v[204:207], v[84:87]
	v_mfma_f32_16x16x32_bf16 v[80:83], v[180:183], v[204:207], v[80:83]
	v_mfma_f32_16x16x32_bf16 v[68:71], v[172:175], v[212:215], v[68:71]
	v_mfma_f32_16x16x32_bf16 v[64:67], v[180:183], v[212:215], v[64:67]
	s_barrier
	s_add_i32 s30, s55, s37
	v_lshl_add_u64 v[216:217], v[216:217], 0, s[12:13]
	s_mov_b32 m0, s30
	ds_read_b128 v[184:187], v155 offset:49152
	ds_read_b128 v[188:191], v155 offset:50176
	ds_read_b128 v[192:195], v155 offset:51200
	ds_read_b128 v[196:199], v155 offset:52224
	ds_read_b128 v[200:203], v155 offset:53248
	ds_read_b128 v[204:207], v155 offset:54272
	ds_read_b128 v[208:211], v155 offset:55296
	ds_read_b128 v[212:215], v155 offset:56320
	global_load_lds_dwordx4 v[216:217], off
	s_add_i32 m0, s30, 0x2000
	s_add_u32 s28, s28, 0x40080
	v_lshl_add_u64 v[216:217], v[218:219], 0, s[12:13]
	s_addc_u32 s29, s29, 0
	s_add_i32 s30, s56, s37
	global_load_lds_dwordx4 v[216:217], off
	v_lshl_add_u64 v[216:217], s[28:29], 0, v[130:131]
	s_mov_b32 m0, s30
	s_nop 0
	global_load_lds_dwordx4 v[216:217], off
	v_lshl_add_u64 v[216:217], s[28:29], 0, v[134:135]
	s_add_i32 m0, s30, 0x2000
	s_nop 0
	global_load_lds_dwordx4 v[216:217], off
	v_lshl_add_u64 v[216:217], v[220:221], 0, s[12:13]
	s_mov_b32 m0, s43
	s_nop 0
	global_load_lds_dwordx4 v[216:217], off
	v_lshl_add_u64 v[216:217], v[222:223], 0, s[12:13]
	s_mov_b32 m0, s44
	s_nop 0
	global_load_lds_dwordx4 v[216:217], off
	s_waitcnt vmcnt(8)
	s_waitcnt lgkmcnt(0)
	s_barrier
	s_waitcnt lgkmcnt(0)
	v_mfma_f32_16x16x32_bf16 v[60:63], v[148:151], v[184:187], v[60:63]
	v_mfma_f32_16x16x32_bf16 v[56:59], v[160:163], v[184:187], v[56:59]
	v_mfma_f32_16x16x32_bf16 v[44:47], v[148:151], v[192:195], v[44:47]
	v_mfma_f32_16x16x32_bf16 v[40:43], v[160:163], v[192:195], v[40:43]
	v_mfma_f32_16x16x32_bf16 v[28:31], v[148:151], v[200:203], v[28:31]
	v_mfma_f32_16x16x32_bf16 v[24:27], v[160:163], v[200:203], v[24:27]
	v_mfma_f32_16x16x32_bf16 v[12:15], v[148:151], v[208:211], v[12:15]
	v_mfma_f32_16x16x32_bf16 v[8:11], v[160:163], v[208:211], v[8:11]
	v_mfma_f32_16x16x32_bf16 v[60:63], v[156:159], v[188:191], v[60:63]
	v_mfma_f32_16x16x32_bf16 v[56:59], v[164:167], v[188:191], v[56:59]
	v_mfma_f32_16x16x32_bf16 v[44:47], v[156:159], v[196:199], v[44:47]
	v_mfma_f32_16x16x32_bf16 v[40:43], v[164:167], v[196:199], v[40:43]
	v_mfma_f32_16x16x32_bf16 v[28:31], v[156:159], v[204:207], v[28:31]
	v_mfma_f32_16x16x32_bf16 v[24:27], v[164:167], v[204:207], v[24:27]
	v_mfma_f32_16x16x32_bf16 v[12:15], v[156:159], v[212:215], v[12:15]
	v_mfma_f32_16x16x32_bf16 v[8:11], v[164:167], v[212:215], v[8:11]
	v_mfma_f32_16x16x32_bf16 v[52:55], v[168:171], v[184:187], v[52:55]
	v_mfma_f32_16x16x32_bf16 v[48:51], v[176:179], v[184:187], v[48:51]
	v_mfma_f32_16x16x32_bf16 v[36:39], v[168:171], v[192:195], v[36:39]
	v_mfma_f32_16x16x32_bf16 v[32:35], v[176:179], v[192:195], v[32:35]
	v_mfma_f32_16x16x32_bf16 v[20:23], v[168:171], v[200:203], v[20:23]
	v_mfma_f32_16x16x32_bf16 v[16:19], v[176:179], v[200:203], v[16:19]
	v_mfma_f32_16x16x32_bf16 v[4:7], v[168:171], v[208:211], v[4:7]
	v_mfma_f32_16x16x32_bf16 v[0:3], v[176:179], v[208:211], v[0:3]
	v_mfma_f32_16x16x32_bf16 v[52:55], v[172:175], v[188:191], v[52:55]
	v_mfma_f32_16x16x32_bf16 v[48:51], v[180:183], v[188:191], v[48:51]
	v_mfma_f32_16x16x32_bf16 v[36:39], v[172:175], v[196:199], v[36:39]
	v_mfma_f32_16x16x32_bf16 v[32:35], v[180:183], v[196:199], v[32:35]
	v_mfma_f32_16x16x32_bf16 v[20:23], v[172:175], v[204:207], v[20:23]
	v_mfma_f32_16x16x32_bf16 v[16:19], v[180:183], v[204:207], v[16:19]
	v_mfma_f32_16x16x32_bf16 v[4:7], v[172:175], v[212:215], v[4:7]
	v_mfma_f32_16x16x32_bf16 v[0:3], v[180:183], v[212:215], v[0:3]
	s_add_i32 s54, s54, 2
	s_add_u32 s26, s26, 0x100
	s_addc_u32 s27, s27, 0
	s_add_u32 s52, s52, 0x100
	s_addc_u32 s53, s53, 0
	s_cmp_gt_u32 s54, 13
	s_barrier
	s_cbranch_scc0 .LBB1_94
	s_and_b64 vcc, exec, s[14:15]
	s_cbranch_vccz .LBB1_97
	s_barrier

.LBB3_19:
	s_ashr_i32 s17, s16, 31
	s_lshl_b64 s[18:19], s[16:17], 19
	s_add_u32 s18, s33, s18
	v_cmp_lt_i64_e64 s[4:5], s[4:5], v[142:143]
	s_addc_u32 s19, s34, s19
	s_and_b64 s[20:21], s[4:5], exec
	s_cselect_b32 s17, s19, s25
	s_cselect_b32 s53, s18, s24
	s_ashr_i32 s15, s14, 31
	s_lshl_b64 s[20:21], s[14:15], 19
	s_add_u32 s20, s6, s20
	s_addc_u32 s21, s7, s21
	s_and_b64 s[28:29], s[4:5], exec
	s_cselect_b32 s15, s21, s27
	s_cselect_b32 s54, s20, s26
	s_add_u32 s24, s24, 0x40080
	s_addc_u32 s25, s25, 0
	s_add_u32 s55, s26, 0x100
	s_addc_u32 s56, s27, 0
	s_mov_b32 s57, -2
	ds_read_b128 v[152:155], v149
	ds_read_b128 v[156:159], v149 offset:1024
	ds_read_b128 v[160:163], v149 offset:2048
	ds_read_b128 v[164:167], v149 offset:3072
	ds_read_b128 v[168:171], v150
	ds_read_b128 v[172:175], v150 offset:1024
	ds_read_b128 v[176:179], v150 offset:2048
	ds_read_b128 v[180:183], v150 offset:3072
	s_add_u32 s26, s24, 0xfffc0080
	s_addc_u32 s27, s25, -1
	s_cmp_eq_u32 s57, 12
	s_cselect_b32 s29, s17, s27
	s_cselect_b32 s28, s53, s26
	s_cselect_b32 s27, s15, s56
	s_cselect_b32 s26, s54, s55
	v_lshl_add_u64 v[146:147], s[24:25], 0, v[138:139]
	s_add_i32 m0, s23, 0xc000
	ds_read_b128 v[184:187], v151
	ds_read_b128 v[188:191], v151 offset:1024
	ds_read_b128 v[192:195], v151 offset:2048
	ds_read_b128 v[196:199], v151 offset:3072
	ds_read_b128 v[200:203], v151 offset:4096
	ds_read_b128 v[204:207], v151 offset:5120
	ds_read_b128 v[208:211], v151 offset:6144
	ds_read_b128 v[212:215], v151 offset:7168
	global_load_lds_dwordx4 v[146:147], off
	v_lshl_add_u64 v[146:147], s[24:25], 0, v[140:141]
	s_add_i32 m0, s23, 0xe000
	s_nop 0
	global_load_lds_dwordx4 v[146:147], off
	s_waitcnt vmcnt(8)
	s_waitcnt lgkmcnt(0)
	s_barrier
	s_waitcnt lgkmcnt(0)
	v_mfma_f32_16x16x32_bf16 v[124:127], v[152:155], v[184:187], 0
	v_mfma_f32_16x16x32_bf16 v[120:123], v[160:163], v[184:187], 0
	v_mfma_f32_16x16x32_bf16 v[116:119], v[152:155], v[192:195], 0
	v_mfma_f32_16x16x32_bf16 v[108:111], v[160:163], v[192:195], 0
	v_mfma_f32_16x16x32_bf16 v[100:103], v[152:155], v[200:203], 0
	v_mfma_f32_16x16x32_bf16 v[92:95], v[160:163], v[200:203], 0
	v_mfma_f32_16x16x32_bf16 v[84:87], v[152:155], v[208:211], 0
	v_mfma_f32_16x16x32_bf16 v[76:79], v[160:163], v[208:211], 0
	v_mfma_f32_16x16x32_bf16 v[124:127], v[156:159], v[188:191], v[124:127]
	v_mfma_f32_16x16x32_bf16 v[120:123], v[164:167], v[188:191], v[120:123]
	v_mfma_f32_16x16x32_bf16 v[116:119], v[156:159], v[196:199], v[116:119]
	v_mfma_f32_16x16x32_bf16 v[108:111], v[164:167], v[196:199], v[108:111]
	v_mfma_f32_16x16x32_bf16 v[100:103], v[156:159], v[204:207], v[100:103]
	v_mfma_f32_16x16x32_bf16 v[92:95], v[164:167], v[204:207], v[92:95]
	v_mfma_f32_16x16x32_bf16 v[84:87], v[156:159], v[212:215], v[84:87]
	v_mfma_f32_16x16x32_bf16 v[76:79], v[164:167], v[212:215], v[76:79]
	v_mfma_f32_16x16x32_bf16 v[112:115], v[168:171], v[184:187], 0
	v_mfma_f32_16x16x32_bf16 v[104:107], v[176:179], v[184:187], 0
	v_mfma_f32_16x16x32_bf16 v[96:99], v[168:171], v[192:195], 0
	v_mfma_f32_16x16x32_bf16 v[88:91], v[176:179], v[192:195], 0
	v_mfma_f32_16x16x32_bf16 v[80:83], v[168:171], v[200:203], 0
	v_mfma_f32_16x16x32_bf16 v[72:75], v[176:179], v[200:203], 0
	v_mfma_f32_16x16x32_bf16 v[68:71], v[168:171], v[208:211], 0
	v_mfma_f32_16x16x32_bf16 v[64:67], v[176:179], v[208:211], 0
	v_mfma_f32_16x16x32_bf16 v[112:115], v[172:175], v[188:191], v[112:115]
	v_mfma_f32_16x16x32_bf16 v[104:107], v[180:183], v[188:191], v[104:107]
	v_mfma_f32_16x16x32_bf16 v[96:99], v[172:175], v[196:199], v[96:99]
	v_mfma_f32_16x16x32_bf16 v[88:91], v[180:183], v[196:199], v[88:91]
	v_mfma_f32_16x16x32_bf16 v[80:83], v[172:175], v[204:207], v[80:83]
	v_mfma_f32_16x16x32_bf16 v[72:75], v[180:183], v[204:207], v[72:75]
	v_mfma_f32_16x16x32_bf16 v[68:71], v[172:175], v[212:215], v[68:71]
	v_mfma_f32_16x16x32_bf16 v[64:67], v[180:183], v[212:215], v[64:67]
	s_barrier
	s_add_i32 s58, s45, s31
	v_lshl_add_u64 v[146:147], s[26:27], 0, v[130:131]
	s_mov_b32 m0, s58
	ds_read_b128 v[184:187], v151 offset:16384
	ds_read_b128 v[188:191], v151 offset:17408
	ds_read_b128 v[192:195], v151 offset:18432
	ds_read_b128 v[196:199], v151 offset:19456
	ds_read_b128 v[200:203], v151 offset:20480
	ds_read_b128 v[204:207], v151 offset:21504
	ds_read_b128 v[208:211], v151 offset:22528
	ds_read_b128 v[212:215], v151 offset:23552
	global_load_lds_dwordx4 v[146:147], off
	s_add_i32 m0, s58, 0x2000
	s_add_u32 s58, s26, 0x40000
	v_lshl_add_u64 v[216:217], s[26:27], 0, v[134:135]
	s_addc_u32 s59, s27, 0
	s_add_i32 s60, s46, s31
	global_load_lds_dwordx4 v[216:217], off
	v_lshl_add_u64 v[218:219], s[58:59], 0, v[130:131]
	s_mov_b32 m0, s60
	v_lshl_add_u64 v[220:221], s[28:29], 0, v[132:133]
	global_load_lds_dwordx4 v[218:219], off
	v_lshl_add_u64 v[218:219], s[58:59], 0, v[134:135]
	s_add_i32 m0, s60, 0x2000
	s_nop 0
	global_load_lds_dwordx4 v[218:219], off
	v_lshl_add_u64 v[218:219], s[28:29], 0, v[128:129]
	s_mov_b32 m0, s23
	s_nop 0
	global_load_lds_dwordx4 v[218:219], off
	s_mov_b32 m0, s35
	s_nop 0
	global_load_lds_dwordx4 v[220:221], off
	s_waitcnt vmcnt(8)
	s_waitcnt lgkmcnt(0)
	s_barrier
	s_waitcnt lgkmcnt(0)
	v_mfma_f32_16x16x32_bf16 v[60:63], v[152:155], v[184:187], 0
	v_mfma_f32_16x16x32_bf16 v[56:59], v[160:163], v[184:187], 0
	v_mfma_f32_16x16x32_bf16 v[52:55], v[152:155], v[192:195], 0
	v_mfma_f32_16x16x32_bf16 v[44:47], v[160:163], v[192:195], 0
	v_mfma_f32_16x16x32_bf16 v[36:39], v[152:155], v[200:203], 0
	v_mfma_f32_16x16x32_bf16 v[28:31], v[160:163], v[200:203], 0
	v_mfma_f32_16x16x32_bf16 v[20:23], v[152:155], v[208:211], 0
	v_mfma_f32_16x16x32_bf16 v[12:15], v[160:163], v[208:211], 0
	v_mfma_f32_16x16x32_bf16 v[60:63], v[156:159], v[188:191], v[60:63]
	v_mfma_f32_16x16x32_bf16 v[56:59], v[164:167], v[188:191], v[56:59]
	v_mfma_f32_16x16x32_bf16 v[52:55], v[156:159], v[196:199], v[52:55]
	v_mfma_f32_16x16x32_bf16 v[44:47], v[164:167], v[196:199], v[44:47]
	v_mfma_f32_16x16x32_bf16 v[36:39], v[156:159], v[204:207], v[36:39]
	v_mfma_f32_16x16x32_bf16 v[28:31], v[164:167], v[204:207], v[28:31]
	v_mfma_f32_16x16x32_bf16 v[20:23], v[156:159], v[212:215], v[20:23]
	v_mfma_f32_16x16x32_bf16 v[12:15], v[164:167], v[212:215], v[12:15]
	v_mfma_f32_16x16x32_bf16 v[48:51], v[168:171], v[184:187], 0
	v_mfma_f32_16x16x32_bf16 v[40:43], v[176:179], v[184:187], 0
	v_mfma_f32_16x16x32_bf16 v[32:35], v[168:171], v[192:195], 0
	v_mfma_f32_16x16x32_bf16 v[24:27], v[176:179], v[192:195], 0
	v_mfma_f32_16x16x32_bf16 v[16:19], v[168:171], v[200:203], 0
	v_mfma_f32_16x16x32_bf16 v[8:11], v[176:179], v[200:203], 0
	v_mfma_f32_16x16x32_bf16 v[4:7], v[168:171], v[208:211], 0
	v_mfma_f32_16x16x32_bf16 v[0:3], v[176:179], v[208:211], 0
	v_mfma_f32_16x16x32_bf16 v[48:51], v[172:175], v[188:191], v[48:51]
	v_mfma_f32_16x16x32_bf16 v[40:43], v[180:183], v[188:191], v[40:43]
	v_mfma_f32_16x16x32_bf16 v[32:35], v[172:175], v[196:199], v[32:35]
	v_mfma_f32_16x16x32_bf16 v[24:27], v[180:183], v[196:199], v[24:27]
	v_mfma_f32_16x16x32_bf16 v[16:19], v[172:175], v[204:207], v[16:19]
	v_mfma_f32_16x16x32_bf16 v[8:11], v[180:183], v[204:207], v[8:11]
	v_mfma_f32_16x16x32_bf16 v[4:7], v[172:175], v[212:215], v[4:7]
	v_mfma_f32_16x16x32_bf16 v[0:3], v[180:183], v[212:215], v[0:3]
	s_barrier
	s_add_i32 s58, 0, 0x18000
	s_add_i32 s59, 0, 0x1c000
	v_add_u32_e32 v164, s58, v148
	v_add_u32_e32 v180, s59, v148
	ds_read_b128 v[152:155], v164
	ds_read_b128 v[156:159], v164 offset:1024
	ds_read_b128 v[160:163], v164 offset:2048
	ds_read_b128 v[164:167], v164 offset:3072
	ds_read_b128 v[168:171], v180
	ds_read_b128 v[172:175], v180 offset:1024
	ds_read_b128 v[176:179], v180 offset:2048
	ds_read_b128 v[180:183], v180 offset:3072
	s_add_u32 s28, s28, 0x40000
	s_addc_u32 s29, s29, 0
	s_mov_b32 m0, s36
	v_lshl_add_u64 v[222:223], s[28:29], 0, v[128:129]
	ds_read_b128 v[184:187], v151 offset:32768
	ds_read_b128 v[188:191], v151 offset:33792
	ds_read_b128 v[192:195], v151 offset:34816
	ds_read_b128 v[196:199], v151 offset:35840
	ds_read_b128 v[200:203], v151 offset:36864
	ds_read_b128 v[204:207], v151 offset:37888
	ds_read_b128 v[208:211], v151 offset:38912
	ds_read_b128 v[212:215], v151 offset:39936
	global_load_lds_dwordx4 v[222:223], off
	v_lshl_add_u64 v[222:223], s[28:29], 0, v[132:133]
	s_mov_b32 m0, s37
	s_nop 0
	global_load_lds_dwordx4 v[222:223], off
	s_waitcnt vmcnt(8)
	s_waitcnt lgkmcnt(0)
	s_barrier
	s_waitcnt lgkmcnt(0)
	v_mfma_f32_16x16x32_bf16 v[124:127], v[152:155], v[184:187], v[124:127]
	v_mfma_f32_16x16x32_bf16 v[120:123], v[160:163], v[184:187], v[120:123]
	v_mfma_f32_16x16x32_bf16 v[116:119], v[152:155], v[192:195], v[116:119]
	v_mfma_f32_16x16x32_bf16 v[108:111], v[160:163], v[192:195], v[108:111]
	v_mfma_f32_16x16x32_bf16 v[100:103], v[152:155], v[200:203], v[100:103]
	v_mfma_f32_16x16x32_bf16 v[92:95], v[160:163], v[200:203], v[92:95]
	v_mfma_f32_16x16x32_bf16 v[84:87], v[152:155], v[208:211], v[84:87]
	v_mfma_f32_16x16x32_bf16 v[76:79], v[160:163], v[208:211], v[76:79]
	v_mfma_f32_16x16x32_bf16 v[124:127], v[156:159], v[188:191], v[124:127]
	v_mfma_f32_16x16x32_bf16 v[120:123], v[164:167], v[188:191], v[120:123]
	v_mfma_f32_16x16x32_bf16 v[116:119], v[156:159], v[196:199], v[116:119]
	v_mfma_f32_16x16x32_bf16 v[108:111], v[164:167], v[196:199], v[108:111]
	v_mfma_f32_16x16x32_bf16 v[100:103], v[156:159], v[204:207], v[100:103]
	v_mfma_f32_16x16x32_bf16 v[92:95], v[164:167], v[204:207], v[92:95]
	v_mfma_f32_16x16x32_bf16 v[84:87], v[156:159], v[212:215], v[84:87]
	v_mfma_f32_16x16x32_bf16 v[76:79], v[164:167], v[212:215], v[76:79]
	v_mfma_f32_16x16x32_bf16 v[112:115], v[168:171], v[184:187], v[112:115]
	v_mfma_f32_16x16x32_bf16 v[104:107], v[176:179], v[184:187], v[104:107]
	v_mfma_f32_16x16x32_bf16 v[96:99], v[168:171], v[192:195], v[96:99]
	v_mfma_f32_16x16x32_bf16 v[88:91], v[176:179], v[192:195], v[88:91]
	v_mfma_f32_16x16x32_bf16 v[80:83], v[168:171], v[200:203], v[80:83]
	v_mfma_f32_16x16x32_bf16 v[72:75], v[176:179], v[200:203], v[72:75]
	v_mfma_f32_16x16x32_bf16 v[68:71], v[168:171], v[208:211], v[68:71]
	v_mfma_f32_16x16x32_bf16 v[64:67], v[176:179], v[208:211], v[64:67]
	v_mfma_f32_16x16x32_bf16 v[112:115], v[172:175], v[188:191], v[112:115]
	v_mfma_f32_16x16x32_bf16 v[104:107], v[180:183], v[188:191], v[104:107]
	v_mfma_f32_16x16x32_bf16 v[96:99], v[172:175], v[196:199], v[96:99]
	v_mfma_f32_16x16x32_bf16 v[88:91], v[180:183], v[196:199], v[88:91]
	v_mfma_f32_16x16x32_bf16 v[80:83], v[172:175], v[204:207], v[80:83]
	v_mfma_f32_16x16x32_bf16 v[72:75], v[180:183], v[204:207], v[72:75]
	v_mfma_f32_16x16x32_bf16 v[68:71], v[172:175], v[212:215], v[68:71]
	v_mfma_f32_16x16x32_bf16 v[64:67], v[180:183], v[212:215], v[64:67]
	s_barrier
	s_add_i32 s28, s58, s31
	v_lshl_add_u64 v[146:147], v[146:147], 0, s[12:13]
	s_mov_b32 m0, s28
	ds_read_b128 v[184:187], v151 offset:49152
	ds_read_b128 v[188:191], v151 offset:50176
	ds_read_b128 v[192:195], v151 offset:51200
	ds_read_b128 v[196:199], v151 offset:52224
	ds_read_b128 v[200:203], v151 offset:53248
	ds_read_b128 v[204:207], v151 offset:54272
	ds_read_b128 v[208:211], v151 offset:55296
	ds_read_b128 v[212:215], v151 offset:56320
	global_load_lds_dwordx4 v[146:147], off
	s_add_i32 m0, s28, 0x2000
	s_add_u32 s26, s26, 0x40080
	v_lshl_add_u64 v[146:147], v[216:217], 0, s[12:13]
	s_addc_u32 s27, s27, 0
	s_add_i32 s28, s59, s31
	global_load_lds_dwordx4 v[146:147], off
	v_lshl_add_u64 v[146:147], s[26:27], 0, v[130:131]
	s_mov_b32 m0, s28
	s_nop 0
	global_load_lds_dwordx4 v[146:147], off
	v_lshl_add_u64 v[146:147], s[26:27], 0, v[134:135]
	s_add_i32 m0, s28, 0x2000
	s_nop 0
	global_load_lds_dwordx4 v[146:147], off
	v_lshl_add_u64 v[146:147], v[218:219], 0, s[12:13]
	s_mov_b32 m0, s40
	s_nop 0
	global_load_lds_dwordx4 v[146:147], off
	v_lshl_add_u64 v[146:147], v[220:221], 0, s[12:13]
	s_mov_b32 m0, s41
	s_nop 0
	global_load_lds_dwordx4 v[146:147], off
	s_waitcnt vmcnt(8)
	s_waitcnt lgkmcnt(0)
	s_barrier
	s_waitcnt lgkmcnt(0)
	v_mfma_f32_16x16x32_bf16 v[60:63], v[152:155], v[184:187], v[60:63]
	v_mfma_f32_16x16x32_bf16 v[56:59], v[160:163], v[184:187], v[56:59]
	v_mfma_f32_16x16x32_bf16 v[52:55], v[152:155], v[192:195], v[52:55]
	v_mfma_f32_16x16x32_bf16 v[44:47], v[160:163], v[192:195], v[44:47]
	v_mfma_f32_16x16x32_bf16 v[36:39], v[152:155], v[200:203], v[36:39]
	v_mfma_f32_16x16x32_bf16 v[28:31], v[160:163], v[200:203], v[28:31]
	v_mfma_f32_16x16x32_bf16 v[20:23], v[152:155], v[208:211], v[20:23]
	v_mfma_f32_16x16x32_bf16 v[12:15], v[160:163], v[208:211], v[12:15]
	v_mfma_f32_16x16x32_bf16 v[60:63], v[156:159], v[188:191], v[60:63]
	v_mfma_f32_16x16x32_bf16 v[56:59], v[164:167], v[188:191], v[56:59]
	v_mfma_f32_16x16x32_bf16 v[52:55], v[156:159], v[196:199], v[52:55]
	v_mfma_f32_16x16x32_bf16 v[44:47], v[164:167], v[196:199], v[44:47]
	v_mfma_f32_16x16x32_bf16 v[36:39], v[156:159], v[204:207], v[36:39]
	v_mfma_f32_16x16x32_bf16 v[28:31], v[164:167], v[204:207], v[28:31]
	v_mfma_f32_16x16x32_bf16 v[20:23], v[156:159], v[212:215], v[20:23]
	v_mfma_f32_16x16x32_bf16 v[12:15], v[164:167], v[212:215], v[12:15]
	v_mfma_f32_16x16x32_bf16 v[48:51], v[168:171], v[184:187], v[48:51]
	v_mfma_f32_16x16x32_bf16 v[40:43], v[176:179], v[184:187], v[40:43]
	v_mfma_f32_16x16x32_bf16 v[32:35], v[168:171], v[192:195], v[32:35]
	v_mfma_f32_16x16x32_bf16 v[24:27], v[176:179], v[192:195], v[24:27]
	v_mfma_f32_16x16x32_bf16 v[16:19], v[168:171], v[200:203], v[16:19]
	v_mfma_f32_16x16x32_bf16 v[8:11], v[176:179], v[200:203], v[8:11]
	v_mfma_f32_16x16x32_bf16 v[4:7], v[168:171], v[208:211], v[4:7]
	v_mfma_f32_16x16x32_bf16 v[0:3], v[176:179], v[208:211], v[0:3]
	v_mfma_f32_16x16x32_bf16 v[48:51], v[172:175], v[188:191], v[48:51]
	v_mfma_f32_16x16x32_bf16 v[40:43], v[180:183], v[188:191], v[40:43]
	v_mfma_f32_16x16x32_bf16 v[32:35], v[172:175], v[196:199], v[32:35]
	v_mfma_f32_16x16x32_bf16 v[24:27], v[180:183], v[196:199], v[24:27]
	v_mfma_f32_16x16x32_bf16 v[16:19], v[172:175], v[204:207], v[16:19]
	v_mfma_f32_16x16x32_bf16 v[8:11], v[180:183], v[204:207], v[8:11]
	v_mfma_f32_16x16x32_bf16 v[4:7], v[172:175], v[212:215], v[4:7]
	v_mfma_f32_16x16x32_bf16 v[0:3], v[180:183], v[212:215], v[0:3]
	s_add_i32 s57, s57, 2
	s_add_u32 s24, s24, 0x100
	s_addc_u32 s25, s25, 0
	s_add_u32 s55, s55, 0x100
	s_addc_u32 s56, s56, 0
	s_cmp_gt_u32 s57, 13
	s_barrier
.LBB3_20:
	ds_read_b128 v[152:155], v149
	ds_read_b128 v[156:159], v149 offset:1024
	ds_read_b128 v[160:163], v149 offset:2048
	ds_read_b128 v[164:167], v149 offset:3072
	ds_read_b128 v[168:171], v150
	ds_read_b128 v[172:175], v150 offset:1024
	ds_read_b128 v[176:179], v150 offset:2048
	ds_read_b128 v[180:183], v150 offset:3072
	s_add_u32 s26, s24, 0xfffc0080
	s_addc_u32 s27, s25, -1
	s_cmp_eq_u32 s57, 12
	s_cselect_b32 s29, s17, s27
	s_cselect_b32 s28, s53, s26
	s_cselect_b32 s27, s15, s56
	s_cselect_b32 s26, s54, s55
	v_lshl_add_u64 v[146:147], s[24:25], 0, v[138:139]
	s_add_i32 m0, s23, 0xc000
	ds_read_b128 v[184:187], v151
	ds_read_b128 v[188:191], v151 offset:1024
	ds_read_b128 v[192:195], v151 offset:2048
	ds_read_b128 v[196:199], v151 offset:3072
	ds_read_b128 v[200:203], v151 offset:4096
	ds_read_b128 v[204:207], v151 offset:5120
	ds_read_b128 v[208:211], v151 offset:6144
	ds_read_b128 v[212:215], v151 offset:7168
	global_load_lds_dwordx4 v[146:147], off
	v_lshl_add_u64 v[146:147], s[24:25], 0, v[140:141]
	s_add_i32 m0, s23, 0xe000
	s_nop 0
	global_load_lds_dwordx4 v[146:147], off
	s_waitcnt vmcnt(8)
	s_waitcnt lgkmcnt(0)
	s_barrier
	s_waitcnt lgkmcnt(0)
	v_mfma_f32_16x16x32_bf16 v[124:127], v[152:155], v[184:187], v[124:127]
	v_mfma_f32_16x16x32_bf16 v[120:123], v[160:163], v[184:187], v[120:123]
	v_mfma_f32_16x16x32_bf16 v[116:119], v[152:155], v[192:195], v[116:119]
	v_mfma_f32_16x16x32_bf16 v[108:111], v[160:163], v[192:195], v[108:111]
	v_mfma_f32_16x16x32_bf16 v[100:103], v[152:155], v[200:203], v[100:103]
	v_mfma_f32_16x16x32_bf16 v[92:95], v[160:163], v[200:203], v[92:95]
	v_mfma_f32_16x16x32_bf16 v[84:87], v[152:155], v[208:211], v[84:87]
	v_mfma_f32_16x16x32_bf16 v[76:79], v[160:163], v[208:211], v[76:79]
	v_mfma_f32_16x16x32_bf16 v[124:127], v[156:159], v[188:191], v[124:127]
	v_mfma_f32_16x16x32_bf16 v[120:123], v[164:167], v[188:191], v[120:123]
	v_mfma_f32_16x16x32_bf16 v[116:119], v[156:159], v[196:199], v[116:119]
	v_mfma_f32_16x16x32_bf16 v[108:111], v[164:167], v[196:199], v[108:111]
	v_mfma_f32_16x16x32_bf16 v[100:103], v[156:159], v[204:207], v[100:103]
	v_mfma_f32_16x16x32_bf16 v[92:95], v[164:167], v[204:207], v[92:95]
	v_mfma_f32_16x16x32_bf16 v[84:87], v[156:159], v[212:215], v[84:87]
	v_mfma_f32_16x16x32_bf16 v[76:79], v[164:167], v[212:215], v[76:79]
	v_mfma_f32_16x16x32_bf16 v[112:115], v[168:171], v[184:187], v[112:115]
	v_mfma_f32_16x16x32_bf16 v[104:107], v[176:179], v[184:187], v[104:107]
	v_mfma_f32_16x16x32_bf16 v[96:99], v[168:171], v[192:195], v[96:99]
	v_mfma_f32_16x16x32_bf16 v[88:91], v[176:179], v[192:195], v[88:91]
	v_mfma_f32_16x16x32_bf16 v[80:83], v[168:171], v[200:203], v[80:83]
	v_mfma_f32_16x16x32_bf16 v[72:75], v[176:179], v[200:203], v[72:75]
	v_mfma_f32_16x16x32_bf16 v[68:71], v[168:171], v[208:211], v[68:71]
	v_mfma_f32_16x16x32_bf16 v[64:67], v[176:179], v[208:211], v[64:67]
	v_mfma_f32_16x16x32_bf16 v[112:115], v[172:175], v[188:191], v[112:115]
	v_mfma_f32_16x16x32_bf16 v[104:107], v[180:183], v[188:191], v[104:107]
	v_mfma_f32_16x16x32_bf16 v[96:99], v[172:175], v[196:199], v[96:99]
	v_mfma_f32_16x16x32_bf16 v[88:91], v[180:183], v[196:199], v[88:91]
	v_mfma_f32_16x16x32_bf16 v[80:83], v[172:175], v[204:207], v[80:83]
	v_mfma_f32_16x16x32_bf16 v[72:75], v[180:183], v[204:207], v[72:75]
	v_mfma_f32_16x16x32_bf16 v[68:71], v[172:175], v[212:215], v[68:71]
	v_mfma_f32_16x16x32_bf16 v[64:67], v[180:183], v[212:215], v[64:67]
	s_barrier
	s_add_i32 s58, s45, s31
	v_lshl_add_u64 v[146:147], s[26:27], 0, v[130:131]
	s_mov_b32 m0, s58
	ds_read_b128 v[184:187], v151 offset:16384
	ds_read_b128 v[188:191], v151 offset:17408
	ds_read_b128 v[192:195], v151 offset:18432
	ds_read_b128 v[196:199], v151 offset:19456
	ds_read_b128 v[200:203], v151 offset:20480
	ds_read_b128 v[204:207], v151 offset:21504
	ds_read_b128 v[208:211], v151 offset:22528
	ds_read_b128 v[212:215], v151 offset:23552
	global_load_lds_dwordx4 v[146:147], off
	s_add_i32 m0, s58, 0x2000
	s_add_u32 s58, s26, 0x40000
	v_lshl_add_u64 v[216:217], s[26:27], 0, v[134:135]
	s_addc_u32 s59, s27, 0
	s_add_i32 s60, s46, s31
	global_load_lds_dwordx4 v[216:217], off
	v_lshl_add_u64 v[218:219], s[58:59], 0, v[130:131]
	s_mov_b32 m0, s60
	v_lshl_add_u64 v[220:221], s[28:29], 0, v[132:133]
	global_load_lds_dwordx4 v[218:219], off
	v_lshl_add_u64 v[218:219], s[58:59], 0, v[134:135]
	s_add_i32 m0, s60, 0x2000
	s_nop 0
	global_load_lds_dwordx4 v[218:219], off
	v_lshl_add_u64 v[218:219], s[28:29], 0, v[128:129]
	s_mov_b32 m0, s23
	s_nop 0
	global_load_lds_dwordx4 v[218:219], off
	s_mov_b32 m0, s35
	s_nop 0
	global_load_lds_dwordx4 v[220:221], off
	s_waitcnt vmcnt(8)
	s_waitcnt lgkmcnt(0)
	s_barrier
	s_waitcnt lgkmcnt(0)
	v_mfma_f32_16x16x32_bf16 v[60:63], v[152:155], v[184:187], v[60:63]
	v_mfma_f32_16x16x32_bf16 v[56:59], v[160:163], v[184:187], v[56:59]
	v_mfma_f32_16x16x32_bf16 v[52:55], v[152:155], v[192:195], v[52:55]
	v_mfma_f32_16x16x32_bf16 v[44:47], v[160:163], v[192:195], v[44:47]
	v_mfma_f32_16x16x32_bf16 v[36:39], v[152:155], v[200:203], v[36:39]
	v_mfma_f32_16x16x32_bf16 v[28:31], v[160:163], v[200:203], v[28:31]
	v_mfma_f32_16x16x32_bf16 v[20:23], v[152:155], v[208:211], v[20:23]
	v_mfma_f32_16x16x32_bf16 v[12:15], v[160:163], v[208:211], v[12:15]
	v_mfma_f32_16x16x32_bf16 v[60:63], v[156:159], v[188:191], v[60:63]
	v_mfma_f32_16x16x32_bf16 v[56:59], v[164:167], v[188:191], v[56:59]
	v_mfma_f32_16x16x32_bf16 v[52:55], v[156:159], v[196:199], v[52:55]
	v_mfma_f32_16x16x32_bf16 v[44:47], v[164:167], v[196:199], v[44:47]
	v_mfma_f32_16x16x32_bf16 v[36:39], v[156:159], v[204:207], v[36:39]
	v_mfma_f32_16x16x32_bf16 v[28:31], v[164:167], v[204:207], v[28:31]
	v_mfma_f32_16x16x32_bf16 v[20:23], v[156:159], v[212:215], v[20:23]
	v_mfma_f32_16x16x32_bf16 v[12:15], v[164:167], v[212:215], v[12:15]
	v_mfma_f32_16x16x32_bf16 v[48:51], v[168:171], v[184:187], v[48:51]
	v_mfma_f32_16x16x32_bf16 v[40:43], v[176:179], v[184:187], v[40:43]
	v_mfma_f32_16x16x32_bf16 v[32:35], v[168:171], v[192:195], v[32:35]
	v_mfma_f32_16x16x32_bf16 v[24:27], v[176:179], v[192:195], v[24:27]
	v_mfma_f32_16x16x32_bf16 v[16:19], v[168:171], v[200:203], v[16:19]
	v_mfma_f32_16x16x32_bf16 v[8:11], v[176:179], v[200:203], v[8:11]
	v_mfma_f32_16x16x32_bf16 v[4:7], v[168:171], v[208:211], v[4:7]
	v_mfma_f32_16x16x32_bf16 v[0:3], v[176:179], v[208:211], v[0:3]
	v_mfma_f32_16x16x32_bf16 v[48:51], v[172:175], v[188:191], v[48:51]
	v_mfma_f32_16x16x32_bf16 v[40:43], v[180:183], v[188:191], v[40:43]
	v_mfma_f32_16x16x32_bf16 v[32:35], v[172:175], v[196:199], v[32:35]
	v_mfma_f32_16x16x32_bf16 v[24:27], v[180:183], v[196:199], v[24:27]
	v_mfma_f32_16x16x32_bf16 v[16:19], v[172:175], v[204:207], v[16:19]
	v_mfma_f32_16x16x32_bf16 v[8:11], v[180:183], v[204:207], v[8:11]
	v_mfma_f32_16x16x32_bf16 v[4:7], v[172:175], v[212:215], v[4:7]
	v_mfma_f32_16x16x32_bf16 v[0:3], v[180:183], v[212:215], v[0:3]
	s_barrier
	s_add_i32 s58, 0, 0x18000
	s_add_i32 s59, 0, 0x1c000
	v_add_u32_e32 v164, s58, v148
	v_add_u32_e32 v180, s59, v148
	ds_read_b128 v[152:155], v164
	ds_read_b128 v[156:159], v164 offset:1024
	ds_read_b128 v[160:163], v164 offset:2048
	ds_read_b128 v[164:167], v164 offset:3072
	ds_read_b128 v[168:171], v180
	ds_read_b128 v[172:175], v180 offset:1024
	ds_read_b128 v[176:179], v180 offset:2048
	ds_read_b128 v[180:183], v180 offset:3072
	s_add_u32 s28, s28, 0x40000
	s_addc_u32 s29, s29, 0
	s_mov_b32 m0, s36
	v_lshl_add_u64 v[222:223], s[28:29], 0, v[128:129]
	ds_read_b128 v[184:187], v151 offset:32768
	ds_read_b128 v[188:191], v151 offset:33792
	ds_read_b128 v[192:195], v151 offset:34816
	ds_read_b128 v[196:199], v151 offset:35840
	ds_read_b128 v[200:203], v151 offset:36864
	ds_read_b128 v[204:207], v151 offset:37888
	ds_read_b128 v[208:211], v151 offset:38912
	ds_read_b128 v[212:215], v151 offset:39936
	global_load_lds_dwordx4 v[222:223], off
	v_lshl_add_u64 v[222:223], s[28:29], 0, v[132:133]
	s_mov_b32 m0, s37
	s_nop 0
	global_load_lds_dwordx4 v[222:223], off
	s_waitcnt vmcnt(8)
	s_waitcnt lgkmcnt(0)
	s_barrier
	s_waitcnt lgkmcnt(0)
	v_mfma_f32_16x16x32_bf16 v[124:127], v[152:155], v[184:187], v[124:127]
	v_mfma_f32_16x16x32_bf16 v[120:123], v[160:163], v[184:187], v[120:123]
	v_mfma_f32_16x16x32_bf16 v[116:119], v[152:155], v[192:195], v[116:119]
	v_mfma_f32_16x16x32_bf16 v[108:111], v[160:163], v[192:195], v[108:111]
	v_mfma_f32_16x16x32_bf16 v[100:103], v[152:155], v[200:203], v[100:103]
	v_mfma_f32_16x16x32_bf16 v[92:95], v[160:163], v[200:203], v[92:95]
	v_mfma_f32_16x16x32_bf16 v[84:87], v[152:155], v[208:211], v[84:87]
	v_mfma_f32_16x16x32_bf16 v[76:79], v[160:163], v[208:211], v[76:79]
	v_mfma_f32_16x16x32_bf16 v[124:127], v[156:159], v[188:191], v[124:127]
	v_mfma_f32_16x16x32_bf16 v[120:123], v[164:167], v[188:191], v[120:123]
	v_mfma_f32_16x16x32_bf16 v[116:119], v[156:159], v[196:199], v[116:119]
	v_mfma_f32_16x16x32_bf16 v[108:111], v[164:167], v[196:199], v[108:111]
	v_mfma_f32_16x16x32_bf16 v[100:103], v[156:159], v[204:207], v[100:103]
	v_mfma_f32_16x16x32_bf16 v[92:95], v[164:167], v[204:207], v[92:95]
	v_mfma_f32_16x16x32_bf16 v[84:87], v[156:159], v[212:215], v[84:87]
	v_mfma_f32_16x16x32_bf16 v[76:79], v[164:167], v[212:215], v[76:79]
	v_mfma_f32_16x16x32_bf16 v[112:115], v[168:171], v[184:187], v[112:115]
	v_mfma_f32_16x16x32_bf16 v[104:107], v[176:179], v[184:187], v[104:107]
	v_mfma_f32_16x16x32_bf16 v[96:99], v[168:171], v[192:195], v[96:99]
	v_mfma_f32_16x16x32_bf16 v[88:91], v[176:179], v[192:195], v[88:91]
	v_mfma_f32_16x16x32_bf16 v[80:83], v[168:171], v[200:203], v[80:83]
	v_mfma_f32_16x16x32_bf16 v[72:75], v[176:179], v[200:203], v[72:75]
	v_mfma_f32_16x16x32_bf16 v[68:71], v[168:171], v[208:211], v[68:71]
	v_mfma_f32_16x16x32_bf16 v[64:67], v[176:179], v[208:211], v[64:67]
	v_mfma_f32_16x16x32_bf16 v[112:115], v[172:175], v[188:191], v[112:115]
	v_mfma_f32_16x16x32_bf16 v[104:107], v[180:183], v[188:191], v[104:107]
	v_mfma_f32_16x16x32_bf16 v[96:99], v[172:175], v[196:199], v[96:99]
	v_mfma_f32_16x16x32_bf16 v[88:91], v[180:183], v[196:199], v[88:91]
	v_mfma_f32_16x16x32_bf16 v[80:83], v[172:175], v[204:207], v[80:83]
	v_mfma_f32_16x16x32_bf16 v[72:75], v[180:183], v[204:207], v[72:75]
	v_mfma_f32_16x16x32_bf16 v[68:71], v[172:175], v[212:215], v[68:71]
	v_mfma_f32_16x16x32_bf16 v[64:67], v[180:183], v[212:215], v[64:67]
	s_barrier
	s_add_i32 s28, s58, s31
	v_lshl_add_u64 v[146:147], v[146:147], 0, s[12:13]
	s_mov_b32 m0, s28
	ds_read_b128 v[184:187], v151 offset:49152
	ds_read_b128 v[188:191], v151 offset:50176
	ds_read_b128 v[192:195], v151 offset:51200
	ds_read_b128 v[196:199], v151 offset:52224
	ds_read_b128 v[200:203], v151 offset:53248
	ds_read_b128 v[204:207], v151 offset:54272
	ds_read_b128 v[208:211], v151 offset:55296
	ds_read_b128 v[212:215], v151 offset:56320
	global_load_lds_dwordx4 v[146:147], off
	s_add_i32 m0, s28, 0x2000
	s_add_u32 s26, s26, 0x40080
	v_lshl_add_u64 v[146:147], v[216:217], 0, s[12:13]
	s_addc_u32 s27, s27, 0
	s_add_i32 s28, s59, s31
	global_load_lds_dwordx4 v[146:147], off
	v_lshl_add_u64 v[146:147], s[26:27], 0, v[130:131]
	s_mov_b32 m0, s28
	s_nop 0
	global_load_lds_dwordx4 v[146:147], off
	v_lshl_add_u64 v[146:147], s[26:27], 0, v[134:135]
	s_add_i32 m0, s28, 0x2000
	s_nop 0
	global_load_lds_dwordx4 v[146:147], off
	v_lshl_add_u64 v[146:147], v[218:219], 0, s[12:13]
	s_mov_b32 m0, s40
	s_nop 0
	global_load_lds_dwordx4 v[146:147], off
	v_lshl_add_u64 v[146:147], v[220:221], 0, s[12:13]
	s_mov_b32 m0, s41
	s_nop 0
	global_load_lds_dwordx4 v[146:147], off
	s_waitcnt vmcnt(8)
	s_waitcnt lgkmcnt(0)
	s_barrier
	s_waitcnt lgkmcnt(0)
	v_mfma_f32_16x16x32_bf16 v[60:63], v[152:155], v[184:187], v[60:63]
	v_mfma_f32_16x16x32_bf16 v[56:59], v[160:163], v[184:187], v[56:59]
	v_mfma_f32_16x16x32_bf16 v[52:55], v[152:155], v[192:195], v[52:55]
	v_mfma_f32_16x16x32_bf16 v[44:47], v[160:163], v[192:195], v[44:47]
	v_mfma_f32_16x16x32_bf16 v[36:39], v[152:155], v[200:203], v[36:39]
	v_mfma_f32_16x16x32_bf16 v[28:31], v[160:163], v[200:203], v[28:31]
	v_mfma_f32_16x16x32_bf16 v[20:23], v[152:155], v[208:211], v[20:23]
	v_mfma_f32_16x16x32_bf16 v[12:15], v[160:163], v[208:211], v[12:15]
	v_mfma_f32_16x16x32_bf16 v[60:63], v[156:159], v[188:191], v[60:63]
	v_mfma_f32_16x16x32_bf16 v[56:59], v[164:167], v[188:191], v[56:59]
	v_mfma_f32_16x16x32_bf16 v[52:55], v[156:159], v[196:199], v[52:55]
	v_mfma_f32_16x16x32_bf16 v[44:47], v[164:167], v[196:199], v[44:47]
	v_mfma_f32_16x16x32_bf16 v[36:39], v[156:159], v[204:207], v[36:39]
	v_mfma_f32_16x16x32_bf16 v[28:31], v[164:167], v[204:207], v[28:31]
	v_mfma_f32_16x16x32_bf16 v[20:23], v[156:159], v[212:215], v[20:23]
	v_mfma_f32_16x16x32_bf16 v[12:15], v[164:167], v[212:215], v[12:15]
	v_mfma_f32_16x16x32_bf16 v[48:51], v[168:171], v[184:187], v[48:51]
	v_mfma_f32_16x16x32_bf16 v[40:43], v[176:179], v[184:187], v[40:43]
	v_mfma_f32_16x16x32_bf16 v[32:35], v[168:171], v[192:195], v[32:35]
	v_mfma_f32_16x16x32_bf16 v[24:27], v[176:179], v[192:195], v[24:27]
	v_mfma_f32_16x16x32_bf16 v[16:19], v[168:171], v[200:203], v[16:19]
	v_mfma_f32_16x16x32_bf16 v[8:11], v[176:179], v[200:203], v[8:11]
	v_mfma_f32_16x16x32_bf16 v[4:7], v[168:171], v[208:211], v[4:7]
	v_mfma_f32_16x16x32_bf16 v[0:3], v[176:179], v[208:211], v[0:3]
	v_mfma_f32_16x16x32_bf16 v[48:51], v[172:175], v[188:191], v[48:51]
	v_mfma_f32_16x16x32_bf16 v[40:43], v[180:183], v[188:191], v[40:43]
	v_mfma_f32_16x16x32_bf16 v[32:35], v[172:175], v[196:199], v[32:35]
	v_mfma_f32_16x16x32_bf16 v[24:27], v[180:183], v[196:199], v[24:27]
	v_mfma_f32_16x16x32_bf16 v[16:19], v[172:175], v[204:207], v[16:19]
	v_mfma_f32_16x16x32_bf16 v[8:11], v[180:183], v[204:207], v[8:11]
	v_mfma_f32_16x16x32_bf16 v[4:7], v[172:175], v[212:215], v[4:7]
	v_mfma_f32_16x16x32_bf16 v[0:3], v[180:183], v[212:215], v[0:3]
	s_add_i32 s57, s57, 2
	s_add_u32 s24, s24, 0x100
	s_addc_u32 s25, s25, 0
	s_add_u32 s55, s55, 0x100
	s_addc_u32 s56, s56, 0
	s_cmp_gt_u32 s57, 13
	s_barrier
	s_cbranch_scc0 .LBB3_20
	s_mov_b64 vcc, s[0:1]
	s_cbranch_vccz .LBB3_23
	s_barrier

.LBB5_8:
	s_ashr_i32 s15, s14, 31
	s_lshl_b64 s[16:17], s[14:15], 19
	s_add_u32 s16, s28, s16
	v_cmp_lt_i64_e64 s[4:5], s[4:5], v[142:143]
	s_addc_u32 s17, s29, s17
	s_and_b64 s[18:19], s[4:5], exec
	s_cselect_b32 s15, s17, s23
	s_cselect_b32 s54, s16, s22
	s_ashr_i32 s13, s12, 31
	s_lshl_b64 s[18:19], s[12:13], 19
	s_add_u32 s18, s30, s18
	s_addc_u32 s19, s31, s19
	s_and_b64 s[26:27], s[4:5], exec
	s_cselect_b32 s13, s19, s25
	s_cselect_b32 s55, s18, s24
	s_add_u32 s22, s22, 0x40080
	s_addc_u32 s23, s23, 0
	s_add_u32 s56, s24, 0x100
	s_addc_u32 s57, s25, 0
	s_mov_b32 s58, -2
	ds_read_b128 v[152:155], v149
	ds_read_b128 v[156:159], v149 offset:1024
	ds_read_b128 v[160:163], v149 offset:2048
	ds_read_b128 v[164:167], v149 offset:3072
	ds_read_b128 v[168:171], v150
	ds_read_b128 v[172:175], v150 offset:1024
	ds_read_b128 v[176:179], v150 offset:2048
	ds_read_b128 v[180:183], v150 offset:3072
	s_add_u32 s24, s22, 0xfffc0080
	s_addc_u32 s25, s23, -1
	s_cmp_eq_u32 s58, 12
	s_cselect_b32 s27, s15, s25
	s_cselect_b32 s26, s54, s24
	s_cselect_b32 s25, s13, s57
	s_cselect_b32 s24, s55, s56
	v_lshl_add_u64 v[146:147], s[22:23], 0, v[138:139]
	s_add_i32 m0, s21, 0xc000
	ds_read_b128 v[184:187], v151
	ds_read_b128 v[188:191], v151 offset:1024
	ds_read_b128 v[192:195], v151 offset:2048
	ds_read_b128 v[196:199], v151 offset:3072
	ds_read_b128 v[200:203], v151 offset:4096
	ds_read_b128 v[204:207], v151 offset:5120
	ds_read_b128 v[208:211], v151 offset:6144
	ds_read_b128 v[212:215], v151 offset:7168
	global_load_lds_dwordx4 v[146:147], off
	v_lshl_add_u64 v[146:147], s[22:23], 0, v[140:141]
	s_add_i32 m0, s21, 0xe000
	s_nop 0
	global_load_lds_dwordx4 v[146:147], off
	s_waitcnt vmcnt(8)
	s_waitcnt lgkmcnt(0)
	s_barrier
	s_waitcnt lgkmcnt(0)
	v_mfma_f32_16x16x32_bf16 v[124:127], v[152:155], v[184:187], 0
	v_mfma_f32_16x16x32_bf16 v[120:123], v[160:163], v[184:187], 0
	v_mfma_f32_16x16x32_bf16 v[108:111], v[152:155], v[192:195], 0
	v_mfma_f32_16x16x32_bf16 v[104:107], v[160:163], v[192:195], 0
	v_mfma_f32_16x16x32_bf16 v[92:95], v[152:155], v[200:203], 0
	v_mfma_f32_16x16x32_bf16 v[88:91], v[160:163], v[200:203], 0
	v_mfma_f32_16x16x32_bf16 v[76:79], v[152:155], v[208:211], 0
	v_mfma_f32_16x16x32_bf16 v[72:75], v[160:163], v[208:211], 0
	v_mfma_f32_16x16x32_bf16 v[124:127], v[156:159], v[188:191], v[124:127]
	v_mfma_f32_16x16x32_bf16 v[120:123], v[164:167], v[188:191], v[120:123]
	v_mfma_f32_16x16x32_bf16 v[108:111], v[156:159], v[196:199], v[108:111]
	v_mfma_f32_16x16x32_bf16 v[104:107], v[164:167], v[196:199], v[104:107]
	v_mfma_f32_16x16x32_bf16 v[92:95], v[156:159], v[204:207], v[92:95]
	v_mfma_f32_16x16x32_bf16 v[88:91], v[164:167], v[204:207], v[88:91]
	v_mfma_f32_16x16x32_bf16 v[76:79], v[156:159], v[212:215], v[76:79]
	v_mfma_f32_16x16x32_bf16 v[72:75], v[164:167], v[212:215], v[72:75]
	v_mfma_f32_16x16x32_bf16 v[116:119], v[168:171], v[184:187], 0
	v_mfma_f32_16x16x32_bf16 v[112:115], v[176:179], v[184:187], 0
	v_mfma_f32_16x16x32_bf16 v[100:103], v[168:171], v[192:195], 0
	v_mfma_f32_16x16x32_bf16 v[96:99], v[176:179], v[192:195], 0
	v_mfma_f32_16x16x32_bf16 v[84:87], v[168:171], v[200:203], 0
	v_mfma_f32_16x16x32_bf16 v[80:83], v[176:179], v[200:203], 0
	v_mfma_f32_16x16x32_bf16 v[68:71], v[168:171], v[208:211], 0
	v_mfma_f32_16x16x32_bf16 v[64:67], v[176:179], v[208:211], 0
	v_mfma_f32_16x16x32_bf16 v[116:119], v[172:175], v[188:191], v[116:119]
	v_mfma_f32_16x16x32_bf16 v[112:115], v[180:183], v[188:191], v[112:115]
	v_mfma_f32_16x16x32_bf16 v[100:103], v[172:175], v[196:199], v[100:103]
	v_mfma_f32_16x16x32_bf16 v[96:99], v[180:183], v[196:199], v[96:99]
	v_mfma_f32_16x16x32_bf16 v[84:87], v[172:175], v[204:207], v[84:87]
	v_mfma_f32_16x16x32_bf16 v[80:83], v[180:183], v[204:207], v[80:83]
	v_mfma_f32_16x16x32_bf16 v[68:71], v[172:175], v[212:215], v[68:71]
	v_mfma_f32_16x16x32_bf16 v[64:67], v[180:183], v[212:215], v[64:67]
	s_barrier
	s_add_i32 s59, s43, s33
	v_lshl_add_u64 v[146:147], s[24:25], 0, v[132:133]
	s_mov_b32 m0, s59
	ds_read_b128 v[184:187], v151 offset:16384
	ds_read_b128 v[188:191], v151 offset:17408
	ds_read_b128 v[192:195], v151 offset:18432
	ds_read_b128 v[196:199], v151 offset:19456
	ds_read_b128 v[200:203], v151 offset:20480
	ds_read_b128 v[204:207], v151 offset:21504
	ds_read_b128 v[208:211], v151 offset:22528
	ds_read_b128 v[212:215], v151 offset:23552
	global_load_lds_dwordx4 v[146:147], off
	s_add_i32 m0, s59, 0x2000
	s_add_u32 s60, s24, 0x40000
	v_lshl_add_u64 v[216:217], s[24:25], 0, v[128:129]
	s_addc_u32 s61, s25, 0
	s_add_i32 s59, s44, s33
	global_load_lds_dwordx4 v[216:217], off
	v_lshl_add_u64 v[218:219], s[60:61], 0, v[132:133]
	s_mov_b32 m0, s59
	v_lshl_add_u64 v[220:221], s[26:27], 0, v[130:131]
	global_load_lds_dwordx4 v[218:219], off
	v_lshl_add_u64 v[218:219], s[60:61], 0, v[128:129]
	s_add_i32 m0, s59, 0x2000
	s_nop 0
	global_load_lds_dwordx4 v[218:219], off
	v_lshl_add_u64 v[218:219], s[26:27], 0, v[134:135]
	s_mov_b32 m0, s21
	s_nop 0
	global_load_lds_dwordx4 v[218:219], off
	s_mov_b32 m0, s36
	s_nop 0
	global_load_lds_dwordx4 v[220:221], off
	s_waitcnt vmcnt(8)
	s_waitcnt lgkmcnt(0)
	s_barrier
	s_waitcnt lgkmcnt(0)
	v_mfma_f32_16x16x32_bf16 v[60:63], v[152:155], v[184:187], 0
	v_mfma_f32_16x16x32_bf16 v[56:59], v[160:163], v[184:187], 0
	v_mfma_f32_16x16x32_bf16 v[44:47], v[152:155], v[192:195], 0
	v_mfma_f32_16x16x32_bf16 v[40:43], v[160:163], v[192:195], 0
	v_mfma_f32_16x16x32_bf16 v[28:31], v[152:155], v[200:203], 0
	v_mfma_f32_16x16x32_bf16 v[24:27], v[160:163], v[200:203], 0
	v_mfma_f32_16x16x32_bf16 v[12:15], v[152:155], v[208:211], 0
	v_mfma_f32_16x16x32_bf16 v[8:11], v[160:163], v[208:211], 0
	v_mfma_f32_16x16x32_bf16 v[60:63], v[156:159], v[188:191], v[60:63]
	v_mfma_f32_16x16x32_bf16 v[56:59], v[164:167], v[188:191], v[56:59]
	v_mfma_f32_16x16x32_bf16 v[44:47], v[156:159], v[196:199], v[44:47]
	v_mfma_f32_16x16x32_bf16 v[40:43], v[164:167], v[196:199], v[40:43]
	v_mfma_f32_16x16x32_bf16 v[28:31], v[156:159], v[204:207], v[28:31]
	v_mfma_f32_16x16x32_bf16 v[24:27], v[164:167], v[204:207], v[24:27]
	v_mfma_f32_16x16x32_bf16 v[12:15], v[156:159], v[212:215], v[12:15]
	v_mfma_f32_16x16x32_bf16 v[8:11], v[164:167], v[212:215], v[8:11]
	v_mfma_f32_16x16x32_bf16 v[52:55], v[168:171], v[184:187], 0
	v_mfma_f32_16x16x32_bf16 v[48:51], v[176:179], v[184:187], 0
	v_mfma_f32_16x16x32_bf16 v[36:39], v[168:171], v[192:195], 0
	v_mfma_f32_16x16x32_bf16 v[32:35], v[176:179], v[192:195], 0
	v_mfma_f32_16x16x32_bf16 v[20:23], v[168:171], v[200:203], 0
	v_mfma_f32_16x16x32_bf16 v[16:19], v[176:179], v[200:203], 0
	v_mfma_f32_16x16x32_bf16 v[4:7], v[168:171], v[208:211], 0
	v_mfma_f32_16x16x32_bf16 v[0:3], v[176:179], v[208:211], 0
	v_mfma_f32_16x16x32_bf16 v[52:55], v[172:175], v[188:191], v[52:55]
	v_mfma_f32_16x16x32_bf16 v[48:51], v[180:183], v[188:191], v[48:51]
	v_mfma_f32_16x16x32_bf16 v[36:39], v[172:175], v[196:199], v[36:39]
	v_mfma_f32_16x16x32_bf16 v[32:35], v[180:183], v[196:199], v[32:35]
	v_mfma_f32_16x16x32_bf16 v[20:23], v[172:175], v[204:207], v[20:23]
	v_mfma_f32_16x16x32_bf16 v[16:19], v[180:183], v[204:207], v[16:19]
	v_mfma_f32_16x16x32_bf16 v[4:7], v[172:175], v[212:215], v[4:7]
	v_mfma_f32_16x16x32_bf16 v[0:3], v[180:183], v[212:215], v[0:3]
	s_barrier
	s_add_i32 s59, 0, 0x18000
	s_add_i32 s60, 0, 0x1c000
	v_add_u32_e32 v164, s59, v148
	v_add_u32_e32 v180, s60, v148
	ds_read_b128 v[152:155], v164
	ds_read_b128 v[156:159], v164 offset:1024
	ds_read_b128 v[160:163], v164 offset:2048
	ds_read_b128 v[164:167], v164 offset:3072
	ds_read_b128 v[168:171], v180
	ds_read_b128 v[172:175], v180 offset:1024
	ds_read_b128 v[176:179], v180 offset:2048
	ds_read_b128 v[180:183], v180 offset:3072
	s_add_u32 s26, s26, 0x40000
	s_addc_u32 s27, s27, 0
	s_mov_b32 m0, s37
	v_lshl_add_u64 v[222:223], s[26:27], 0, v[134:135]
	ds_read_b128 v[184:187], v151 offset:32768
	ds_read_b128 v[188:191], v151 offset:33792
	ds_read_b128 v[192:195], v151 offset:34816
	ds_read_b128 v[196:199], v151 offset:35840
	ds_read_b128 v[200:203], v151 offset:36864
	ds_read_b128 v[204:207], v151 offset:37888
	ds_read_b128 v[208:211], v151 offset:38912
	ds_read_b128 v[212:215], v151 offset:39936
	global_load_lds_dwordx4 v[222:223], off
	v_lshl_add_u64 v[222:223], s[26:27], 0, v[130:131]
	s_mov_b32 m0, s38
	s_nop 0
	global_load_lds_dwordx4 v[222:223], off
	s_waitcnt vmcnt(8)
	s_waitcnt lgkmcnt(0)
	s_barrier
	s_waitcnt lgkmcnt(0)
	v_mfma_f32_16x16x32_bf16 v[124:127], v[152:155], v[184:187], v[124:127]
	v_mfma_f32_16x16x32_bf16 v[120:123], v[160:163], v[184:187], v[120:123]
	v_mfma_f32_16x16x32_bf16 v[108:111], v[152:155], v[192:195], v[108:111]
	v_mfma_f32_16x16x32_bf16 v[104:107], v[160:163], v[192:195], v[104:107]
	v_mfma_f32_16x16x32_bf16 v[92:95], v[152:155], v[200:203], v[92:95]
	v_mfma_f32_16x16x32_bf16 v[88:91], v[160:163], v[200:203], v[88:91]
	v_mfma_f32_16x16x32_bf16 v[76:79], v[152:155], v[208:211], v[76:79]
	v_mfma_f32_16x16x32_bf16 v[72:75], v[160:163], v[208:211], v[72:75]
	v_mfma_f32_16x16x32_bf16 v[124:127], v[156:159], v[188:191], v[124:127]
	v_mfma_f32_16x16x32_bf16 v[120:123], v[164:167], v[188:191], v[120:123]
	v_mfma_f32_16x16x32_bf16 v[108:111], v[156:159], v[196:199], v[108:111]
	v_mfma_f32_16x16x32_bf16 v[104:107], v[164:167], v[196:199], v[104:107]
	v_mfma_f32_16x16x32_bf16 v[92:95], v[156:159], v[204:207], v[92:95]
	v_mfma_f32_16x16x32_bf16 v[88:91], v[164:167], v[204:207], v[88:91]
	v_mfma_f32_16x16x32_bf16 v[76:79], v[156:159], v[212:215], v[76:79]
	v_mfma_f32_16x16x32_bf16 v[72:75], v[164:167], v[212:215], v[72:75]
	v_mfma_f32_16x16x32_bf16 v[116:119], v[168:171], v[184:187], v[116:119]
	v_mfma_f32_16x16x32_bf16 v[112:115], v[176:179], v[184:187], v[112:115]
	v_mfma_f32_16x16x32_bf16 v[100:103], v[168:171], v[192:195], v[100:103]
	v_mfma_f32_16x16x32_bf16 v[96:99], v[176:179], v[192:195], v[96:99]
	v_mfma_f32_16x16x32_bf16 v[84:87], v[168:171], v[200:203], v[84:87]
	v_mfma_f32_16x16x32_bf16 v[80:83], v[176:179], v[200:203], v[80:83]
	v_mfma_f32_16x16x32_bf16 v[68:71], v[168:171], v[208:211], v[68:71]
	v_mfma_f32_16x16x32_bf16 v[64:67], v[176:179], v[208:211], v[64:67]
	v_mfma_f32_16x16x32_bf16 v[116:119], v[172:175], v[188:191], v[116:119]
	v_mfma_f32_16x16x32_bf16 v[112:115], v[180:183], v[188:191], v[112:115]
	v_mfma_f32_16x16x32_bf16 v[100:103], v[172:175], v[196:199], v[100:103]
	v_mfma_f32_16x16x32_bf16 v[96:99], v[180:183], v[196:199], v[96:99]
	v_mfma_f32_16x16x32_bf16 v[84:87], v[172:175], v[204:207], v[84:87]
	v_mfma_f32_16x16x32_bf16 v[80:83], v[180:183], v[204:207], v[80:83]
	v_mfma_f32_16x16x32_bf16 v[68:71], v[172:175], v[212:215], v[68:71]
	v_mfma_f32_16x16x32_bf16 v[64:67], v[180:183], v[212:215], v[64:67]
	s_barrier
	s_add_i32 s26, s59, s33
	v_lshl_add_u64 v[146:147], v[146:147], 0, s[10:11]
	s_mov_b32 m0, s26
	ds_read_b128 v[184:187], v151 offset:49152
	ds_read_b128 v[188:191], v151 offset:50176
	ds_read_b128 v[192:195], v151 offset:51200
	ds_read_b128 v[196:199], v151 offset:52224
	ds_read_b128 v[200:203], v151 offset:53248
	ds_read_b128 v[204:207], v151 offset:54272
	ds_read_b128 v[208:211], v151 offset:55296
	ds_read_b128 v[212:215], v151 offset:56320
	global_load_lds_dwordx4 v[146:147], off
	s_add_i32 m0, s26, 0x2000
	s_add_u32 s24, s24, 0x40080
	v_lshl_add_u64 v[146:147], v[216:217], 0, s[10:11]
	s_addc_u32 s25, s25, 0
	s_add_i32 s26, s60, s33
	global_load_lds_dwordx4 v[146:147], off
	v_lshl_add_u64 v[146:147], s[24:25], 0, v[132:133]
	s_mov_b32 m0, s26
	s_nop 0
	global_load_lds_dwordx4 v[146:147], off
	v_lshl_add_u64 v[146:147], s[24:25], 0, v[128:129]
	s_add_i32 m0, s26, 0x2000
	s_nop 0
	global_load_lds_dwordx4 v[146:147], off
	v_lshl_add_u64 v[146:147], v[218:219], 0, s[10:11]
	s_mov_b32 m0, s40
	s_nop 0
	global_load_lds_dwordx4 v[146:147], off
	v_lshl_add_u64 v[146:147], v[220:221], 0, s[10:11]
	s_mov_b32 m0, s41
	s_nop 0
	global_load_lds_dwordx4 v[146:147], off
	s_waitcnt vmcnt(8)
	s_waitcnt lgkmcnt(0)
	s_barrier
	s_waitcnt lgkmcnt(0)
	v_mfma_f32_16x16x32_bf16 v[60:63], v[152:155], v[184:187], v[60:63]
	v_mfma_f32_16x16x32_bf16 v[56:59], v[160:163], v[184:187], v[56:59]
	v_mfma_f32_16x16x32_bf16 v[44:47], v[152:155], v[192:195], v[44:47]
	v_mfma_f32_16x16x32_bf16 v[40:43], v[160:163], v[192:195], v[40:43]
	v_mfma_f32_16x16x32_bf16 v[28:31], v[152:155], v[200:203], v[28:31]
	v_mfma_f32_16x16x32_bf16 v[24:27], v[160:163], v[200:203], v[24:27]
	v_mfma_f32_16x16x32_bf16 v[12:15], v[152:155], v[208:211], v[12:15]
	v_mfma_f32_16x16x32_bf16 v[8:11], v[160:163], v[208:211], v[8:11]
	v_mfma_f32_16x16x32_bf16 v[60:63], v[156:159], v[188:191], v[60:63]
	v_mfma_f32_16x16x32_bf16 v[56:59], v[164:167], v[188:191], v[56:59]
	v_mfma_f32_16x16x32_bf16 v[44:47], v[156:159], v[196:199], v[44:47]
	v_mfma_f32_16x16x32_bf16 v[40:43], v[164:167], v[196:199], v[40:43]
	v_mfma_f32_16x16x32_bf16 v[28:31], v[156:159], v[204:207], v[28:31]
	v_mfma_f32_16x16x32_bf16 v[24:27], v[164:167], v[204:207], v[24:27]
	v_mfma_f32_16x16x32_bf16 v[12:15], v[156:159], v[212:215], v[12:15]
	v_mfma_f32_16x16x32_bf16 v[8:11], v[164:167], v[212:215], v[8:11]
	v_mfma_f32_16x16x32_bf16 v[52:55], v[168:171], v[184:187], v[52:55]
	v_mfma_f32_16x16x32_bf16 v[48:51], v[176:179], v[184:187], v[48:51]
	v_mfma_f32_16x16x32_bf16 v[36:39], v[168:171], v[192:195], v[36:39]
	v_mfma_f32_16x16x32_bf16 v[32:35], v[176:179], v[192:195], v[32:35]
	v_mfma_f32_16x16x32_bf16 v[20:23], v[168:171], v[200:203], v[20:23]
	v_mfma_f32_16x16x32_bf16 v[16:19], v[176:179], v[200:203], v[16:19]
	v_mfma_f32_16x16x32_bf16 v[4:7], v[168:171], v[208:211], v[4:7]
	v_mfma_f32_16x16x32_bf16 v[0:3], v[176:179], v[208:211], v[0:3]
	v_mfma_f32_16x16x32_bf16 v[52:55], v[172:175], v[188:191], v[52:55]
	v_mfma_f32_16x16x32_bf16 v[48:51], v[180:183], v[188:191], v[48:51]
	v_mfma_f32_16x16x32_bf16 v[36:39], v[172:175], v[196:199], v[36:39]
	v_mfma_f32_16x16x32_bf16 v[32:35], v[180:183], v[196:199], v[32:35]
	v_mfma_f32_16x16x32_bf16 v[20:23], v[172:175], v[204:207], v[20:23]
	v_mfma_f32_16x16x32_bf16 v[16:19], v[180:183], v[204:207], v[16:19]
	v_mfma_f32_16x16x32_bf16 v[4:7], v[172:175], v[212:215], v[4:7]
	v_mfma_f32_16x16x32_bf16 v[0:3], v[180:183], v[212:215], v[0:3]
	s_add_i32 s58, s58, 2
	s_add_u32 s22, s22, 0x100
	s_addc_u32 s23, s23, 0
	s_add_u32 s56, s56, 0x100
	s_addc_u32 s57, s57, 0
	s_cmp_gt_u32 s58, 13
	s_barrier
.LBB5_9:
	ds_read_b128 v[152:155], v149
	ds_read_b128 v[156:159], v149 offset:1024
	ds_read_b128 v[160:163], v149 offset:2048
	ds_read_b128 v[164:167], v149 offset:3072
	ds_read_b128 v[168:171], v150
	ds_read_b128 v[172:175], v150 offset:1024
	ds_read_b128 v[176:179], v150 offset:2048
	ds_read_b128 v[180:183], v150 offset:3072
	s_add_u32 s24, s22, 0xfffc0080
	s_addc_u32 s25, s23, -1
	s_cmp_eq_u32 s58, 12
	s_cselect_b32 s27, s15, s25
	s_cselect_b32 s26, s54, s24
	s_cselect_b32 s25, s13, s57
	s_cselect_b32 s24, s55, s56
	v_lshl_add_u64 v[146:147], s[22:23], 0, v[138:139]
	s_add_i32 m0, s21, 0xc000
	ds_read_b128 v[184:187], v151
	ds_read_b128 v[188:191], v151 offset:1024
	ds_read_b128 v[192:195], v151 offset:2048
	ds_read_b128 v[196:199], v151 offset:3072
	ds_read_b128 v[200:203], v151 offset:4096
	ds_read_b128 v[204:207], v151 offset:5120
	ds_read_b128 v[208:211], v151 offset:6144
	ds_read_b128 v[212:215], v151 offset:7168
	global_load_lds_dwordx4 v[146:147], off
	v_lshl_add_u64 v[146:147], s[22:23], 0, v[140:141]
	s_add_i32 m0, s21, 0xe000
	s_nop 0
	global_load_lds_dwordx4 v[146:147], off
	s_waitcnt vmcnt(8)
	s_waitcnt lgkmcnt(0)
	s_barrier
	s_waitcnt lgkmcnt(0)
	v_mfma_f32_16x16x32_bf16 v[124:127], v[152:155], v[184:187], v[124:127]
	v_mfma_f32_16x16x32_bf16 v[120:123], v[160:163], v[184:187], v[120:123]
	v_mfma_f32_16x16x32_bf16 v[108:111], v[152:155], v[192:195], v[108:111]
	v_mfma_f32_16x16x32_bf16 v[104:107], v[160:163], v[192:195], v[104:107]
	v_mfma_f32_16x16x32_bf16 v[92:95], v[152:155], v[200:203], v[92:95]
	v_mfma_f32_16x16x32_bf16 v[88:91], v[160:163], v[200:203], v[88:91]
	v_mfma_f32_16x16x32_bf16 v[76:79], v[152:155], v[208:211], v[76:79]
	v_mfma_f32_16x16x32_bf16 v[72:75], v[160:163], v[208:211], v[72:75]
	v_mfma_f32_16x16x32_bf16 v[124:127], v[156:159], v[188:191], v[124:127]
	v_mfma_f32_16x16x32_bf16 v[120:123], v[164:167], v[188:191], v[120:123]
	v_mfma_f32_16x16x32_bf16 v[108:111], v[156:159], v[196:199], v[108:111]
	v_mfma_f32_16x16x32_bf16 v[104:107], v[164:167], v[196:199], v[104:107]
	v_mfma_f32_16x16x32_bf16 v[92:95], v[156:159], v[204:207], v[92:95]
	v_mfma_f32_16x16x32_bf16 v[88:91], v[164:167], v[204:207], v[88:91]
	v_mfma_f32_16x16x32_bf16 v[76:79], v[156:159], v[212:215], v[76:79]
	v_mfma_f32_16x16x32_bf16 v[72:75], v[164:167], v[212:215], v[72:75]
	v_mfma_f32_16x16x32_bf16 v[116:119], v[168:171], v[184:187], v[116:119]
	v_mfma_f32_16x16x32_bf16 v[112:115], v[176:179], v[184:187], v[112:115]
	v_mfma_f32_16x16x32_bf16 v[100:103], v[168:171], v[192:195], v[100:103]
	v_mfma_f32_16x16x32_bf16 v[96:99], v[176:179], v[192:195], v[96:99]
	v_mfma_f32_16x16x32_bf16 v[84:87], v[168:171], v[200:203], v[84:87]
	v_mfma_f32_16x16x32_bf16 v[80:83], v[176:179], v[200:203], v[80:83]
	v_mfma_f32_16x16x32_bf16 v[68:71], v[168:171], v[208:211], v[68:71]
	v_mfma_f32_16x16x32_bf16 v[64:67], v[176:179], v[208:211], v[64:67]
	v_mfma_f32_16x16x32_bf16 v[116:119], v[172:175], v[188:191], v[116:119]
	v_mfma_f32_16x16x32_bf16 v[112:115], v[180:183], v[188:191], v[112:115]
	v_mfma_f32_16x16x32_bf16 v[100:103], v[172:175], v[196:199], v[100:103]
	v_mfma_f32_16x16x32_bf16 v[96:99], v[180:183], v[196:199], v[96:99]
	v_mfma_f32_16x16x32_bf16 v[84:87], v[172:175], v[204:207], v[84:87]
	v_mfma_f32_16x16x32_bf16 v[80:83], v[180:183], v[204:207], v[80:83]
	v_mfma_f32_16x16x32_bf16 v[68:71], v[172:175], v[212:215], v[68:71]
	v_mfma_f32_16x16x32_bf16 v[64:67], v[180:183], v[212:215], v[64:67]
	s_barrier
	s_add_i32 s59, s43, s33
	v_lshl_add_u64 v[146:147], s[24:25], 0, v[132:133]
	s_mov_b32 m0, s59
	ds_read_b128 v[184:187], v151 offset:16384
	ds_read_b128 v[188:191], v151 offset:17408
	ds_read_b128 v[192:195], v151 offset:18432
	ds_read_b128 v[196:199], v151 offset:19456
	ds_read_b128 v[200:203], v151 offset:20480
	ds_read_b128 v[204:207], v151 offset:21504
	ds_read_b128 v[208:211], v151 offset:22528
	ds_read_b128 v[212:215], v151 offset:23552
	global_load_lds_dwordx4 v[146:147], off
	s_add_i32 m0, s59, 0x2000
	s_add_u32 s60, s24, 0x40000
	v_lshl_add_u64 v[216:217], s[24:25], 0, v[128:129]
	s_addc_u32 s61, s25, 0
	s_add_i32 s59, s44, s33
	global_load_lds_dwordx4 v[216:217], off
	v_lshl_add_u64 v[218:219], s[60:61], 0, v[132:133]
	s_mov_b32 m0, s59
	v_lshl_add_u64 v[220:221], s[26:27], 0, v[130:131]
	global_load_lds_dwordx4 v[218:219], off
	v_lshl_add_u64 v[218:219], s[60:61], 0, v[128:129]
	s_add_i32 m0, s59, 0x2000
	s_nop 0
	global_load_lds_dwordx4 v[218:219], off
	v_lshl_add_u64 v[218:219], s[26:27], 0, v[134:135]
	s_mov_b32 m0, s21
	s_nop 0
	global_load_lds_dwordx4 v[218:219], off
	s_mov_b32 m0, s36
	s_nop 0
	global_load_lds_dwordx4 v[220:221], off
	s_waitcnt vmcnt(8)
	s_waitcnt lgkmcnt(0)
	s_barrier
	s_waitcnt lgkmcnt(0)
	v_mfma_f32_16x16x32_bf16 v[60:63], v[152:155], v[184:187], v[60:63]
	v_mfma_f32_16x16x32_bf16 v[56:59], v[160:163], v[184:187], v[56:59]
	v_mfma_f32_16x16x32_bf16 v[44:47], v[152:155], v[192:195], v[44:47]
	v_mfma_f32_16x16x32_bf16 v[40:43], v[160:163], v[192:195], v[40:43]
	v_mfma_f32_16x16x32_bf16 v[28:31], v[152:155], v[200:203], v[28:31]
	v_mfma_f32_16x16x32_bf16 v[24:27], v[160:163], v[200:203], v[24:27]
	v_mfma_f32_16x16x32_bf16 v[12:15], v[152:155], v[208:211], v[12:15]
	v_mfma_f32_16x16x32_bf16 v[8:11], v[160:163], v[208:211], v[8:11]
	v_mfma_f32_16x16x32_bf16 v[60:63], v[156:159], v[188:191], v[60:63]
	v_mfma_f32_16x16x32_bf16 v[56:59], v[164:167], v[188:191], v[56:59]
	v_mfma_f32_16x16x32_bf16 v[44:47], v[156:159], v[196:199], v[44:47]
	v_mfma_f32_16x16x32_bf16 v[40:43], v[164:167], v[196:199], v[40:43]
	v_mfma_f32_16x16x32_bf16 v[28:31], v[156:159], v[204:207], v[28:31]
	v_mfma_f32_16x16x32_bf16 v[24:27], v[164:167], v[204:207], v[24:27]
	v_mfma_f32_16x16x32_bf16 v[12:15], v[156:159], v[212:215], v[12:15]
	v_mfma_f32_16x16x32_bf16 v[8:11], v[164:167], v[212:215], v[8:11]
	v_mfma_f32_16x16x32_bf16 v[52:55], v[168:171], v[184:187], v[52:55]
	v_mfma_f32_16x16x32_bf16 v[48:51], v[176:179], v[184:187], v[48:51]
	v_mfma_f32_16x16x32_bf16 v[36:39], v[168:171], v[192:195], v[36:39]
	v_mfma_f32_16x16x32_bf16 v[32:35], v[176:179], v[192:195], v[32:35]
	v_mfma_f32_16x16x32_bf16 v[20:23], v[168:171], v[200:203], v[20:23]
	v_mfma_f32_16x16x32_bf16 v[16:19], v[176:179], v[200:203], v[16:19]
	v_mfma_f32_16x16x32_bf16 v[4:7], v[168:171], v[208:211], v[4:7]
	v_mfma_f32_16x16x32_bf16 v[0:3], v[176:179], v[208:211], v[0:3]
	v_mfma_f32_16x16x32_bf16 v[52:55], v[172:175], v[188:191], v[52:55]
	v_mfma_f32_16x16x32_bf16 v[48:51], v[180:183], v[188:191], v[48:51]
	v_mfma_f32_16x16x32_bf16 v[36:39], v[172:175], v[196:199], v[36:39]
	v_mfma_f32_16x16x32_bf16 v[32:35], v[180:183], v[196:199], v[32:35]
	v_mfma_f32_16x16x32_bf16 v[20:23], v[172:175], v[204:207], v[20:23]
	v_mfma_f32_16x16x32_bf16 v[16:19], v[180:183], v[204:207], v[16:19]
	v_mfma_f32_16x16x32_bf16 v[4:7], v[172:175], v[212:215], v[4:7]
	v_mfma_f32_16x16x32_bf16 v[0:3], v[180:183], v[212:215], v[0:3]
	s_barrier
	s_add_i32 s59, 0, 0x18000
	s_add_i32 s60, 0, 0x1c000
	v_add_u32_e32 v164, s59, v148
	v_add_u32_e32 v180, s60, v148
	ds_read_b128 v[152:155], v164
	ds_read_b128 v[156:159], v164 offset:1024
	ds_read_b128 v[160:163], v164 offset:2048
	ds_read_b128 v[164:167], v164 offset:3072
	ds_read_b128 v[168:171], v180
	ds_read_b128 v[172:175], v180 offset:1024
	ds_read_b128 v[176:179], v180 offset:2048
	ds_read_b128 v[180:183], v180 offset:3072
	s_add_u32 s26, s26, 0x40000
	s_addc_u32 s27, s27, 0
	s_mov_b32 m0, s37
	v_lshl_add_u64 v[222:223], s[26:27], 0, v[134:135]
	ds_read_b128 v[184:187], v151 offset:32768
	ds_read_b128 v[188:191], v151 offset:33792
	ds_read_b128 v[192:195], v151 offset:34816
	ds_read_b128 v[196:199], v151 offset:35840
	ds_read_b128 v[200:203], v151 offset:36864
	ds_read_b128 v[204:207], v151 offset:37888
	ds_read_b128 v[208:211], v151 offset:38912
	ds_read_b128 v[212:215], v151 offset:39936
	global_load_lds_dwordx4 v[222:223], off
	v_lshl_add_u64 v[222:223], s[26:27], 0, v[130:131]
	s_mov_b32 m0, s38
	s_nop 0
	global_load_lds_dwordx4 v[222:223], off
	s_waitcnt vmcnt(8)
	s_waitcnt lgkmcnt(0)
	s_barrier
	s_waitcnt lgkmcnt(0)
	v_mfma_f32_16x16x32_bf16 v[124:127], v[152:155], v[184:187], v[124:127]
	v_mfma_f32_16x16x32_bf16 v[120:123], v[160:163], v[184:187], v[120:123]
	v_mfma_f32_16x16x32_bf16 v[108:111], v[152:155], v[192:195], v[108:111]
	v_mfma_f32_16x16x32_bf16 v[104:107], v[160:163], v[192:195], v[104:107]
	v_mfma_f32_16x16x32_bf16 v[92:95], v[152:155], v[200:203], v[92:95]
	v_mfma_f32_16x16x32_bf16 v[88:91], v[160:163], v[200:203], v[88:91]
	v_mfma_f32_16x16x32_bf16 v[76:79], v[152:155], v[208:211], v[76:79]
	v_mfma_f32_16x16x32_bf16 v[72:75], v[160:163], v[208:211], v[72:75]
	v_mfma_f32_16x16x32_bf16 v[124:127], v[156:159], v[188:191], v[124:127]
	v_mfma_f32_16x16x32_bf16 v[120:123], v[164:167], v[188:191], v[120:123]
	v_mfma_f32_16x16x32_bf16 v[108:111], v[156:159], v[196:199], v[108:111]
	v_mfma_f32_16x16x32_bf16 v[104:107], v[164:167], v[196:199], v[104:107]
	v_mfma_f32_16x16x32_bf16 v[92:95], v[156:159], v[204:207], v[92:95]
	v_mfma_f32_16x16x32_bf16 v[88:91], v[164:167], v[204:207], v[88:91]
	v_mfma_f32_16x16x32_bf16 v[76:79], v[156:159], v[212:215], v[76:79]
	v_mfma_f32_16x16x32_bf16 v[72:75], v[164:167], v[212:215], v[72:75]
	v_mfma_f32_16x16x32_bf16 v[116:119], v[168:171], v[184:187], v[116:119]
	v_mfma_f32_16x16x32_bf16 v[112:115], v[176:179], v[184:187], v[112:115]
	v_mfma_f32_16x16x32_bf16 v[100:103], v[168:171], v[192:195], v[100:103]
	v_mfma_f32_16x16x32_bf16 v[96:99], v[176:179], v[192:195], v[96:99]
	v_mfma_f32_16x16x32_bf16 v[84:87], v[168:171], v[200:203], v[84:87]
	v_mfma_f32_16x16x32_bf16 v[80:83], v[176:179], v[200:203], v[80:83]
	v_mfma_f32_16x16x32_bf16 v[68:71], v[168:171], v[208:211], v[68:71]
	v_mfma_f32_16x16x32_bf16 v[64:67], v[176:179], v[208:211], v[64:67]
	v_mfma_f32_16x16x32_bf16 v[116:119], v[172:175], v[188:191], v[116:119]
	v_mfma_f32_16x16x32_bf16 v[112:115], v[180:183], v[188:191], v[112:115]
	v_mfma_f32_16x16x32_bf16 v[100:103], v[172:175], v[196:199], v[100:103]
	v_mfma_f32_16x16x32_bf16 v[96:99], v[180:183], v[196:199], v[96:99]
	v_mfma_f32_16x16x32_bf16 v[84:87], v[172:175], v[204:207], v[84:87]
	v_mfma_f32_16x16x32_bf16 v[80:83], v[180:183], v[204:207], v[80:83]
	v_mfma_f32_16x16x32_bf16 v[68:71], v[172:175], v[212:215], v[68:71]
	v_mfma_f32_16x16x32_bf16 v[64:67], v[180:183], v[212:215], v[64:67]
	s_barrier
	s_add_i32 s26, s59, s33
	v_lshl_add_u64 v[146:147], v[146:147], 0, s[10:11]
	s_mov_b32 m0, s26
	ds_read_b128 v[184:187], v151 offset:49152
	ds_read_b128 v[188:191], v151 offset:50176
	ds_read_b128 v[192:195], v151 offset:51200
	ds_read_b128 v[196:199], v151 offset:52224
	ds_read_b128 v[200:203], v151 offset:53248
	ds_read_b128 v[204:207], v151 offset:54272
	ds_read_b128 v[208:211], v151 offset:55296
	ds_read_b128 v[212:215], v151 offset:56320
	global_load_lds_dwordx4 v[146:147], off
	s_add_i32 m0, s26, 0x2000
	s_add_u32 s24, s24, 0x40080
	v_lshl_add_u64 v[146:147], v[216:217], 0, s[10:11]
	s_addc_u32 s25, s25, 0
	s_add_i32 s26, s60, s33
	global_load_lds_dwordx4 v[146:147], off
	v_lshl_add_u64 v[146:147], s[24:25], 0, v[132:133]
	s_mov_b32 m0, s26
	s_nop 0
	global_load_lds_dwordx4 v[146:147], off
	v_lshl_add_u64 v[146:147], s[24:25], 0, v[128:129]
	s_add_i32 m0, s26, 0x2000
	s_nop 0
	global_load_lds_dwordx4 v[146:147], off
	v_lshl_add_u64 v[146:147], v[218:219], 0, s[10:11]
	s_mov_b32 m0, s40
	s_nop 0
	global_load_lds_dwordx4 v[146:147], off
	v_lshl_add_u64 v[146:147], v[220:221], 0, s[10:11]
	s_mov_b32 m0, s41
	s_nop 0
	global_load_lds_dwordx4 v[146:147], off
	s_waitcnt vmcnt(8)
	s_waitcnt lgkmcnt(0)
	s_barrier
	s_waitcnt lgkmcnt(0)
	v_mfma_f32_16x16x32_bf16 v[60:63], v[152:155], v[184:187], v[60:63]
	v_mfma_f32_16x16x32_bf16 v[56:59], v[160:163], v[184:187], v[56:59]
	v_mfma_f32_16x16x32_bf16 v[44:47], v[152:155], v[192:195], v[44:47]
	v_mfma_f32_16x16x32_bf16 v[40:43], v[160:163], v[192:195], v[40:43]
	v_mfma_f32_16x16x32_bf16 v[28:31], v[152:155], v[200:203], v[28:31]
	v_mfma_f32_16x16x32_bf16 v[24:27], v[160:163], v[200:203], v[24:27]
	v_mfma_f32_16x16x32_bf16 v[12:15], v[152:155], v[208:211], v[12:15]
	v_mfma_f32_16x16x32_bf16 v[8:11], v[160:163], v[208:211], v[8:11]
	v_mfma_f32_16x16x32_bf16 v[60:63], v[156:159], v[188:191], v[60:63]
	v_mfma_f32_16x16x32_bf16 v[56:59], v[164:167], v[188:191], v[56:59]
	v_mfma_f32_16x16x32_bf16 v[44:47], v[156:159], v[196:199], v[44:47]
	v_mfma_f32_16x16x32_bf16 v[40:43], v[164:167], v[196:199], v[40:43]
	v_mfma_f32_16x16x32_bf16 v[28:31], v[156:159], v[204:207], v[28:31]
	v_mfma_f32_16x16x32_bf16 v[24:27], v[164:167], v[204:207], v[24:27]
	v_mfma_f32_16x16x32_bf16 v[12:15], v[156:159], v[212:215], v[12:15]
	v_mfma_f32_16x16x32_bf16 v[8:11], v[164:167], v[212:215], v[8:11]
	v_mfma_f32_16x16x32_bf16 v[52:55], v[168:171], v[184:187], v[52:55]
	v_mfma_f32_16x16x32_bf16 v[48:51], v[176:179], v[184:187], v[48:51]
	v_mfma_f32_16x16x32_bf16 v[36:39], v[168:171], v[192:195], v[36:39]
	v_mfma_f32_16x16x32_bf16 v[32:35], v[176:179], v[192:195], v[32:35]
	v_mfma_f32_16x16x32_bf16 v[20:23], v[168:171], v[200:203], v[20:23]
	v_mfma_f32_16x16x32_bf16 v[16:19], v[176:179], v[200:203], v[16:19]
	v_mfma_f32_16x16x32_bf16 v[4:7], v[168:171], v[208:211], v[4:7]
	v_mfma_f32_16x16x32_bf16 v[0:3], v[176:179], v[208:211], v[0:3]
	v_mfma_f32_16x16x32_bf16 v[52:55], v[172:175], v[188:191], v[52:55]
	v_mfma_f32_16x16x32_bf16 v[48:51], v[180:183], v[188:191], v[48:51]
	v_mfma_f32_16x16x32_bf16 v[36:39], v[172:175], v[196:199], v[36:39]
	v_mfma_f32_16x16x32_bf16 v[32:35], v[180:183], v[196:199], v[32:35]
	v_mfma_f32_16x16x32_bf16 v[20:23], v[172:175], v[204:207], v[20:23]
	v_mfma_f32_16x16x32_bf16 v[16:19], v[180:183], v[204:207], v[16:19]
	v_mfma_f32_16x16x32_bf16 v[4:7], v[172:175], v[212:215], v[4:7]
	v_mfma_f32_16x16x32_bf16 v[0:3], v[180:183], v[212:215], v[0:3]
	s_add_i32 s58, s58, 2
	s_add_u32 s22, s22, 0x100
	s_addc_u32 s23, s23, 0
	s_add_u32 s56, s56, 0x100
	s_addc_u32 s57, s57, 0
	s_cmp_gt_u32 s58, 13
	s_barrier
	s_cbranch_scc0 .LBB5_9
	s_mov_b64 vcc, s[0:1]
	s_cbranch_vccz .LBB5_12
	s_barrier

.LBB6_19:
	s_ashr_i32 s17, s16, 31
	s_lshl_b64 s[18:19], s[16:17], 21
	s_add_u32 s18, s33, s18
	v_cmp_lt_i64_e64 s[4:5], s[4:5], v[142:143]
	s_addc_u32 s19, s34, s19
	s_and_b64 s[20:21], s[4:5], exec
	s_cselect_b32 s17, s19, s25
	s_cselect_b32 s53, s18, s24
	s_ashr_i32 s15, s14, 31
	s_lshl_b64 s[20:21], s[14:15], 21
	s_add_u32 s20, s6, s20
	s_addc_u32 s21, s7, s21
	s_and_b64 s[28:29], s[4:5], exec
	s_cselect_b32 s15, s21, s27
	s_cselect_b32 s54, s20, s26
	s_add_u32 s24, s24, 0x100080
	s_addc_u32 s25, s25, 0
	s_add_u32 s55, s26, 0x100
	s_addc_u32 s56, s27, 0
	s_mov_b32 s57, -2
	ds_read_b128 v[152:155], v149
	ds_read_b128 v[156:159], v149 offset:1024
	ds_read_b128 v[160:163], v149 offset:2048
	ds_read_b128 v[164:167], v149 offset:3072
	ds_read_b128 v[168:171], v150
	ds_read_b128 v[172:175], v150 offset:1024
	ds_read_b128 v[176:179], v150 offset:2048
	ds_read_b128 v[180:183], v150 offset:3072
	s_add_u32 s26, s24, 0xfff00080
	s_addc_u32 s27, s25, -1
	s_cmp_eq_u32 s57, 60
	s_cselect_b32 s29, s17, s27
	s_cselect_b32 s28, s53, s26
	s_cselect_b32 s27, s15, s56
	s_cselect_b32 s26, s54, s55
	v_lshl_add_u64 v[146:147], s[24:25], 0, v[138:139]
	s_add_i32 m0, s23, 0xc000
	ds_read_b128 v[184:187], v151
	ds_read_b128 v[188:191], v151 offset:1024
	ds_read_b128 v[192:195], v151 offset:2048
	ds_read_b128 v[196:199], v151 offset:3072
	ds_read_b128 v[200:203], v151 offset:4096
	ds_read_b128 v[204:207], v151 offset:5120
	ds_read_b128 v[208:211], v151 offset:6144
	ds_read_b128 v[212:215], v151 offset:7168
	global_load_lds_dwordx4 v[146:147], off
	v_lshl_add_u64 v[146:147], s[24:25], 0, v[140:141]
	s_add_i32 m0, s23, 0xe000
	s_nop 0
	global_load_lds_dwordx4 v[146:147], off
	s_waitcnt vmcnt(8)
	s_waitcnt lgkmcnt(0)
	s_barrier
	s_waitcnt lgkmcnt(0)
	v_mfma_f32_16x16x32_bf16 v[124:127], v[152:155], v[184:187], 0
	v_mfma_f32_16x16x32_bf16 v[120:123], v[160:163], v[184:187], 0
	v_mfma_f32_16x16x32_bf16 v[116:119], v[152:155], v[192:195], 0
	v_mfma_f32_16x16x32_bf16 v[108:111], v[160:163], v[192:195], 0
	v_mfma_f32_16x16x32_bf16 v[100:103], v[152:155], v[200:203], 0
	v_mfma_f32_16x16x32_bf16 v[92:95], v[160:163], v[200:203], 0
	v_mfma_f32_16x16x32_bf16 v[84:87], v[152:155], v[208:211], 0
	v_mfma_f32_16x16x32_bf16 v[76:79], v[160:163], v[208:211], 0
	v_mfma_f32_16x16x32_bf16 v[124:127], v[156:159], v[188:191], v[124:127]
	v_mfma_f32_16x16x32_bf16 v[120:123], v[164:167], v[188:191], v[120:123]
	v_mfma_f32_16x16x32_bf16 v[116:119], v[156:159], v[196:199], v[116:119]
	v_mfma_f32_16x16x32_bf16 v[108:111], v[164:167], v[196:199], v[108:111]
	v_mfma_f32_16x16x32_bf16 v[100:103], v[156:159], v[204:207], v[100:103]
	v_mfma_f32_16x16x32_bf16 v[92:95], v[164:167], v[204:207], v[92:95]
	v_mfma_f32_16x16x32_bf16 v[84:87], v[156:159], v[212:215], v[84:87]
	v_mfma_f32_16x16x32_bf16 v[76:79], v[164:167], v[212:215], v[76:79]
	v_mfma_f32_16x16x32_bf16 v[112:115], v[168:171], v[184:187], 0
	v_mfma_f32_16x16x32_bf16 v[104:107], v[176:179], v[184:187], 0
	v_mfma_f32_16x16x32_bf16 v[96:99], v[168:171], v[192:195], 0
	v_mfma_f32_16x16x32_bf16 v[88:91], v[176:179], v[192:195], 0
	v_mfma_f32_16x16x32_bf16 v[80:83], v[168:171], v[200:203], 0
	v_mfma_f32_16x16x32_bf16 v[72:75], v[176:179], v[200:203], 0
	v_mfma_f32_16x16x32_bf16 v[68:71], v[168:171], v[208:211], 0
	v_mfma_f32_16x16x32_bf16 v[64:67], v[176:179], v[208:211], 0
	v_mfma_f32_16x16x32_bf16 v[112:115], v[172:175], v[188:191], v[112:115]
	v_mfma_f32_16x16x32_bf16 v[104:107], v[180:183], v[188:191], v[104:107]
	v_mfma_f32_16x16x32_bf16 v[96:99], v[172:175], v[196:199], v[96:99]
	v_mfma_f32_16x16x32_bf16 v[88:91], v[180:183], v[196:199], v[88:91]
	v_mfma_f32_16x16x32_bf16 v[80:83], v[172:175], v[204:207], v[80:83]
	v_mfma_f32_16x16x32_bf16 v[72:75], v[180:183], v[204:207], v[72:75]
	v_mfma_f32_16x16x32_bf16 v[68:71], v[172:175], v[212:215], v[68:71]
	v_mfma_f32_16x16x32_bf16 v[64:67], v[180:183], v[212:215], v[64:67]
	s_barrier
	s_add_i32 s58, s45, s31
	v_lshl_add_u64 v[146:147], s[26:27], 0, v[130:131]
	s_mov_b32 m0, s58
	ds_read_b128 v[184:187], v151 offset:16384
	ds_read_b128 v[188:191], v151 offset:17408
	ds_read_b128 v[192:195], v151 offset:18432
	ds_read_b128 v[196:199], v151 offset:19456
	ds_read_b128 v[200:203], v151 offset:20480
	ds_read_b128 v[204:207], v151 offset:21504
	ds_read_b128 v[208:211], v151 offset:22528
	ds_read_b128 v[212:215], v151 offset:23552
	global_load_lds_dwordx4 v[146:147], off
	s_add_i32 m0, s58, 0x2000
	s_add_u32 s58, s26, 0x100000
	v_lshl_add_u64 v[216:217], s[26:27], 0, v[134:135]
	s_addc_u32 s59, s27, 0
	s_add_i32 s60, s46, s31
	global_load_lds_dwordx4 v[216:217], off
	v_lshl_add_u64 v[218:219], s[58:59], 0, v[130:131]
	s_mov_b32 m0, s60
	v_lshl_add_u64 v[220:221], s[28:29], 0, v[132:133]
	global_load_lds_dwordx4 v[218:219], off
	v_lshl_add_u64 v[218:219], s[58:59], 0, v[134:135]
	s_add_i32 m0, s60, 0x2000
	s_nop 0
	global_load_lds_dwordx4 v[218:219], off
	v_lshl_add_u64 v[218:219], s[28:29], 0, v[128:129]
	s_mov_b32 m0, s23
	s_nop 0
	global_load_lds_dwordx4 v[218:219], off
	s_mov_b32 m0, s35
	s_nop 0
	global_load_lds_dwordx4 v[220:221], off
	s_waitcnt vmcnt(8)
	s_waitcnt lgkmcnt(0)
	s_barrier
	s_waitcnt lgkmcnt(0)
	v_mfma_f32_16x16x32_bf16 v[60:63], v[152:155], v[184:187], 0
	v_mfma_f32_16x16x32_bf16 v[56:59], v[160:163], v[184:187], 0
	v_mfma_f32_16x16x32_bf16 v[52:55], v[152:155], v[192:195], 0
	v_mfma_f32_16x16x32_bf16 v[44:47], v[160:163], v[192:195], 0
	v_mfma_f32_16x16x32_bf16 v[36:39], v[152:155], v[200:203], 0
	v_mfma_f32_16x16x32_bf16 v[28:31], v[160:163], v[200:203], 0
	v_mfma_f32_16x16x32_bf16 v[20:23], v[152:155], v[208:211], 0
	v_mfma_f32_16x16x32_bf16 v[12:15], v[160:163], v[208:211], 0
	v_mfma_f32_16x16x32_bf16 v[60:63], v[156:159], v[188:191], v[60:63]
	v_mfma_f32_16x16x32_bf16 v[56:59], v[164:167], v[188:191], v[56:59]
	v_mfma_f32_16x16x32_bf16 v[52:55], v[156:159], v[196:199], v[52:55]
	v_mfma_f32_16x16x32_bf16 v[44:47], v[164:167], v[196:199], v[44:47]
	v_mfma_f32_16x16x32_bf16 v[36:39], v[156:159], v[204:207], v[36:39]
	v_mfma_f32_16x16x32_bf16 v[28:31], v[164:167], v[204:207], v[28:31]
	v_mfma_f32_16x16x32_bf16 v[20:23], v[156:159], v[212:215], v[20:23]
	v_mfma_f32_16x16x32_bf16 v[12:15], v[164:167], v[212:215], v[12:15]
	v_mfma_f32_16x16x32_bf16 v[48:51], v[168:171], v[184:187], 0
	v_mfma_f32_16x16x32_bf16 v[40:43], v[176:179], v[184:187], 0
	v_mfma_f32_16x16x32_bf16 v[32:35], v[168:171], v[192:195], 0
	v_mfma_f32_16x16x32_bf16 v[24:27], v[176:179], v[192:195], 0
	v_mfma_f32_16x16x32_bf16 v[16:19], v[168:171], v[200:203], 0
	v_mfma_f32_16x16x32_bf16 v[8:11], v[176:179], v[200:203], 0
	v_mfma_f32_16x16x32_bf16 v[4:7], v[168:171], v[208:211], 0
	v_mfma_f32_16x16x32_bf16 v[0:3], v[176:179], v[208:211], 0
	v_mfma_f32_16x16x32_bf16 v[48:51], v[172:175], v[188:191], v[48:51]
	v_mfma_f32_16x16x32_bf16 v[40:43], v[180:183], v[188:191], v[40:43]
	v_mfma_f32_16x16x32_bf16 v[32:35], v[172:175], v[196:199], v[32:35]
	v_mfma_f32_16x16x32_bf16 v[24:27], v[180:183], v[196:199], v[24:27]
	v_mfma_f32_16x16x32_bf16 v[16:19], v[172:175], v[204:207], v[16:19]
	v_mfma_f32_16x16x32_bf16 v[8:11], v[180:183], v[204:207], v[8:11]
	v_mfma_f32_16x16x32_bf16 v[4:7], v[172:175], v[212:215], v[4:7]
	v_mfma_f32_16x16x32_bf16 v[0:3], v[180:183], v[212:215], v[0:3]
	s_barrier
	s_add_i32 s58, 0, 0x18000
	s_add_i32 s59, 0, 0x1c000
	v_add_u32_e32 v164, s58, v148
	v_add_u32_e32 v180, s59, v148
	ds_read_b128 v[152:155], v164
	ds_read_b128 v[156:159], v164 offset:1024
	ds_read_b128 v[160:163], v164 offset:2048
	ds_read_b128 v[164:167], v164 offset:3072
	ds_read_b128 v[168:171], v180
	ds_read_b128 v[172:175], v180 offset:1024
	ds_read_b128 v[176:179], v180 offset:2048
	ds_read_b128 v[180:183], v180 offset:3072
	s_add_u32 s28, s28, 0x100000
	s_addc_u32 s29, s29, 0
	s_mov_b32 m0, s36
	v_lshl_add_u64 v[222:223], s[28:29], 0, v[128:129]
	ds_read_b128 v[184:187], v151 offset:32768
	ds_read_b128 v[188:191], v151 offset:33792
	ds_read_b128 v[192:195], v151 offset:34816
	ds_read_b128 v[196:199], v151 offset:35840
	ds_read_b128 v[200:203], v151 offset:36864
	ds_read_b128 v[204:207], v151 offset:37888
	ds_read_b128 v[208:211], v151 offset:38912
	ds_read_b128 v[212:215], v151 offset:39936
	global_load_lds_dwordx4 v[222:223], off
	v_lshl_add_u64 v[222:223], s[28:29], 0, v[132:133]
	s_mov_b32 m0, s37
	s_nop 0
	global_load_lds_dwordx4 v[222:223], off
	s_waitcnt vmcnt(8)
	s_waitcnt lgkmcnt(0)
	s_barrier
	s_waitcnt lgkmcnt(0)
	v_mfma_f32_16x16x32_bf16 v[124:127], v[152:155], v[184:187], v[124:127]
	v_mfma_f32_16x16x32_bf16 v[120:123], v[160:163], v[184:187], v[120:123]
	v_mfma_f32_16x16x32_bf16 v[116:119], v[152:155], v[192:195], v[116:119]
	v_mfma_f32_16x16x32_bf16 v[108:111], v[160:163], v[192:195], v[108:111]
	v_mfma_f32_16x16x32_bf16 v[100:103], v[152:155], v[200:203], v[100:103]
	v_mfma_f32_16x16x32_bf16 v[92:95], v[160:163], v[200:203], v[92:95]
	v_mfma_f32_16x16x32_bf16 v[84:87], v[152:155], v[208:211], v[84:87]
	v_mfma_f32_16x16x32_bf16 v[76:79], v[160:163], v[208:211], v[76:79]
	v_mfma_f32_16x16x32_bf16 v[124:127], v[156:159], v[188:191], v[124:127]
	v_mfma_f32_16x16x32_bf16 v[120:123], v[164:167], v[188:191], v[120:123]
	v_mfma_f32_16x16x32_bf16 v[116:119], v[156:159], v[196:199], v[116:119]
	v_mfma_f32_16x16x32_bf16 v[108:111], v[164:167], v[196:199], v[108:111]
	v_mfma_f32_16x16x32_bf16 v[100:103], v[156:159], v[204:207], v[100:103]
	v_mfma_f32_16x16x32_bf16 v[92:95], v[164:167], v[204:207], v[92:95]
	v_mfma_f32_16x16x32_bf16 v[84:87], v[156:159], v[212:215], v[84:87]
	v_mfma_f32_16x16x32_bf16 v[76:79], v[164:167], v[212:215], v[76:79]
	v_mfma_f32_16x16x32_bf16 v[112:115], v[168:171], v[184:187], v[112:115]
	v_mfma_f32_16x16x32_bf16 v[104:107], v[176:179], v[184:187], v[104:107]
	v_mfma_f32_16x16x32_bf16 v[96:99], v[168:171], v[192:195], v[96:99]
	v_mfma_f32_16x16x32_bf16 v[88:91], v[176:179], v[192:195], v[88:91]
	v_mfma_f32_16x16x32_bf16 v[80:83], v[168:171], v[200:203], v[80:83]
	v_mfma_f32_16x16x32_bf16 v[72:75], v[176:179], v[200:203], v[72:75]
	v_mfma_f32_16x16x32_bf16 v[68:71], v[168:171], v[208:211], v[68:71]
	v_mfma_f32_16x16x32_bf16 v[64:67], v[176:179], v[208:211], v[64:67]
	v_mfma_f32_16x16x32_bf16 v[112:115], v[172:175], v[188:191], v[112:115]
	v_mfma_f32_16x16x32_bf16 v[104:107], v[180:183], v[188:191], v[104:107]
	v_mfma_f32_16x16x32_bf16 v[96:99], v[172:175], v[196:199], v[96:99]
	v_mfma_f32_16x16x32_bf16 v[88:91], v[180:183], v[196:199], v[88:91]
	v_mfma_f32_16x16x32_bf16 v[80:83], v[172:175], v[204:207], v[80:83]
	v_mfma_f32_16x16x32_bf16 v[72:75], v[180:183], v[204:207], v[72:75]
	v_mfma_f32_16x16x32_bf16 v[68:71], v[172:175], v[212:215], v[68:71]
	v_mfma_f32_16x16x32_bf16 v[64:67], v[180:183], v[212:215], v[64:67]
	s_barrier
	s_add_i32 s28, s58, s31
	v_lshl_add_u64 v[146:147], v[146:147], 0, s[12:13]
	s_mov_b32 m0, s28
	ds_read_b128 v[184:187], v151 offset:49152
	ds_read_b128 v[188:191], v151 offset:50176
	ds_read_b128 v[192:195], v151 offset:51200
	ds_read_b128 v[196:199], v151 offset:52224
	ds_read_b128 v[200:203], v151 offset:53248
	ds_read_b128 v[204:207], v151 offset:54272
	ds_read_b128 v[208:211], v151 offset:55296
	ds_read_b128 v[212:215], v151 offset:56320
	global_load_lds_dwordx4 v[146:147], off
	s_add_i32 m0, s28, 0x2000
	s_add_u32 s26, s26, 0x100080
	v_lshl_add_u64 v[146:147], v[216:217], 0, s[12:13]
	s_addc_u32 s27, s27, 0
	s_add_i32 s28, s59, s31
	global_load_lds_dwordx4 v[146:147], off
	v_lshl_add_u64 v[146:147], s[26:27], 0, v[130:131]
	s_mov_b32 m0, s28
	s_nop 0
	global_load_lds_dwordx4 v[146:147], off
	v_lshl_add_u64 v[146:147], s[26:27], 0, v[134:135]
	s_add_i32 m0, s28, 0x2000
	s_nop 0
	global_load_lds_dwordx4 v[146:147], off
	v_lshl_add_u64 v[146:147], v[218:219], 0, s[12:13]
	s_mov_b32 m0, s40
	s_nop 0
	global_load_lds_dwordx4 v[146:147], off
	v_lshl_add_u64 v[146:147], v[220:221], 0, s[12:13]
	s_mov_b32 m0, s41
	s_nop 0
	global_load_lds_dwordx4 v[146:147], off
	s_waitcnt vmcnt(8)
	s_waitcnt lgkmcnt(0)
	s_barrier
	s_waitcnt lgkmcnt(0)
	v_mfma_f32_16x16x32_bf16 v[60:63], v[152:155], v[184:187], v[60:63]
	v_mfma_f32_16x16x32_bf16 v[56:59], v[160:163], v[184:187], v[56:59]
	v_mfma_f32_16x16x32_bf16 v[52:55], v[152:155], v[192:195], v[52:55]
	v_mfma_f32_16x16x32_bf16 v[44:47], v[160:163], v[192:195], v[44:47]
	v_mfma_f32_16x16x32_bf16 v[36:39], v[152:155], v[200:203], v[36:39]
	v_mfma_f32_16x16x32_bf16 v[28:31], v[160:163], v[200:203], v[28:31]
	v_mfma_f32_16x16x32_bf16 v[20:23], v[152:155], v[208:211], v[20:23]
	v_mfma_f32_16x16x32_bf16 v[12:15], v[160:163], v[208:211], v[12:15]
	v_mfma_f32_16x16x32_bf16 v[60:63], v[156:159], v[188:191], v[60:63]
	v_mfma_f32_16x16x32_bf16 v[56:59], v[164:167], v[188:191], v[56:59]
	v_mfma_f32_16x16x32_bf16 v[52:55], v[156:159], v[196:199], v[52:55]
	v_mfma_f32_16x16x32_bf16 v[44:47], v[164:167], v[196:199], v[44:47]
	v_mfma_f32_16x16x32_bf16 v[36:39], v[156:159], v[204:207], v[36:39]
	v_mfma_f32_16x16x32_bf16 v[28:31], v[164:167], v[204:207], v[28:31]
	v_mfma_f32_16x16x32_bf16 v[20:23], v[156:159], v[212:215], v[20:23]
	v_mfma_f32_16x16x32_bf16 v[12:15], v[164:167], v[212:215], v[12:15]
	v_mfma_f32_16x16x32_bf16 v[48:51], v[168:171], v[184:187], v[48:51]
	v_mfma_f32_16x16x32_bf16 v[40:43], v[176:179], v[184:187], v[40:43]
	v_mfma_f32_16x16x32_bf16 v[32:35], v[168:171], v[192:195], v[32:35]
	v_mfma_f32_16x16x32_bf16 v[24:27], v[176:179], v[192:195], v[24:27]
	v_mfma_f32_16x16x32_bf16 v[16:19], v[168:171], v[200:203], v[16:19]
	v_mfma_f32_16x16x32_bf16 v[8:11], v[176:179], v[200:203], v[8:11]
	v_mfma_f32_16x16x32_bf16 v[4:7], v[168:171], v[208:211], v[4:7]
	v_mfma_f32_16x16x32_bf16 v[0:3], v[176:179], v[208:211], v[0:3]
	v_mfma_f32_16x16x32_bf16 v[48:51], v[172:175], v[188:191], v[48:51]
	v_mfma_f32_16x16x32_bf16 v[40:43], v[180:183], v[188:191], v[40:43]
	v_mfma_f32_16x16x32_bf16 v[32:35], v[172:175], v[196:199], v[32:35]
	v_mfma_f32_16x16x32_bf16 v[24:27], v[180:183], v[196:199], v[24:27]
	v_mfma_f32_16x16x32_bf16 v[16:19], v[172:175], v[204:207], v[16:19]
	v_mfma_f32_16x16x32_bf16 v[8:11], v[180:183], v[204:207], v[8:11]
	v_mfma_f32_16x16x32_bf16 v[4:7], v[172:175], v[212:215], v[4:7]
	v_mfma_f32_16x16x32_bf16 v[0:3], v[180:183], v[212:215], v[0:3]
	s_add_i32 s57, s57, 2
	s_add_u32 s24, s24, 0x100
	s_addc_u32 s25, s25, 0
	s_add_u32 s55, s55, 0x100
	s_addc_u32 s56, s56, 0
	s_cmp_gt_u32 s57, 61
	s_barrier
.LBB6_20:
	ds_read_b128 v[152:155], v149
	ds_read_b128 v[156:159], v149 offset:1024
	ds_read_b128 v[160:163], v149 offset:2048
	ds_read_b128 v[164:167], v149 offset:3072
	ds_read_b128 v[168:171], v150
	ds_read_b128 v[172:175], v150 offset:1024
	ds_read_b128 v[176:179], v150 offset:2048
	ds_read_b128 v[180:183], v150 offset:3072
	s_add_u32 s26, s24, 0xfff00080
	s_addc_u32 s27, s25, -1
	s_cmp_eq_u32 s57, 60
	s_cselect_b32 s29, s17, s27
	s_cselect_b32 s28, s53, s26
	s_cselect_b32 s27, s15, s56
	s_cselect_b32 s26, s54, s55
	v_lshl_add_u64 v[146:147], s[24:25], 0, v[138:139]
	s_add_i32 m0, s23, 0xc000
	ds_read_b128 v[184:187], v151
	ds_read_b128 v[188:191], v151 offset:1024
	ds_read_b128 v[192:195], v151 offset:2048
	ds_read_b128 v[196:199], v151 offset:3072
	ds_read_b128 v[200:203], v151 offset:4096
	ds_read_b128 v[204:207], v151 offset:5120
	ds_read_b128 v[208:211], v151 offset:6144
	ds_read_b128 v[212:215], v151 offset:7168
	global_load_lds_dwordx4 v[146:147], off
	v_lshl_add_u64 v[146:147], s[24:25], 0, v[140:141]
	s_add_i32 m0, s23, 0xe000
	s_nop 0
	global_load_lds_dwordx4 v[146:147], off
	s_waitcnt vmcnt(8)
	s_waitcnt lgkmcnt(0)
	s_barrier
	s_waitcnt lgkmcnt(0)
	v_mfma_f32_16x16x32_bf16 v[124:127], v[152:155], v[184:187], v[124:127]
	v_mfma_f32_16x16x32_bf16 v[120:123], v[160:163], v[184:187], v[120:123]
	v_mfma_f32_16x16x32_bf16 v[116:119], v[152:155], v[192:195], v[116:119]
	v_mfma_f32_16x16x32_bf16 v[108:111], v[160:163], v[192:195], v[108:111]
	v_mfma_f32_16x16x32_bf16 v[100:103], v[152:155], v[200:203], v[100:103]
	v_mfma_f32_16x16x32_bf16 v[92:95], v[160:163], v[200:203], v[92:95]
	v_mfma_f32_16x16x32_bf16 v[84:87], v[152:155], v[208:211], v[84:87]
	v_mfma_f32_16x16x32_bf16 v[76:79], v[160:163], v[208:211], v[76:79]
	v_mfma_f32_16x16x32_bf16 v[124:127], v[156:159], v[188:191], v[124:127]
	v_mfma_f32_16x16x32_bf16 v[120:123], v[164:167], v[188:191], v[120:123]
	v_mfma_f32_16x16x32_bf16 v[116:119], v[156:159], v[196:199], v[116:119]
	v_mfma_f32_16x16x32_bf16 v[108:111], v[164:167], v[196:199], v[108:111]
	v_mfma_f32_16x16x32_bf16 v[100:103], v[156:159], v[204:207], v[100:103]
	v_mfma_f32_16x16x32_bf16 v[92:95], v[164:167], v[204:207], v[92:95]
	v_mfma_f32_16x16x32_bf16 v[84:87], v[156:159], v[212:215], v[84:87]
	v_mfma_f32_16x16x32_bf16 v[76:79], v[164:167], v[212:215], v[76:79]
	v_mfma_f32_16x16x32_bf16 v[112:115], v[168:171], v[184:187], v[112:115]
	v_mfma_f32_16x16x32_bf16 v[104:107], v[176:179], v[184:187], v[104:107]
	v_mfma_f32_16x16x32_bf16 v[96:99], v[168:171], v[192:195], v[96:99]
	v_mfma_f32_16x16x32_bf16 v[88:91], v[176:179], v[192:195], v[88:91]
	v_mfma_f32_16x16x32_bf16 v[80:83], v[168:171], v[200:203], v[80:83]
	v_mfma_f32_16x16x32_bf16 v[72:75], v[176:179], v[200:203], v[72:75]
	v_mfma_f32_16x16x32_bf16 v[68:71], v[168:171], v[208:211], v[68:71]
	v_mfma_f32_16x16x32_bf16 v[64:67], v[176:179], v[208:211], v[64:67]
	v_mfma_f32_16x16x32_bf16 v[112:115], v[172:175], v[188:191], v[112:115]
	v_mfma_f32_16x16x32_bf16 v[104:107], v[180:183], v[188:191], v[104:107]
	v_mfma_f32_16x16x32_bf16 v[96:99], v[172:175], v[196:199], v[96:99]
	v_mfma_f32_16x16x32_bf16 v[88:91], v[180:183], v[196:199], v[88:91]
	v_mfma_f32_16x16x32_bf16 v[80:83], v[172:175], v[204:207], v[80:83]
	v_mfma_f32_16x16x32_bf16 v[72:75], v[180:183], v[204:207], v[72:75]
	v_mfma_f32_16x16x32_bf16 v[68:71], v[172:175], v[212:215], v[68:71]
	v_mfma_f32_16x16x32_bf16 v[64:67], v[180:183], v[212:215], v[64:67]
	s_barrier
	s_add_i32 s58, s45, s31
	v_lshl_add_u64 v[146:147], s[26:27], 0, v[130:131]
	s_mov_b32 m0, s58
	ds_read_b128 v[184:187], v151 offset:16384
	ds_read_b128 v[188:191], v151 offset:17408
	ds_read_b128 v[192:195], v151 offset:18432
	ds_read_b128 v[196:199], v151 offset:19456
	ds_read_b128 v[200:203], v151 offset:20480
	ds_read_b128 v[204:207], v151 offset:21504
	ds_read_b128 v[208:211], v151 offset:22528
	ds_read_b128 v[212:215], v151 offset:23552
	global_load_lds_dwordx4 v[146:147], off
	s_add_i32 m0, s58, 0x2000
	s_add_u32 s58, s26, 0x100000
	v_lshl_add_u64 v[216:217], s[26:27], 0, v[134:135]
	s_addc_u32 s59, s27, 0
	s_add_i32 s60, s46, s31
	global_load_lds_dwordx4 v[216:217], off
	v_lshl_add_u64 v[218:219], s[58:59], 0, v[130:131]
	s_mov_b32 m0, s60
	v_lshl_add_u64 v[220:221], s[28:29], 0, v[132:133]
	global_load_lds_dwordx4 v[218:219], off
	v_lshl_add_u64 v[218:219], s[58:59], 0, v[134:135]
	s_add_i32 m0, s60, 0x2000
	s_nop 0
	global_load_lds_dwordx4 v[218:219], off
	v_lshl_add_u64 v[218:219], s[28:29], 0, v[128:129]
	s_mov_b32 m0, s23
	s_nop 0
	global_load_lds_dwordx4 v[218:219], off
	s_mov_b32 m0, s35
	s_nop 0
	global_load_lds_dwordx4 v[220:221], off
	s_waitcnt vmcnt(8)
	s_waitcnt lgkmcnt(0)
	s_barrier
	s_waitcnt lgkmcnt(0)
	v_mfma_f32_16x16x32_bf16 v[60:63], v[152:155], v[184:187], v[60:63]
	v_mfma_f32_16x16x32_bf16 v[56:59], v[160:163], v[184:187], v[56:59]
	v_mfma_f32_16x16x32_bf16 v[52:55], v[152:155], v[192:195], v[52:55]
	v_mfma_f32_16x16x32_bf16 v[44:47], v[160:163], v[192:195], v[44:47]
	v_mfma_f32_16x16x32_bf16 v[36:39], v[152:155], v[200:203], v[36:39]
	v_mfma_f32_16x16x32_bf16 v[28:31], v[160:163], v[200:203], v[28:31]
	v_mfma_f32_16x16x32_bf16 v[20:23], v[152:155], v[208:211], v[20:23]
	v_mfma_f32_16x16x32_bf16 v[12:15], v[160:163], v[208:211], v[12:15]
	v_mfma_f32_16x16x32_bf16 v[60:63], v[156:159], v[188:191], v[60:63]
	v_mfma_f32_16x16x32_bf16 v[56:59], v[164:167], v[188:191], v[56:59]
	v_mfma_f32_16x16x32_bf16 v[52:55], v[156:159], v[196:199], v[52:55]
	v_mfma_f32_16x16x32_bf16 v[44:47], v[164:167], v[196:199], v[44:47]
	v_mfma_f32_16x16x32_bf16 v[36:39], v[156:159], v[204:207], v[36:39]
	v_mfma_f32_16x16x32_bf16 v[28:31], v[164:167], v[204:207], v[28:31]
	v_mfma_f32_16x16x32_bf16 v[20:23], v[156:159], v[212:215], v[20:23]
	v_mfma_f32_16x16x32_bf16 v[12:15], v[164:167], v[212:215], v[12:15]
	v_mfma_f32_16x16x32_bf16 v[48:51], v[168:171], v[184:187], v[48:51]
	v_mfma_f32_16x16x32_bf16 v[40:43], v[176:179], v[184:187], v[40:43]
	v_mfma_f32_16x16x32_bf16 v[32:35], v[168:171], v[192:195], v[32:35]
	v_mfma_f32_16x16x32_bf16 v[24:27], v[176:179], v[192:195], v[24:27]
	v_mfma_f32_16x16x32_bf16 v[16:19], v[168:171], v[200:203], v[16:19]
	v_mfma_f32_16x16x32_bf16 v[8:11], v[176:179], v[200:203], v[8:11]
	v_mfma_f32_16x16x32_bf16 v[4:7], v[168:171], v[208:211], v[4:7]
	v_mfma_f32_16x16x32_bf16 v[0:3], v[176:179], v[208:211], v[0:3]
	v_mfma_f32_16x16x32_bf16 v[48:51], v[172:175], v[188:191], v[48:51]
	v_mfma_f32_16x16x32_bf16 v[40:43], v[180:183], v[188:191], v[40:43]
	v_mfma_f32_16x16x32_bf16 v[32:35], v[172:175], v[196:199], v[32:35]
	v_mfma_f32_16x16x32_bf16 v[24:27], v[180:183], v[196:199], v[24:27]
	v_mfma_f32_16x16x32_bf16 v[16:19], v[172:175], v[204:207], v[16:19]
	v_mfma_f32_16x16x32_bf16 v[8:11], v[180:183], v[204:207], v[8:11]
	v_mfma_f32_16x16x32_bf16 v[4:7], v[172:175], v[212:215], v[4:7]
	v_mfma_f32_16x16x32_bf16 v[0:3], v[180:183], v[212:215], v[0:3]
	s_barrier
	s_add_i32 s58, 0, 0x18000
	s_add_i32 s59, 0, 0x1c000
	v_add_u32_e32 v164, s58, v148
	v_add_u32_e32 v180, s59, v148
	ds_read_b128 v[152:155], v164
	ds_read_b128 v[156:159], v164 offset:1024
	ds_read_b128 v[160:163], v164 offset:2048
	ds_read_b128 v[164:167], v164 offset:3072
	ds_read_b128 v[168:171], v180
	ds_read_b128 v[172:175], v180 offset:1024
	ds_read_b128 v[176:179], v180 offset:2048
	ds_read_b128 v[180:183], v180 offset:3072
	s_add_u32 s28, s28, 0x100000
	s_addc_u32 s29, s29, 0
	s_mov_b32 m0, s36
	v_lshl_add_u64 v[222:223], s[28:29], 0, v[128:129]
	ds_read_b128 v[184:187], v151 offset:32768
	ds_read_b128 v[188:191], v151 offset:33792
	ds_read_b128 v[192:195], v151 offset:34816
	ds_read_b128 v[196:199], v151 offset:35840
	ds_read_b128 v[200:203], v151 offset:36864
	ds_read_b128 v[204:207], v151 offset:37888
	ds_read_b128 v[208:211], v151 offset:38912
	ds_read_b128 v[212:215], v151 offset:39936
	global_load_lds_dwordx4 v[222:223], off
	v_lshl_add_u64 v[222:223], s[28:29], 0, v[132:133]
	s_mov_b32 m0, s37
	s_nop 0
	global_load_lds_dwordx4 v[222:223], off
	s_waitcnt vmcnt(8)
	s_waitcnt lgkmcnt(0)
	s_barrier
	s_waitcnt lgkmcnt(0)
	v_mfma_f32_16x16x32_bf16 v[124:127], v[152:155], v[184:187], v[124:127]
	v_mfma_f32_16x16x32_bf16 v[120:123], v[160:163], v[184:187], v[120:123]
	v_mfma_f32_16x16x32_bf16 v[116:119], v[152:155], v[192:195], v[116:119]
	v_mfma_f32_16x16x32_bf16 v[108:111], v[160:163], v[192:195], v[108:111]
	v_mfma_f32_16x16x32_bf16 v[100:103], v[152:155], v[200:203], v[100:103]
	v_mfma_f32_16x16x32_bf16 v[92:95], v[160:163], v[200:203], v[92:95]
	v_mfma_f32_16x16x32_bf16 v[84:87], v[152:155], v[208:211], v[84:87]
	v_mfma_f32_16x16x32_bf16 v[76:79], v[160:163], v[208:211], v[76:79]
	v_mfma_f32_16x16x32_bf16 v[124:127], v[156:159], v[188:191], v[124:127]
	v_mfma_f32_16x16x32_bf16 v[120:123], v[164:167], v[188:191], v[120:123]
	v_mfma_f32_16x16x32_bf16 v[116:119], v[156:159], v[196:199], v[116:119]
	v_mfma_f32_16x16x32_bf16 v[108:111], v[164:167], v[196:199], v[108:111]
	v_mfma_f32_16x16x32_bf16 v[100:103], v[156:159], v[204:207], v[100:103]
	v_mfma_f32_16x16x32_bf16 v[92:95], v[164:167], v[204:207], v[92:95]
	v_mfma_f32_16x16x32_bf16 v[84:87], v[156:159], v[212:215], v[84:87]
	v_mfma_f32_16x16x32_bf16 v[76:79], v[164:167], v[212:215], v[76:79]
	v_mfma_f32_16x16x32_bf16 v[112:115], v[168:171], v[184:187], v[112:115]
	v_mfma_f32_16x16x32_bf16 v[104:107], v[176:179], v[184:187], v[104:107]
	v_mfma_f32_16x16x32_bf16 v[96:99], v[168:171], v[192:195], v[96:99]
	v_mfma_f32_16x16x32_bf16 v[88:91], v[176:179], v[192:195], v[88:91]
	v_mfma_f32_16x16x32_bf16 v[80:83], v[168:171], v[200:203], v[80:83]
	v_mfma_f32_16x16x32_bf16 v[72:75], v[176:179], v[200:203], v[72:75]
	v_mfma_f32_16x16x32_bf16 v[68:71], v[168:171], v[208:211], v[68:71]
	v_mfma_f32_16x16x32_bf16 v[64:67], v[176:179], v[208:211], v[64:67]
	v_mfma_f32_16x16x32_bf16 v[112:115], v[172:175], v[188:191], v[112:115]
	v_mfma_f32_16x16x32_bf16 v[104:107], v[180:183], v[188:191], v[104:107]
	v_mfma_f32_16x16x32_bf16 v[96:99], v[172:175], v[196:199], v[96:99]
	v_mfma_f32_16x16x32_bf16 v[88:91], v[180:183], v[196:199], v[88:91]
	v_mfma_f32_16x16x32_bf16 v[80:83], v[172:175], v[204:207], v[80:83]
	v_mfma_f32_16x16x32_bf16 v[72:75], v[180:183], v[204:207], v[72:75]
	v_mfma_f32_16x16x32_bf16 v[68:71], v[172:175], v[212:215], v[68:71]
	v_mfma_f32_16x16x32_bf16 v[64:67], v[180:183], v[212:215], v[64:67]
	s_barrier
	s_add_i32 s28, s58, s31
	v_lshl_add_u64 v[146:147], v[146:147], 0, s[12:13]
	s_mov_b32 m0, s28
	ds_read_b128 v[184:187], v151 offset:49152
	ds_read_b128 v[188:191], v151 offset:50176
	ds_read_b128 v[192:195], v151 offset:51200
	ds_read_b128 v[196:199], v151 offset:52224
	ds_read_b128 v[200:203], v151 offset:53248
	ds_read_b128 v[204:207], v151 offset:54272
	ds_read_b128 v[208:211], v151 offset:55296
	ds_read_b128 v[212:215], v151 offset:56320
	global_load_lds_dwordx4 v[146:147], off
	s_add_i32 m0, s28, 0x2000
	s_add_u32 s26, s26, 0x100080
	v_lshl_add_u64 v[146:147], v[216:217], 0, s[12:13]
	s_addc_u32 s27, s27, 0
	s_add_i32 s28, s59, s31
	global_load_lds_dwordx4 v[146:147], off
	v_lshl_add_u64 v[146:147], s[26:27], 0, v[130:131]
	s_mov_b32 m0, s28
	s_nop 0
	global_load_lds_dwordx4 v[146:147], off
	v_lshl_add_u64 v[146:147], s[26:27], 0, v[134:135]
	s_add_i32 m0, s28, 0x2000
	s_nop 0
	global_load_lds_dwordx4 v[146:147], off
	v_lshl_add_u64 v[146:147], v[218:219], 0, s[12:13]
	s_mov_b32 m0, s40
	s_nop 0
	global_load_lds_dwordx4 v[146:147], off
	v_lshl_add_u64 v[146:147], v[220:221], 0, s[12:13]
	s_mov_b32 m0, s41
	s_nop 0
	global_load_lds_dwordx4 v[146:147], off
	s_waitcnt vmcnt(8)
	s_waitcnt lgkmcnt(0)
	s_barrier
	s_waitcnt lgkmcnt(0)
	v_mfma_f32_16x16x32_bf16 v[60:63], v[152:155], v[184:187], v[60:63]
	v_mfma_f32_16x16x32_bf16 v[56:59], v[160:163], v[184:187], v[56:59]
	v_mfma_f32_16x16x32_bf16 v[52:55], v[152:155], v[192:195], v[52:55]
	v_mfma_f32_16x16x32_bf16 v[44:47], v[160:163], v[192:195], v[44:47]
	v_mfma_f32_16x16x32_bf16 v[36:39], v[152:155], v[200:203], v[36:39]
	v_mfma_f32_16x16x32_bf16 v[28:31], v[160:163], v[200:203], v[28:31]
	v_mfma_f32_16x16x32_bf16 v[20:23], v[152:155], v[208:211], v[20:23]
	v_mfma_f32_16x16x32_bf16 v[12:15], v[160:163], v[208:211], v[12:15]
	v_mfma_f32_16x16x32_bf16 v[60:63], v[156:159], v[188:191], v[60:63]
	v_mfma_f32_16x16x32_bf16 v[56:59], v[164:167], v[188:191], v[56:59]
	v_mfma_f32_16x16x32_bf16 v[52:55], v[156:159], v[196:199], v[52:55]
	v_mfma_f32_16x16x32_bf16 v[44:47], v[164:167], v[196:199], v[44:47]
	v_mfma_f32_16x16x32_bf16 v[36:39], v[156:159], v[204:207], v[36:39]
	v_mfma_f32_16x16x32_bf16 v[28:31], v[164:167], v[204:207], v[28:31]
	v_mfma_f32_16x16x32_bf16 v[20:23], v[156:159], v[212:215], v[20:23]
	v_mfma_f32_16x16x32_bf16 v[12:15], v[164:167], v[212:215], v[12:15]
	v_mfma_f32_16x16x32_bf16 v[48:51], v[168:171], v[184:187], v[48:51]
	v_mfma_f32_16x16x32_bf16 v[40:43], v[176:179], v[184:187], v[40:43]
	v_mfma_f32_16x16x32_bf16 v[32:35], v[168:171], v[192:195], v[32:35]
	v_mfma_f32_16x16x32_bf16 v[24:27], v[176:179], v[192:195], v[24:27]
	v_mfma_f32_16x16x32_bf16 v[16:19], v[168:171], v[200:203], v[16:19]
	v_mfma_f32_16x16x32_bf16 v[8:11], v[176:179], v[200:203], v[8:11]
	v_mfma_f32_16x16x32_bf16 v[4:7], v[168:171], v[208:211], v[4:7]
	v_mfma_f32_16x16x32_bf16 v[0:3], v[176:179], v[208:211], v[0:3]
	v_mfma_f32_16x16x32_bf16 v[48:51], v[172:175], v[188:191], v[48:51]
	v_mfma_f32_16x16x32_bf16 v[40:43], v[180:183], v[188:191], v[40:43]
	v_mfma_f32_16x16x32_bf16 v[32:35], v[172:175], v[196:199], v[32:35]
	v_mfma_f32_16x16x32_bf16 v[24:27], v[180:183], v[196:199], v[24:27]
	v_mfma_f32_16x16x32_bf16 v[16:19], v[172:175], v[204:207], v[16:19]
	v_mfma_f32_16x16x32_bf16 v[8:11], v[180:183], v[204:207], v[8:11]
	v_mfma_f32_16x16x32_bf16 v[4:7], v[172:175], v[212:215], v[4:7]
	v_mfma_f32_16x16x32_bf16 v[0:3], v[180:183], v[212:215], v[0:3]
	s_add_i32 s57, s57, 2
	s_add_u32 s24, s24, 0x100
	s_addc_u32 s25, s25, 0
	s_add_u32 s55, s55, 0x100
	s_addc_u32 s56, s56, 0
	s_cmp_gt_u32 s57, 61
	s_barrier
	s_cbranch_scc0 .LBB6_20
	s_mov_b64 vcc, s[0:1]
	s_cbranch_vccz .LBB6_23
	s_barrier

.LBB8_11:
	s_ashr_i32 s19, s18, 31
	v_cmp_lt_i64_e32 vcc, s[0:1], v[144:145]
	s_lshl_b64 s[0:1], s[18:19], 19
	s_add_u32 s20, s33, s0
	s_addc_u32 s21, s36, s1
	s_and_b64 s[0:1], vcc, exec
	s_cselect_b32 s5, s21, s29
	s_cselect_b32 s19, s20, s28
	s_ashr_i32 s11, s10, 31
	s_lshl_b64 s[0:1], s[10:11], 19
	s_add_u32 s22, s37, s0
	s_addc_u32 s23, s38, s1
	s_and_b64 s[0:1], vcc, exec
	s_cselect_b32 s11, s23, s27
	s_cselect_b32 s25, s22, s26
	s_add_u32 s34, s26, 0x100
	s_addc_u32 s35, s27, 0
	s_add_u32 s26, s28, 0x40080
	s_addc_u32 s27, s29, 0
	s_mov_b32 s65, -2
	ds_read_b128 v[148:151], v153
	ds_read_b128 v[156:159], v153 offset:1024
	ds_read_b128 v[160:163], v153 offset:2048
	ds_read_b128 v[164:167], v153 offset:3072
	ds_read_b128 v[168:171], v154
	ds_read_b128 v[172:175], v154 offset:1024
	ds_read_b128 v[176:179], v154 offset:2048
	ds_read_b128 v[180:183], v154 offset:3072
	s_add_u32 s28, s26, 0xfffc0080
	s_addc_u32 s29, s27, -1
	s_cmp_eq_u32 s65, 12
	s_cselect_b32 s31, s5, s29
	s_cselect_b32 s30, s19, s28
	s_cselect_b32 s29, s11, s35
	s_cselect_b32 s28, s25, s34
	v_lshl_add_u64 v[216:217], s[26:27], 0, v[142:143]
	s_add_i32 m0, s40, 0xc000
	ds_read_b128 v[184:187], v155
	ds_read_b128 v[188:191], v155 offset:1024
	ds_read_b128 v[192:195], v155 offset:2048
	ds_read_b128 v[196:199], v155 offset:3072
	ds_read_b128 v[200:203], v155 offset:4096
	ds_read_b128 v[204:207], v155 offset:5120
	ds_read_b128 v[208:211], v155 offset:6144
	ds_read_b128 v[212:215], v155 offset:7168
	global_load_lds_dwordx4 v[216:217], off
	v_lshl_add_u64 v[216:217], s[26:27], 0, v[140:141]
	s_add_i32 m0, s40, 0xe000
	s_nop 0
	global_load_lds_dwordx4 v[216:217], off
	s_waitcnt vmcnt(8)
	s_waitcnt lgkmcnt(0)
	s_barrier
	s_waitcnt lgkmcnt(0)
	v_mfma_f32_16x16x32_bf16 v[124:127], v[148:151], v[184:187], 0
	v_mfma_f32_16x16x32_bf16 v[120:123], v[160:163], v[184:187], 0
	v_mfma_f32_16x16x32_bf16 v[108:111], v[148:151], v[192:195], 0
	v_mfma_f32_16x16x32_bf16 v[104:107], v[160:163], v[192:195], 0
	v_mfma_f32_16x16x32_bf16 v[92:95], v[148:151], v[200:203], 0
	v_mfma_f32_16x16x32_bf16 v[88:91], v[160:163], v[200:203], 0
	v_mfma_f32_16x16x32_bf16 v[76:79], v[148:151], v[208:211], 0
	v_mfma_f32_16x16x32_bf16 v[72:75], v[160:163], v[208:211], 0
	v_mfma_f32_16x16x32_bf16 v[124:127], v[156:159], v[188:191], v[124:127]
	v_mfma_f32_16x16x32_bf16 v[120:123], v[164:167], v[188:191], v[120:123]
	v_mfma_f32_16x16x32_bf16 v[108:111], v[156:159], v[196:199], v[108:111]
	v_mfma_f32_16x16x32_bf16 v[104:107], v[164:167], v[196:199], v[104:107]
	v_mfma_f32_16x16x32_bf16 v[92:95], v[156:159], v[204:207], v[92:95]
	v_mfma_f32_16x16x32_bf16 v[88:91], v[164:167], v[204:207], v[88:91]
	v_mfma_f32_16x16x32_bf16 v[76:79], v[156:159], v[212:215], v[76:79]
	v_mfma_f32_16x16x32_bf16 v[72:75], v[164:167], v[212:215], v[72:75]
	v_mfma_f32_16x16x32_bf16 v[116:119], v[168:171], v[184:187], 0
	v_mfma_f32_16x16x32_bf16 v[112:115], v[176:179], v[184:187], 0
	v_mfma_f32_16x16x32_bf16 v[100:103], v[168:171], v[192:195], 0
	v_mfma_f32_16x16x32_bf16 v[96:99], v[176:179], v[192:195], 0
	v_mfma_f32_16x16x32_bf16 v[84:87], v[168:171], v[200:203], 0
	v_mfma_f32_16x16x32_bf16 v[80:83], v[176:179], v[200:203], 0
	v_mfma_f32_16x16x32_bf16 v[68:71], v[168:171], v[208:211], 0
	v_mfma_f32_16x16x32_bf16 v[64:67], v[176:179], v[208:211], 0
	v_mfma_f32_16x16x32_bf16 v[116:119], v[172:175], v[188:191], v[116:119]
	v_mfma_f32_16x16x32_bf16 v[112:115], v[180:183], v[188:191], v[112:115]
	v_mfma_f32_16x16x32_bf16 v[100:103], v[172:175], v[196:199], v[100:103]
	v_mfma_f32_16x16x32_bf16 v[96:99], v[180:183], v[196:199], v[96:99]
	v_mfma_f32_16x16x32_bf16 v[84:87], v[172:175], v[204:207], v[84:87]
	v_mfma_f32_16x16x32_bf16 v[80:83], v[180:183], v[204:207], v[80:83]
	v_mfma_f32_16x16x32_bf16 v[68:71], v[172:175], v[212:215], v[68:71]
	v_mfma_f32_16x16x32_bf16 v[64:67], v[180:183], v[212:215], v[64:67]
	s_barrier
	s_add_i32 s66, s52, s39
	v_lshl_add_u64 v[216:217], s[28:29], 0, v[130:131]
	s_mov_b32 m0, s66
	ds_read_b128 v[184:187], v155 offset:16384
	ds_read_b128 v[188:191], v155 offset:17408
	ds_read_b128 v[192:195], v155 offset:18432
	ds_read_b128 v[196:199], v155 offset:19456
	ds_read_b128 v[200:203], v155 offset:20480
	ds_read_b128 v[204:207], v155 offset:21504
	ds_read_b128 v[208:211], v155 offset:22528
	ds_read_b128 v[212:215], v155 offset:23552
	global_load_lds_dwordx4 v[216:217], off
	s_add_i32 m0, s66, 0x2000
	s_add_u32 s66, s28, 0x40000
	v_lshl_add_u64 v[218:219], s[28:29], 0, v[134:135]
	s_addc_u32 s67, s29, 0
	s_add_i32 s68, s53, s39
	global_load_lds_dwordx4 v[218:219], off
	v_lshl_add_u64 v[220:221], s[66:67], 0, v[130:131]
	s_mov_b32 m0, s68
	v_lshl_add_u64 v[222:223], s[30:31], 0, v[132:133]
	global_load_lds_dwordx4 v[220:221], off
	v_lshl_add_u64 v[220:221], s[66:67], 0, v[134:135]
	s_add_i32 m0, s68, 0x2000
	s_nop 0
	global_load_lds_dwordx4 v[220:221], off
	v_lshl_add_u64 v[220:221], s[30:31], 0, v[128:129]
	s_mov_b32 m0, s40
	s_nop 0
	global_load_lds_dwordx4 v[220:221], off
	s_mov_b32 m0, s41
	s_nop 0
	global_load_lds_dwordx4 v[222:223], off
	s_waitcnt vmcnt(8)
	s_waitcnt lgkmcnt(0)
	s_barrier
	s_waitcnt lgkmcnt(0)
	v_mfma_f32_16x16x32_bf16 v[60:63], v[148:151], v[184:187], 0
	v_mfma_f32_16x16x32_bf16 v[56:59], v[160:163], v[184:187], 0
	v_mfma_f32_16x16x32_bf16 v[44:47], v[148:151], v[192:195], 0
	v_mfma_f32_16x16x32_bf16 v[40:43], v[160:163], v[192:195], 0
	v_mfma_f32_16x16x32_bf16 v[28:31], v[148:151], v[200:203], 0
	v_mfma_f32_16x16x32_bf16 v[24:27], v[160:163], v[200:203], 0
	v_mfma_f32_16x16x32_bf16 v[12:15], v[148:151], v[208:211], 0
	v_mfma_f32_16x16x32_bf16 v[8:11], v[160:163], v[208:211], 0
	v_mfma_f32_16x16x32_bf16 v[60:63], v[156:159], v[188:191], v[60:63]
	v_mfma_f32_16x16x32_bf16 v[56:59], v[164:167], v[188:191], v[56:59]
	v_mfma_f32_16x16x32_bf16 v[44:47], v[156:159], v[196:199], v[44:47]
	v_mfma_f32_16x16x32_bf16 v[40:43], v[164:167], v[196:199], v[40:43]
	v_mfma_f32_16x16x32_bf16 v[28:31], v[156:159], v[204:207], v[28:31]
	v_mfma_f32_16x16x32_bf16 v[24:27], v[164:167], v[204:207], v[24:27]
	v_mfma_f32_16x16x32_bf16 v[12:15], v[156:159], v[212:215], v[12:15]
	v_mfma_f32_16x16x32_bf16 v[8:11], v[164:167], v[212:215], v[8:11]
	v_mfma_f32_16x16x32_bf16 v[52:55], v[168:171], v[184:187], 0
	v_mfma_f32_16x16x32_bf16 v[48:51], v[176:179], v[184:187], 0
	v_mfma_f32_16x16x32_bf16 v[36:39], v[168:171], v[192:195], 0
	v_mfma_f32_16x16x32_bf16 v[32:35], v[176:179], v[192:195], 0
	v_mfma_f32_16x16x32_bf16 v[20:23], v[168:171], v[200:203], 0
	v_mfma_f32_16x16x32_bf16 v[16:19], v[176:179], v[200:203], 0
	v_mfma_f32_16x16x32_bf16 v[4:7], v[168:171], v[208:211], 0
	v_mfma_f32_16x16x32_bf16 v[0:3], v[176:179], v[208:211], 0
	v_mfma_f32_16x16x32_bf16 v[52:55], v[172:175], v[188:191], v[52:55]
	v_mfma_f32_16x16x32_bf16 v[48:51], v[180:183], v[188:191], v[48:51]
	v_mfma_f32_16x16x32_bf16 v[36:39], v[172:175], v[196:199], v[36:39]
	v_mfma_f32_16x16x32_bf16 v[32:35], v[180:183], v[196:199], v[32:35]
	v_mfma_f32_16x16x32_bf16 v[20:23], v[172:175], v[204:207], v[20:23]
	v_mfma_f32_16x16x32_bf16 v[16:19], v[180:183], v[204:207], v[16:19]
	v_mfma_f32_16x16x32_bf16 v[4:7], v[172:175], v[212:215], v[4:7]
	v_mfma_f32_16x16x32_bf16 v[0:3], v[180:183], v[212:215], v[0:3]
	s_barrier
	s_add_i32 s66, 0, 0x18000
	s_add_i32 s67, 0, 0x1c000
	v_add_u32_e32 v164, s66, v152
	v_add_u32_e32 v180, s67, v152
	ds_read_b128 v[148:151], v164
	ds_read_b128 v[156:159], v164 offset:1024
	ds_read_b128 v[160:163], v164 offset:2048
	ds_read_b128 v[164:167], v164 offset:3072
	ds_read_b128 v[168:171], v180
	ds_read_b128 v[172:175], v180 offset:1024
	ds_read_b128 v[176:179], v180 offset:2048
	ds_read_b128 v[180:183], v180 offset:3072
	s_add_u32 s30, s30, 0x40000
	s_addc_u32 s31, s31, 0
	s_mov_b32 m0, s42
	v_lshl_add_u64 v[224:225], s[30:31], 0, v[128:129]
	ds_read_b128 v[184:187], v155 offset:32768
	ds_read_b128 v[188:191], v155 offset:33792
	ds_read_b128 v[192:195], v155 offset:34816
	ds_read_b128 v[196:199], v155 offset:35840
	ds_read_b128 v[200:203], v155 offset:36864
	ds_read_b128 v[204:207], v155 offset:37888
	ds_read_b128 v[208:211], v155 offset:38912
	ds_read_b128 v[212:215], v155 offset:39936
	global_load_lds_dwordx4 v[224:225], off
	v_lshl_add_u64 v[224:225], s[30:31], 0, v[132:133]
	s_mov_b32 m0, s43
	s_nop 0
	global_load_lds_dwordx4 v[224:225], off
	s_waitcnt vmcnt(8)
	s_waitcnt lgkmcnt(0)
	s_barrier
	s_waitcnt lgkmcnt(0)
	v_mfma_f32_16x16x32_bf16 v[124:127], v[148:151], v[184:187], v[124:127]
	v_mfma_f32_16x16x32_bf16 v[120:123], v[160:163], v[184:187], v[120:123]
	v_mfma_f32_16x16x32_bf16 v[108:111], v[148:151], v[192:195], v[108:111]
	v_mfma_f32_16x16x32_bf16 v[104:107], v[160:163], v[192:195], v[104:107]
	v_mfma_f32_16x16x32_bf16 v[92:95], v[148:151], v[200:203], v[92:95]
	v_mfma_f32_16x16x32_bf16 v[88:91], v[160:163], v[200:203], v[88:91]
	v_mfma_f32_16x16x32_bf16 v[76:79], v[148:151], v[208:211], v[76:79]
	v_mfma_f32_16x16x32_bf16 v[72:75], v[160:163], v[208:211], v[72:75]
	v_mfma_f32_16x16x32_bf16 v[124:127], v[156:159], v[188:191], v[124:127]
	v_mfma_f32_16x16x32_bf16 v[120:123], v[164:167], v[188:191], v[120:123]
	v_mfma_f32_16x16x32_bf16 v[108:111], v[156:159], v[196:199], v[108:111]
	v_mfma_f32_16x16x32_bf16 v[104:107], v[164:167], v[196:199], v[104:107]
	v_mfma_f32_16x16x32_bf16 v[92:95], v[156:159], v[204:207], v[92:95]
	v_mfma_f32_16x16x32_bf16 v[88:91], v[164:167], v[204:207], v[88:91]
	v_mfma_f32_16x16x32_bf16 v[76:79], v[156:159], v[212:215], v[76:79]
	v_mfma_f32_16x16x32_bf16 v[72:75], v[164:167], v[212:215], v[72:75]
	v_mfma_f32_16x16x32_bf16 v[116:119], v[168:171], v[184:187], v[116:119]
	v_mfma_f32_16x16x32_bf16 v[112:115], v[176:179], v[184:187], v[112:115]
	v_mfma_f32_16x16x32_bf16 v[100:103], v[168:171], v[192:195], v[100:103]
	v_mfma_f32_16x16x32_bf16 v[96:99], v[176:179], v[192:195], v[96:99]
	v_mfma_f32_16x16x32_bf16 v[84:87], v[168:171], v[200:203], v[84:87]
	v_mfma_f32_16x16x32_bf16 v[80:83], v[176:179], v[200:203], v[80:83]
	v_mfma_f32_16x16x32_bf16 v[68:71], v[168:171], v[208:211], v[68:71]
	v_mfma_f32_16x16x32_bf16 v[64:67], v[176:179], v[208:211], v[64:67]
	v_mfma_f32_16x16x32_bf16 v[116:119], v[172:175], v[188:191], v[116:119]
	v_mfma_f32_16x16x32_bf16 v[112:115], v[180:183], v[188:191], v[112:115]
	v_mfma_f32_16x16x32_bf16 v[100:103], v[172:175], v[196:199], v[100:103]
	v_mfma_f32_16x16x32_bf16 v[96:99], v[180:183], v[196:199], v[96:99]
	v_mfma_f32_16x16x32_bf16 v[84:87], v[172:175], v[204:207], v[84:87]
	v_mfma_f32_16x16x32_bf16 v[80:83], v[180:183], v[204:207], v[80:83]
	v_mfma_f32_16x16x32_bf16 v[68:71], v[172:175], v[212:215], v[68:71]
	v_mfma_f32_16x16x32_bf16 v[64:67], v[180:183], v[212:215], v[64:67]
	s_barrier
	s_add_i32 s30, s66, s39
	v_lshl_add_u64 v[216:217], v[216:217], 0, s[14:15]
	s_mov_b32 m0, s30
	ds_read_b128 v[184:187], v155 offset:49152
	ds_read_b128 v[188:191], v155 offset:50176
	ds_read_b128 v[192:195], v155 offset:51200
	ds_read_b128 v[196:199], v155 offset:52224
	ds_read_b128 v[200:203], v155 offset:53248
	ds_read_b128 v[204:207], v155 offset:54272
	ds_read_b128 v[208:211], v155 offset:55296
	ds_read_b128 v[212:215], v155 offset:56320
	global_load_lds_dwordx4 v[216:217], off
	s_add_i32 m0, s30, 0x2000
	s_add_u32 s28, s28, 0x40080
	v_lshl_add_u64 v[216:217], v[218:219], 0, s[14:15]
	s_addc_u32 s29, s29, 0
	s_add_i32 s30, s67, s39
	global_load_lds_dwordx4 v[216:217], off
	v_lshl_add_u64 v[216:217], s[28:29], 0, v[130:131]
	s_mov_b32 m0, s30
	s_nop 0
	global_load_lds_dwordx4 v[216:217], off
	v_lshl_add_u64 v[216:217], s[28:29], 0, v[134:135]
	s_add_i32 m0, s30, 0x2000
	s_nop 0
	global_load_lds_dwordx4 v[216:217], off
	v_lshl_add_u64 v[216:217], v[220:221], 0, s[14:15]
	s_mov_b32 m0, s45
	s_nop 0
	global_load_lds_dwordx4 v[216:217], off
	v_lshl_add_u64 v[216:217], v[222:223], 0, s[14:15]
	s_mov_b32 m0, s46
	s_nop 0
	global_load_lds_dwordx4 v[216:217], off
	s_waitcnt vmcnt(8)
	s_waitcnt lgkmcnt(0)
	s_barrier
	s_waitcnt lgkmcnt(0)
	v_mfma_f32_16x16x32_bf16 v[60:63], v[148:151], v[184:187], v[60:63]
	v_mfma_f32_16x16x32_bf16 v[56:59], v[160:163], v[184:187], v[56:59]
	v_mfma_f32_16x16x32_bf16 v[44:47], v[148:151], v[192:195], v[44:47]
	v_mfma_f32_16x16x32_bf16 v[40:43], v[160:163], v[192:195], v[40:43]
	v_mfma_f32_16x16x32_bf16 v[28:31], v[148:151], v[200:203], v[28:31]
	v_mfma_f32_16x16x32_bf16 v[24:27], v[160:163], v[200:203], v[24:27]
	v_mfma_f32_16x16x32_bf16 v[12:15], v[148:151], v[208:211], v[12:15]
	v_mfma_f32_16x16x32_bf16 v[8:11], v[160:163], v[208:211], v[8:11]
	v_mfma_f32_16x16x32_bf16 v[60:63], v[156:159], v[188:191], v[60:63]
	v_mfma_f32_16x16x32_bf16 v[56:59], v[164:167], v[188:191], v[56:59]
	v_mfma_f32_16x16x32_bf16 v[44:47], v[156:159], v[196:199], v[44:47]
	v_mfma_f32_16x16x32_bf16 v[40:43], v[164:167], v[196:199], v[40:43]
	v_mfma_f32_16x16x32_bf16 v[28:31], v[156:159], v[204:207], v[28:31]
	v_mfma_f32_16x16x32_bf16 v[24:27], v[164:167], v[204:207], v[24:27]
	v_mfma_f32_16x16x32_bf16 v[12:15], v[156:159], v[212:215], v[12:15]
	v_mfma_f32_16x16x32_bf16 v[8:11], v[164:167], v[212:215], v[8:11]
	v_mfma_f32_16x16x32_bf16 v[52:55], v[168:171], v[184:187], v[52:55]
	v_mfma_f32_16x16x32_bf16 v[48:51], v[176:179], v[184:187], v[48:51]
	v_mfma_f32_16x16x32_bf16 v[36:39], v[168:171], v[192:195], v[36:39]
	v_mfma_f32_16x16x32_bf16 v[32:35], v[176:179], v[192:195], v[32:35]
	v_mfma_f32_16x16x32_bf16 v[20:23], v[168:171], v[200:203], v[20:23]
	v_mfma_f32_16x16x32_bf16 v[16:19], v[176:179], v[200:203], v[16:19]
	v_mfma_f32_16x16x32_bf16 v[4:7], v[168:171], v[208:211], v[4:7]
	v_mfma_f32_16x16x32_bf16 v[0:3], v[176:179], v[208:211], v[0:3]
	v_mfma_f32_16x16x32_bf16 v[52:55], v[172:175], v[188:191], v[52:55]
	v_mfma_f32_16x16x32_bf16 v[48:51], v[180:183], v[188:191], v[48:51]
	v_mfma_f32_16x16x32_bf16 v[36:39], v[172:175], v[196:199], v[36:39]
	v_mfma_f32_16x16x32_bf16 v[32:35], v[180:183], v[196:199], v[32:35]
	v_mfma_f32_16x16x32_bf16 v[20:23], v[172:175], v[204:207], v[20:23]
	v_mfma_f32_16x16x32_bf16 v[16:19], v[180:183], v[204:207], v[16:19]
	v_mfma_f32_16x16x32_bf16 v[4:7], v[172:175], v[212:215], v[4:7]
	v_mfma_f32_16x16x32_bf16 v[0:3], v[180:183], v[212:215], v[0:3]
	s_add_i32 s65, s65, 2
	s_add_u32 s34, s34, 0x100
	s_addc_u32 s35, s35, 0
	s_add_u32 s26, s26, 0x100
	s_addc_u32 s27, s27, 0
	s_cmp_lt_u32 s65, 14
	s_barrier
.LBB8_12:
	ds_read_b128 v[148:151], v153
	ds_read_b128 v[156:159], v153 offset:1024
	ds_read_b128 v[160:163], v153 offset:2048
	ds_read_b128 v[164:167], v153 offset:3072
	ds_read_b128 v[168:171], v154
	ds_read_b128 v[172:175], v154 offset:1024
	ds_read_b128 v[176:179], v154 offset:2048
	ds_read_b128 v[180:183], v154 offset:3072
	s_add_u32 s28, s26, 0xfffc0080
	s_addc_u32 s29, s27, -1
	s_cmp_eq_u32 s65, 12
	s_cselect_b32 s31, s5, s29
	s_cselect_b32 s30, s19, s28
	s_cselect_b32 s29, s11, s35
	s_cselect_b32 s28, s25, s34
	v_lshl_add_u64 v[216:217], s[26:27], 0, v[142:143]
	s_add_i32 m0, s40, 0xc000
	ds_read_b128 v[184:187], v155
	ds_read_b128 v[188:191], v155 offset:1024
	ds_read_b128 v[192:195], v155 offset:2048
	ds_read_b128 v[196:199], v155 offset:3072
	ds_read_b128 v[200:203], v155 offset:4096
	ds_read_b128 v[204:207], v155 offset:5120
	ds_read_b128 v[208:211], v155 offset:6144
	ds_read_b128 v[212:215], v155 offset:7168
	global_load_lds_dwordx4 v[216:217], off
	v_lshl_add_u64 v[216:217], s[26:27], 0, v[140:141]
	s_add_i32 m0, s40, 0xe000
	s_nop 0
	global_load_lds_dwordx4 v[216:217], off
	s_waitcnt vmcnt(8)
	s_waitcnt lgkmcnt(0)
	s_barrier
	s_waitcnt lgkmcnt(0)
	v_mfma_f32_16x16x32_bf16 v[124:127], v[148:151], v[184:187], v[124:127]
	v_mfma_f32_16x16x32_bf16 v[120:123], v[160:163], v[184:187], v[120:123]
	v_mfma_f32_16x16x32_bf16 v[108:111], v[148:151], v[192:195], v[108:111]
	v_mfma_f32_16x16x32_bf16 v[104:107], v[160:163], v[192:195], v[104:107]
	v_mfma_f32_16x16x32_bf16 v[92:95], v[148:151], v[200:203], v[92:95]
	v_mfma_f32_16x16x32_bf16 v[88:91], v[160:163], v[200:203], v[88:91]
	v_mfma_f32_16x16x32_bf16 v[76:79], v[148:151], v[208:211], v[76:79]
	v_mfma_f32_16x16x32_bf16 v[72:75], v[160:163], v[208:211], v[72:75]
	v_mfma_f32_16x16x32_bf16 v[124:127], v[156:159], v[188:191], v[124:127]
	v_mfma_f32_16x16x32_bf16 v[120:123], v[164:167], v[188:191], v[120:123]
	v_mfma_f32_16x16x32_bf16 v[108:111], v[156:159], v[196:199], v[108:111]
	v_mfma_f32_16x16x32_bf16 v[104:107], v[164:167], v[196:199], v[104:107]
	v_mfma_f32_16x16x32_bf16 v[92:95], v[156:159], v[204:207], v[92:95]
	v_mfma_f32_16x16x32_bf16 v[88:91], v[164:167], v[204:207], v[88:91]
	v_mfma_f32_16x16x32_bf16 v[76:79], v[156:159], v[212:215], v[76:79]
	v_mfma_f32_16x16x32_bf16 v[72:75], v[164:167], v[212:215], v[72:75]
	v_mfma_f32_16x16x32_bf16 v[116:119], v[168:171], v[184:187], v[116:119]
	v_mfma_f32_16x16x32_bf16 v[112:115], v[176:179], v[184:187], v[112:115]
	v_mfma_f32_16x16x32_bf16 v[100:103], v[168:171], v[192:195], v[100:103]
	v_mfma_f32_16x16x32_bf16 v[96:99], v[176:179], v[192:195], v[96:99]
	v_mfma_f32_16x16x32_bf16 v[84:87], v[168:171], v[200:203], v[84:87]
	v_mfma_f32_16x16x32_bf16 v[80:83], v[176:179], v[200:203], v[80:83]
	v_mfma_f32_16x16x32_bf16 v[68:71], v[168:171], v[208:211], v[68:71]
	v_mfma_f32_16x16x32_bf16 v[64:67], v[176:179], v[208:211], v[64:67]
	v_mfma_f32_16x16x32_bf16 v[116:119], v[172:175], v[188:191], v[116:119]
	v_mfma_f32_16x16x32_bf16 v[112:115], v[180:183], v[188:191], v[112:115]
	v_mfma_f32_16x16x32_bf16 v[100:103], v[172:175], v[196:199], v[100:103]
	v_mfma_f32_16x16x32_bf16 v[96:99], v[180:183], v[196:199], v[96:99]
	v_mfma_f32_16x16x32_bf16 v[84:87], v[172:175], v[204:207], v[84:87]
	v_mfma_f32_16x16x32_bf16 v[80:83], v[180:183], v[204:207], v[80:83]
	v_mfma_f32_16x16x32_bf16 v[68:71], v[172:175], v[212:215], v[68:71]
	v_mfma_f32_16x16x32_bf16 v[64:67], v[180:183], v[212:215], v[64:67]
	s_barrier
	s_add_i32 s66, s52, s39
	v_lshl_add_u64 v[216:217], s[28:29], 0, v[130:131]
	s_mov_b32 m0, s66
	ds_read_b128 v[184:187], v155 offset:16384
	ds_read_b128 v[188:191], v155 offset:17408
	ds_read_b128 v[192:195], v155 offset:18432
	ds_read_b128 v[196:199], v155 offset:19456
	ds_read_b128 v[200:203], v155 offset:20480
	ds_read_b128 v[204:207], v155 offset:21504
	ds_read_b128 v[208:211], v155 offset:22528
	ds_read_b128 v[212:215], v155 offset:23552
	global_load_lds_dwordx4 v[216:217], off
	s_add_i32 m0, s66, 0x2000
	s_add_u32 s66, s28, 0x40000
	v_lshl_add_u64 v[218:219], s[28:29], 0, v[134:135]
	s_addc_u32 s67, s29, 0
	s_add_i32 s68, s53, s39
	global_load_lds_dwordx4 v[218:219], off
	v_lshl_add_u64 v[220:221], s[66:67], 0, v[130:131]
	s_mov_b32 m0, s68
	v_lshl_add_u64 v[222:223], s[30:31], 0, v[132:133]
	global_load_lds_dwordx4 v[220:221], off
	v_lshl_add_u64 v[220:221], s[66:67], 0, v[134:135]
	s_add_i32 m0, s68, 0x2000
	s_nop 0
	global_load_lds_dwordx4 v[220:221], off
	v_lshl_add_u64 v[220:221], s[30:31], 0, v[128:129]
	s_mov_b32 m0, s40
	s_nop 0
	global_load_lds_dwordx4 v[220:221], off
	s_mov_b32 m0, s41
	s_nop 0
	global_load_lds_dwordx4 v[222:223], off
	s_waitcnt vmcnt(8)
	s_waitcnt lgkmcnt(0)
	s_barrier
	s_waitcnt lgkmcnt(0)
	v_mfma_f32_16x16x32_bf16 v[60:63], v[148:151], v[184:187], v[60:63]
	v_mfma_f32_16x16x32_bf16 v[56:59], v[160:163], v[184:187], v[56:59]
	v_mfma_f32_16x16x32_bf16 v[44:47], v[148:151], v[192:195], v[44:47]
	v_mfma_f32_16x16x32_bf16 v[40:43], v[160:163], v[192:195], v[40:43]
	v_mfma_f32_16x16x32_bf16 v[28:31], v[148:151], v[200:203], v[28:31]
	v_mfma_f32_16x16x32_bf16 v[24:27], v[160:163], v[200:203], v[24:27]
	v_mfma_f32_16x16x32_bf16 v[12:15], v[148:151], v[208:211], v[12:15]
	v_mfma_f32_16x16x32_bf16 v[8:11], v[160:163], v[208:211], v[8:11]
	v_mfma_f32_16x16x32_bf16 v[60:63], v[156:159], v[188:191], v[60:63]
	v_mfma_f32_16x16x32_bf16 v[56:59], v[164:167], v[188:191], v[56:59]
	v_mfma_f32_16x16x32_bf16 v[44:47], v[156:159], v[196:199], v[44:47]
	v_mfma_f32_16x16x32_bf16 v[40:43], v[164:167], v[196:199], v[40:43]
	v_mfma_f32_16x16x32_bf16 v[28:31], v[156:159], v[204:207], v[28:31]
	v_mfma_f32_16x16x32_bf16 v[24:27], v[164:167], v[204:207], v[24:27]
	v_mfma_f32_16x16x32_bf16 v[12:15], v[156:159], v[212:215], v[12:15]
	v_mfma_f32_16x16x32_bf16 v[8:11], v[164:167], v[212:215], v[8:11]
	v_mfma_f32_16x16x32_bf16 v[52:55], v[168:171], v[184:187], v[52:55]
	v_mfma_f32_16x16x32_bf16 v[48:51], v[176:179], v[184:187], v[48:51]
	v_mfma_f32_16x16x32_bf16 v[36:39], v[168:171], v[192:195], v[36:39]
	v_mfma_f32_16x16x32_bf16 v[32:35], v[176:179], v[192:195], v[32:35]
	v_mfma_f32_16x16x32_bf16 v[20:23], v[168:171], v[200:203], v[20:23]
	v_mfma_f32_16x16x32_bf16 v[16:19], v[176:179], v[200:203], v[16:19]
	v_mfma_f32_16x16x32_bf16 v[4:7], v[168:171], v[208:211], v[4:7]
	v_mfma_f32_16x16x32_bf16 v[0:3], v[176:179], v[208:211], v[0:3]
	v_mfma_f32_16x16x32_bf16 v[52:55], v[172:175], v[188:191], v[52:55]
	v_mfma_f32_16x16x32_bf16 v[48:51], v[180:183], v[188:191], v[48:51]
	v_mfma_f32_16x16x32_bf16 v[36:39], v[172:175], v[196:199], v[36:39]
	v_mfma_f32_16x16x32_bf16 v[32:35], v[180:183], v[196:199], v[32:35]
	v_mfma_f32_16x16x32_bf16 v[20:23], v[172:175], v[204:207], v[20:23]
	v_mfma_f32_16x16x32_bf16 v[16:19], v[180:183], v[204:207], v[16:19]
	v_mfma_f32_16x16x32_bf16 v[4:7], v[172:175], v[212:215], v[4:7]
	v_mfma_f32_16x16x32_bf16 v[0:3], v[180:183], v[212:215], v[0:3]
	s_barrier
	s_add_i32 s66, 0, 0x18000
	s_add_i32 s67, 0, 0x1c000
	v_add_u32_e32 v164, s66, v152
	v_add_u32_e32 v180, s67, v152
	ds_read_b128 v[148:151], v164
	ds_read_b128 v[156:159], v164 offset:1024
	ds_read_b128 v[160:163], v164 offset:2048
	ds_read_b128 v[164:167], v164 offset:3072
	ds_read_b128 v[168:171], v180
	ds_read_b128 v[172:175], v180 offset:1024
	ds_read_b128 v[176:179], v180 offset:2048
	ds_read_b128 v[180:183], v180 offset:3072
	s_add_u32 s30, s30, 0x40000
	s_addc_u32 s31, s31, 0
	s_mov_b32 m0, s42
	v_lshl_add_u64 v[224:225], s[30:31], 0, v[128:129]
	ds_read_b128 v[184:187], v155 offset:32768
	ds_read_b128 v[188:191], v155 offset:33792
	ds_read_b128 v[192:195], v155 offset:34816
	ds_read_b128 v[196:199], v155 offset:35840
	ds_read_b128 v[200:203], v155 offset:36864
	ds_read_b128 v[204:207], v155 offset:37888
	ds_read_b128 v[208:211], v155 offset:38912
	ds_read_b128 v[212:215], v155 offset:39936
	global_load_lds_dwordx4 v[224:225], off
	v_lshl_add_u64 v[224:225], s[30:31], 0, v[132:133]
	s_mov_b32 m0, s43
	s_nop 0
	global_load_lds_dwordx4 v[224:225], off
	s_waitcnt vmcnt(8)
	s_waitcnt lgkmcnt(0)
	s_barrier
	s_waitcnt lgkmcnt(0)
	v_mfma_f32_16x16x32_bf16 v[124:127], v[148:151], v[184:187], v[124:127]
	v_mfma_f32_16x16x32_bf16 v[120:123], v[160:163], v[184:187], v[120:123]
	v_mfma_f32_16x16x32_bf16 v[108:111], v[148:151], v[192:195], v[108:111]
	v_mfma_f32_16x16x32_bf16 v[104:107], v[160:163], v[192:195], v[104:107]
	v_mfma_f32_16x16x32_bf16 v[92:95], v[148:151], v[200:203], v[92:95]
	v_mfma_f32_16x16x32_bf16 v[88:91], v[160:163], v[200:203], v[88:91]
	v_mfma_f32_16x16x32_bf16 v[76:79], v[148:151], v[208:211], v[76:79]
	v_mfma_f32_16x16x32_bf16 v[72:75], v[160:163], v[208:211], v[72:75]
	v_mfma_f32_16x16x32_bf16 v[124:127], v[156:159], v[188:191], v[124:127]
	v_mfma_f32_16x16x32_bf16 v[120:123], v[164:167], v[188:191], v[120:123]
	v_mfma_f32_16x16x32_bf16 v[108:111], v[156:159], v[196:199], v[108:111]
	v_mfma_f32_16x16x32_bf16 v[104:107], v[164:167], v[196:199], v[104:107]
	v_mfma_f32_16x16x32_bf16 v[92:95], v[156:159], v[204:207], v[92:95]
	v_mfma_f32_16x16x32_bf16 v[88:91], v[164:167], v[204:207], v[88:91]
	v_mfma_f32_16x16x32_bf16 v[76:79], v[156:159], v[212:215], v[76:79]
	v_mfma_f32_16x16x32_bf16 v[72:75], v[164:167], v[212:215], v[72:75]
	v_mfma_f32_16x16x32_bf16 v[116:119], v[168:171], v[184:187], v[116:119]
	v_mfma_f32_16x16x32_bf16 v[112:115], v[176:179], v[184:187], v[112:115]
	v_mfma_f32_16x16x32_bf16 v[100:103], v[168:171], v[192:195], v[100:103]
	v_mfma_f32_16x16x32_bf16 v[96:99], v[176:179], v[192:195], v[96:99]
	v_mfma_f32_16x16x32_bf16 v[84:87], v[168:171], v[200:203], v[84:87]
	v_mfma_f32_16x16x32_bf16 v[80:83], v[176:179], v[200:203], v[80:83]
	v_mfma_f32_16x16x32_bf16 v[68:71], v[168:171], v[208:211], v[68:71]
	v_mfma_f32_16x16x32_bf16 v[64:67], v[176:179], v[208:211], v[64:67]
	v_mfma_f32_16x16x32_bf16 v[116:119], v[172:175], v[188:191], v[116:119]
	v_mfma_f32_16x16x32_bf16 v[112:115], v[180:183], v[188:191], v[112:115]
	v_mfma_f32_16x16x32_bf16 v[100:103], v[172:175], v[196:199], v[100:103]
	v_mfma_f32_16x16x32_bf16 v[96:99], v[180:183], v[196:199], v[96:99]
	v_mfma_f32_16x16x32_bf16 v[84:87], v[172:175], v[204:207], v[84:87]
	v_mfma_f32_16x16x32_bf16 v[80:83], v[180:183], v[204:207], v[80:83]
	v_mfma_f32_16x16x32_bf16 v[68:71], v[172:175], v[212:215], v[68:71]
	v_mfma_f32_16x16x32_bf16 v[64:67], v[180:183], v[212:215], v[64:67]
	s_barrier
	s_add_i32 s30, s66, s39
	v_lshl_add_u64 v[216:217], v[216:217], 0, s[14:15]
	s_mov_b32 m0, s30
	ds_read_b128 v[184:187], v155 offset:49152
	ds_read_b128 v[188:191], v155 offset:50176
	ds_read_b128 v[192:195], v155 offset:51200
	ds_read_b128 v[196:199], v155 offset:52224
	ds_read_b128 v[200:203], v155 offset:53248
	ds_read_b128 v[204:207], v155 offset:54272
	ds_read_b128 v[208:211], v155 offset:55296
	ds_read_b128 v[212:215], v155 offset:56320
	global_load_lds_dwordx4 v[216:217], off
	s_add_i32 m0, s30, 0x2000
	s_add_u32 s28, s28, 0x40080
	v_lshl_add_u64 v[216:217], v[218:219], 0, s[14:15]
	s_addc_u32 s29, s29, 0
	s_add_i32 s30, s67, s39
	global_load_lds_dwordx4 v[216:217], off
	v_lshl_add_u64 v[216:217], s[28:29], 0, v[130:131]
	s_mov_b32 m0, s30
	s_nop 0
	global_load_lds_dwordx4 v[216:217], off
	v_lshl_add_u64 v[216:217], s[28:29], 0, v[134:135]
	s_add_i32 m0, s30, 0x2000
	s_nop 0
	global_load_lds_dwordx4 v[216:217], off
	v_lshl_add_u64 v[216:217], v[220:221], 0, s[14:15]
	s_mov_b32 m0, s45
	s_nop 0
	global_load_lds_dwordx4 v[216:217], off
	v_lshl_add_u64 v[216:217], v[222:223], 0, s[14:15]
	s_mov_b32 m0, s46
	s_nop 0
	global_load_lds_dwordx4 v[216:217], off
	s_waitcnt vmcnt(8)
	s_waitcnt lgkmcnt(0)
	s_barrier
	s_waitcnt lgkmcnt(0)
	v_mfma_f32_16x16x32_bf16 v[60:63], v[148:151], v[184:187], v[60:63]
	v_mfma_f32_16x16x32_bf16 v[56:59], v[160:163], v[184:187], v[56:59]
	v_mfma_f32_16x16x32_bf16 v[44:47], v[148:151], v[192:195], v[44:47]
	v_mfma_f32_16x16x32_bf16 v[40:43], v[160:163], v[192:195], v[40:43]
	v_mfma_f32_16x16x32_bf16 v[28:31], v[148:151], v[200:203], v[28:31]
	v_mfma_f32_16x16x32_bf16 v[24:27], v[160:163], v[200:203], v[24:27]
	v_mfma_f32_16x16x32_bf16 v[12:15], v[148:151], v[208:211], v[12:15]
	v_mfma_f32_16x16x32_bf16 v[8:11], v[160:163], v[208:211], v[8:11]
	v_mfma_f32_16x16x32_bf16 v[60:63], v[156:159], v[188:191], v[60:63]
	v_mfma_f32_16x16x32_bf16 v[56:59], v[164:167], v[188:191], v[56:59]
	v_mfma_f32_16x16x32_bf16 v[44:47], v[156:159], v[196:199], v[44:47]
	v_mfma_f32_16x16x32_bf16 v[40:43], v[164:167], v[196:199], v[40:43]
	v_mfma_f32_16x16x32_bf16 v[28:31], v[156:159], v[204:207], v[28:31]
	v_mfma_f32_16x16x32_bf16 v[24:27], v[164:167], v[204:207], v[24:27]
	v_mfma_f32_16x16x32_bf16 v[12:15], v[156:159], v[212:215], v[12:15]
	v_mfma_f32_16x16x32_bf16 v[8:11], v[164:167], v[212:215], v[8:11]
	v_mfma_f32_16x16x32_bf16 v[52:55], v[168:171], v[184:187], v[52:55]
	v_mfma_f32_16x16x32_bf16 v[48:51], v[176:179], v[184:187], v[48:51]
	v_mfma_f32_16x16x32_bf16 v[36:39], v[168:171], v[192:195], v[36:39]
	v_mfma_f32_16x16x32_bf16 v[32:35], v[176:179], v[192:195], v[32:35]
	v_mfma_f32_16x16x32_bf16 v[20:23], v[168:171], v[200:203], v[20:23]
	v_mfma_f32_16x16x32_bf16 v[16:19], v[176:179], v[200:203], v[16:19]
	v_mfma_f32_16x16x32_bf16 v[4:7], v[168:171], v[208:211], v[4:7]
	v_mfma_f32_16x16x32_bf16 v[0:3], v[176:179], v[208:211], v[0:3]
	v_mfma_f32_16x16x32_bf16 v[52:55], v[172:175], v[188:191], v[52:55]
	v_mfma_f32_16x16x32_bf16 v[48:51], v[180:183], v[188:191], v[48:51]
	v_mfma_f32_16x16x32_bf16 v[36:39], v[172:175], v[196:199], v[36:39]
	v_mfma_f32_16x16x32_bf16 v[32:35], v[180:183], v[196:199], v[32:35]
	v_mfma_f32_16x16x32_bf16 v[20:23], v[172:175], v[204:207], v[20:23]
	v_mfma_f32_16x16x32_bf16 v[16:19], v[180:183], v[204:207], v[16:19]
	v_mfma_f32_16x16x32_bf16 v[4:7], v[172:175], v[212:215], v[4:7]
	v_mfma_f32_16x16x32_bf16 v[0:3], v[180:183], v[212:215], v[0:3]
	s_add_i32 s65, s65, 2
	s_add_u32 s34, s34, 0x100
	s_addc_u32 s35, s35, 0
	s_add_u32 s26, s26, 0x100
	s_addc_u32 s27, s27, 0
	s_cmp_lt_u32 s65, 14
	s_barrier
	s_cbranch_scc1 .LBB8_12
	s_andn2_b64 vcc, exec, s[16:17]
	s_cbranch_vccnz .LBB8_15
	s_barrier

.LBB10_19:
	s_ashr_i32 s17, s16, 31
	v_cmp_lt_i64_e32 vcc, s[0:1], v[142:143]
	s_lshl_b64 s[0:1], s[16:17], 19
	s_add_u32 s18, s33, s0
	s_addc_u32 s19, s34, s1
	s_and_b64 s[0:1], vcc, exec
	s_cselect_b32 s17, s19, s27
	s_cselect_b32 s53, s18, s26
	s_ashr_i32 s15, s14, 31
	s_lshl_b64 s[0:1], s[14:15], 19
	s_add_u32 s20, s4, s0
	s_addc_u32 s21, s5, s1
	s_and_b64 s[0:1], vcc, exec
	s_cselect_b32 s15, s21, s25
	s_cselect_b32 s54, s20, s24
	s_add_u32 s55, s24, 0x100
	s_addc_u32 s56, s25, 0
	s_add_u32 s24, s26, 0x40080
	s_addc_u32 s25, s27, 0
	s_mov_b32 s57, -2
	ds_read_b128 v[152:155], v149
	ds_read_b128 v[156:159], v149 offset:1024
	ds_read_b128 v[160:163], v149 offset:2048
	ds_read_b128 v[164:167], v149 offset:3072
	ds_read_b128 v[168:171], v150
	ds_read_b128 v[172:175], v150 offset:1024
	ds_read_b128 v[176:179], v150 offset:2048
	ds_read_b128 v[180:183], v150 offset:3072
	s_add_u32 s26, s24, 0xfffc0080
	s_addc_u32 s27, s25, -1
	s_cmp_eq_u32 s57, 12
	s_cselect_b32 s29, s17, s27
	s_cselect_b32 s28, s53, s26
	s_cselect_b32 s27, s15, s56
	s_cselect_b32 s26, s54, s55
	v_lshl_add_u64 v[146:147], s[24:25], 0, v[140:141]
	s_add_i32 m0, s35, 0xc000
	ds_read_b128 v[184:187], v151
	ds_read_b128 v[188:191], v151 offset:1024
	ds_read_b128 v[192:195], v151 offset:2048
	ds_read_b128 v[196:199], v151 offset:3072
	ds_read_b128 v[200:203], v151 offset:4096
	ds_read_b128 v[204:207], v151 offset:5120
	ds_read_b128 v[208:211], v151 offset:6144
	ds_read_b128 v[212:215], v151 offset:7168
	global_load_lds_dwordx4 v[146:147], off
	v_lshl_add_u64 v[146:147], s[24:25], 0, v[138:139]
	s_add_i32 m0, s35, 0xe000
	s_nop 0
	global_load_lds_dwordx4 v[146:147], off
	s_waitcnt vmcnt(8)
	s_waitcnt lgkmcnt(0)
	s_barrier
	s_waitcnt lgkmcnt(0)
	v_mfma_f32_16x16x32_bf16 v[124:127], v[152:155], v[184:187], 0
	v_mfma_f32_16x16x32_bf16 v[120:123], v[160:163], v[184:187], 0
	v_mfma_f32_16x16x32_bf16 v[116:119], v[152:155], v[192:195], 0
	v_mfma_f32_16x16x32_bf16 v[108:111], v[160:163], v[192:195], 0
	v_mfma_f32_16x16x32_bf16 v[100:103], v[152:155], v[200:203], 0
	v_mfma_f32_16x16x32_bf16 v[92:95], v[160:163], v[200:203], 0
	v_mfma_f32_16x16x32_bf16 v[84:87], v[152:155], v[208:211], 0
	v_mfma_f32_16x16x32_bf16 v[76:79], v[160:163], v[208:211], 0
	v_mfma_f32_16x16x32_bf16 v[124:127], v[156:159], v[188:191], v[124:127]
	v_mfma_f32_16x16x32_bf16 v[120:123], v[164:167], v[188:191], v[120:123]
	v_mfma_f32_16x16x32_bf16 v[116:119], v[156:159], v[196:199], v[116:119]
	v_mfma_f32_16x16x32_bf16 v[108:111], v[164:167], v[196:199], v[108:111]
	v_mfma_f32_16x16x32_bf16 v[100:103], v[156:159], v[204:207], v[100:103]
	v_mfma_f32_16x16x32_bf16 v[92:95], v[164:167], v[204:207], v[92:95]
	v_mfma_f32_16x16x32_bf16 v[84:87], v[156:159], v[212:215], v[84:87]
	v_mfma_f32_16x16x32_bf16 v[76:79], v[164:167], v[212:215], v[76:79]
	v_mfma_f32_16x16x32_bf16 v[112:115], v[168:171], v[184:187], 0
	v_mfma_f32_16x16x32_bf16 v[104:107], v[176:179], v[184:187], 0
	v_mfma_f32_16x16x32_bf16 v[96:99], v[168:171], v[192:195], 0
	v_mfma_f32_16x16x32_bf16 v[88:91], v[176:179], v[192:195], 0
	v_mfma_f32_16x16x32_bf16 v[80:83], v[168:171], v[200:203], 0
	v_mfma_f32_16x16x32_bf16 v[72:75], v[176:179], v[200:203], 0
	v_mfma_f32_16x16x32_bf16 v[68:71], v[168:171], v[208:211], 0
	v_mfma_f32_16x16x32_bf16 v[64:67], v[176:179], v[208:211], 0
	v_mfma_f32_16x16x32_bf16 v[112:115], v[172:175], v[188:191], v[112:115]
	v_mfma_f32_16x16x32_bf16 v[104:107], v[180:183], v[188:191], v[104:107]
	v_mfma_f32_16x16x32_bf16 v[96:99], v[172:175], v[196:199], v[96:99]
	v_mfma_f32_16x16x32_bf16 v[88:91], v[180:183], v[196:199], v[88:91]
	v_mfma_f32_16x16x32_bf16 v[80:83], v[172:175], v[204:207], v[80:83]
	v_mfma_f32_16x16x32_bf16 v[72:75], v[180:183], v[204:207], v[72:75]
	v_mfma_f32_16x16x32_bf16 v[68:71], v[172:175], v[212:215], v[68:71]
	v_mfma_f32_16x16x32_bf16 v[64:67], v[180:183], v[212:215], v[64:67]
	s_barrier
	s_add_i32 s58, s46, s31
	v_lshl_add_u64 v[146:147], s[26:27], 0, v[130:131]
	s_mov_b32 m0, s58
	ds_read_b128 v[184:187], v151 offset:16384
	ds_read_b128 v[188:191], v151 offset:17408
	ds_read_b128 v[192:195], v151 offset:18432
	ds_read_b128 v[196:199], v151 offset:19456
	ds_read_b128 v[200:203], v151 offset:20480
	ds_read_b128 v[204:207], v151 offset:21504
	ds_read_b128 v[208:211], v151 offset:22528
	ds_read_b128 v[212:215], v151 offset:23552
	global_load_lds_dwordx4 v[146:147], off
	s_add_i32 m0, s58, 0x2000
	s_add_u32 s58, s26, 0x40000
	v_lshl_add_u64 v[216:217], s[26:27], 0, v[134:135]
	s_addc_u32 s59, s27, 0
	s_add_i32 s60, s47, s31
	global_load_lds_dwordx4 v[216:217], off
	v_lshl_add_u64 v[218:219], s[58:59], 0, v[130:131]
	s_mov_b32 m0, s60
	v_lshl_add_u64 v[220:221], s[28:29], 0, v[132:133]
	global_load_lds_dwordx4 v[218:219], off
	v_lshl_add_u64 v[218:219], s[58:59], 0, v[134:135]
	s_add_i32 m0, s60, 0x2000
	s_nop 0
	global_load_lds_dwordx4 v[218:219], off
	v_lshl_add_u64 v[218:219], s[28:29], 0, v[128:129]
	s_mov_b32 m0, s35
	s_nop 0
	global_load_lds_dwordx4 v[218:219], off
	s_mov_b32 m0, s36
	s_nop 0
	global_load_lds_dwordx4 v[220:221], off
	s_waitcnt vmcnt(8)
	s_waitcnt lgkmcnt(0)
	s_barrier
	s_waitcnt lgkmcnt(0)
	v_mfma_f32_16x16x32_bf16 v[60:63], v[152:155], v[184:187], 0
	v_mfma_f32_16x16x32_bf16 v[56:59], v[160:163], v[184:187], 0
	v_mfma_f32_16x16x32_bf16 v[52:55], v[152:155], v[192:195], 0
	v_mfma_f32_16x16x32_bf16 v[44:47], v[160:163], v[192:195], 0
	v_mfma_f32_16x16x32_bf16 v[36:39], v[152:155], v[200:203], 0
	v_mfma_f32_16x16x32_bf16 v[28:31], v[160:163], v[200:203], 0
	v_mfma_f32_16x16x32_bf16 v[20:23], v[152:155], v[208:211], 0
	v_mfma_f32_16x16x32_bf16 v[12:15], v[160:163], v[208:211], 0
	v_mfma_f32_16x16x32_bf16 v[60:63], v[156:159], v[188:191], v[60:63]
	v_mfma_f32_16x16x32_bf16 v[56:59], v[164:167], v[188:191], v[56:59]
	v_mfma_f32_16x16x32_bf16 v[52:55], v[156:159], v[196:199], v[52:55]
	v_mfma_f32_16x16x32_bf16 v[44:47], v[164:167], v[196:199], v[44:47]
	v_mfma_f32_16x16x32_bf16 v[36:39], v[156:159], v[204:207], v[36:39]
	v_mfma_f32_16x16x32_bf16 v[28:31], v[164:167], v[204:207], v[28:31]
	v_mfma_f32_16x16x32_bf16 v[20:23], v[156:159], v[212:215], v[20:23]
	v_mfma_f32_16x16x32_bf16 v[12:15], v[164:167], v[212:215], v[12:15]
	v_mfma_f32_16x16x32_bf16 v[48:51], v[168:171], v[184:187], 0
	v_mfma_f32_16x16x32_bf16 v[40:43], v[176:179], v[184:187], 0
	v_mfma_f32_16x16x32_bf16 v[32:35], v[168:171], v[192:195], 0
	v_mfma_f32_16x16x32_bf16 v[24:27], v[176:179], v[192:195], 0
	v_mfma_f32_16x16x32_bf16 v[16:19], v[168:171], v[200:203], 0
	v_mfma_f32_16x16x32_bf16 v[8:11], v[176:179], v[200:203], 0
	v_mfma_f32_16x16x32_bf16 v[4:7], v[168:171], v[208:211], 0
	v_mfma_f32_16x16x32_bf16 v[0:3], v[176:179], v[208:211], 0
	v_mfma_f32_16x16x32_bf16 v[48:51], v[172:175], v[188:191], v[48:51]
	v_mfma_f32_16x16x32_bf16 v[40:43], v[180:183], v[188:191], v[40:43]
	v_mfma_f32_16x16x32_bf16 v[32:35], v[172:175], v[196:199], v[32:35]
	v_mfma_f32_16x16x32_bf16 v[24:27], v[180:183], v[196:199], v[24:27]
	v_mfma_f32_16x16x32_bf16 v[16:19], v[172:175], v[204:207], v[16:19]
	v_mfma_f32_16x16x32_bf16 v[8:11], v[180:183], v[204:207], v[8:11]
	v_mfma_f32_16x16x32_bf16 v[4:7], v[172:175], v[212:215], v[4:7]
	v_mfma_f32_16x16x32_bf16 v[0:3], v[180:183], v[212:215], v[0:3]
	s_barrier
	s_add_i32 s58, 0, 0x18000
	s_add_i32 s59, 0, 0x1c000
	v_add_u32_e32 v164, s58, v148
	v_add_u32_e32 v180, s59, v148
	ds_read_b128 v[152:155], v164
	ds_read_b128 v[156:159], v164 offset:1024
	ds_read_b128 v[160:163], v164 offset:2048
	ds_read_b128 v[164:167], v164 offset:3072
	ds_read_b128 v[168:171], v180
	ds_read_b128 v[172:175], v180 offset:1024
	ds_read_b128 v[176:179], v180 offset:2048
	ds_read_b128 v[180:183], v180 offset:3072
	s_add_u32 s28, s28, 0x40000
	s_addc_u32 s29, s29, 0
	s_mov_b32 m0, s37
	v_lshl_add_u64 v[222:223], s[28:29], 0, v[128:129]
	ds_read_b128 v[184:187], v151 offset:32768
	ds_read_b128 v[188:191], v151 offset:33792
	ds_read_b128 v[192:195], v151 offset:34816
	ds_read_b128 v[196:199], v151 offset:35840
	ds_read_b128 v[200:203], v151 offset:36864
	ds_read_b128 v[204:207], v151 offset:37888
	ds_read_b128 v[208:211], v151 offset:38912
	ds_read_b128 v[212:215], v151 offset:39936
	global_load_lds_dwordx4 v[222:223], off
	v_lshl_add_u64 v[222:223], s[28:29], 0, v[132:133]
	s_mov_b32 m0, s38
	s_nop 0
	global_load_lds_dwordx4 v[222:223], off
	s_waitcnt vmcnt(8)
	s_waitcnt lgkmcnt(0)
	s_barrier
	s_waitcnt lgkmcnt(0)
	v_mfma_f32_16x16x32_bf16 v[124:127], v[152:155], v[184:187], v[124:127]
	v_mfma_f32_16x16x32_bf16 v[120:123], v[160:163], v[184:187], v[120:123]
	v_mfma_f32_16x16x32_bf16 v[116:119], v[152:155], v[192:195], v[116:119]
	v_mfma_f32_16x16x32_bf16 v[108:111], v[160:163], v[192:195], v[108:111]
	v_mfma_f32_16x16x32_bf16 v[100:103], v[152:155], v[200:203], v[100:103]
	v_mfma_f32_16x16x32_bf16 v[92:95], v[160:163], v[200:203], v[92:95]
	v_mfma_f32_16x16x32_bf16 v[84:87], v[152:155], v[208:211], v[84:87]
	v_mfma_f32_16x16x32_bf16 v[76:79], v[160:163], v[208:211], v[76:79]
	v_mfma_f32_16x16x32_bf16 v[124:127], v[156:159], v[188:191], v[124:127]
	v_mfma_f32_16x16x32_bf16 v[120:123], v[164:167], v[188:191], v[120:123]
	v_mfma_f32_16x16x32_bf16 v[116:119], v[156:159], v[196:199], v[116:119]
	v_mfma_f32_16x16x32_bf16 v[108:111], v[164:167], v[196:199], v[108:111]
	v_mfma_f32_16x16x32_bf16 v[100:103], v[156:159], v[204:207], v[100:103]
	v_mfma_f32_16x16x32_bf16 v[92:95], v[164:167], v[204:207], v[92:95]
	v_mfma_f32_16x16x32_bf16 v[84:87], v[156:159], v[212:215], v[84:87]
	v_mfma_f32_16x16x32_bf16 v[76:79], v[164:167], v[212:215], v[76:79]
	v_mfma_f32_16x16x32_bf16 v[112:115], v[168:171], v[184:187], v[112:115]
	v_mfma_f32_16x16x32_bf16 v[104:107], v[176:179], v[184:187], v[104:107]
	v_mfma_f32_16x16x32_bf16 v[96:99], v[168:171], v[192:195], v[96:99]
	v_mfma_f32_16x16x32_bf16 v[88:91], v[176:179], v[192:195], v[88:91]
	v_mfma_f32_16x16x32_bf16 v[80:83], v[168:171], v[200:203], v[80:83]
	v_mfma_f32_16x16x32_bf16 v[72:75], v[176:179], v[200:203], v[72:75]
	v_mfma_f32_16x16x32_bf16 v[68:71], v[168:171], v[208:211], v[68:71]
	v_mfma_f32_16x16x32_bf16 v[64:67], v[176:179], v[208:211], v[64:67]
	v_mfma_f32_16x16x32_bf16 v[112:115], v[172:175], v[188:191], v[112:115]
	v_mfma_f32_16x16x32_bf16 v[104:107], v[180:183], v[188:191], v[104:107]
	v_mfma_f32_16x16x32_bf16 v[96:99], v[172:175], v[196:199], v[96:99]
	v_mfma_f32_16x16x32_bf16 v[88:91], v[180:183], v[196:199], v[88:91]
	v_mfma_f32_16x16x32_bf16 v[80:83], v[172:175], v[204:207], v[80:83]
	v_mfma_f32_16x16x32_bf16 v[72:75], v[180:183], v[204:207], v[72:75]
	v_mfma_f32_16x16x32_bf16 v[68:71], v[172:175], v[212:215], v[68:71]
	v_mfma_f32_16x16x32_bf16 v[64:67], v[180:183], v[212:215], v[64:67]
	s_barrier
	s_add_i32 s28, s58, s31
	v_lshl_add_u64 v[146:147], v[146:147], 0, s[10:11]
	s_mov_b32 m0, s28
	ds_read_b128 v[184:187], v151 offset:49152
	ds_read_b128 v[188:191], v151 offset:50176
	ds_read_b128 v[192:195], v151 offset:51200
	ds_read_b128 v[196:199], v151 offset:52224
	ds_read_b128 v[200:203], v151 offset:53248
	ds_read_b128 v[204:207], v151 offset:54272
	ds_read_b128 v[208:211], v151 offset:55296
	ds_read_b128 v[212:215], v151 offset:56320
	global_load_lds_dwordx4 v[146:147], off
	s_add_i32 m0, s28, 0x2000
	s_add_u32 s26, s26, 0x40080
	v_lshl_add_u64 v[146:147], v[216:217], 0, s[10:11]
	s_addc_u32 s27, s27, 0
	s_add_i32 s28, s59, s31
	global_load_lds_dwordx4 v[146:147], off
	v_lshl_add_u64 v[146:147], s[26:27], 0, v[130:131]
	s_mov_b32 m0, s28
	s_nop 0
	global_load_lds_dwordx4 v[146:147], off
	v_lshl_add_u64 v[146:147], s[26:27], 0, v[134:135]
	s_add_i32 m0, s28, 0x2000
	s_nop 0
	global_load_lds_dwordx4 v[146:147], off
	v_lshl_add_u64 v[146:147], v[218:219], 0, s[10:11]
	s_mov_b32 m0, s41
	s_nop 0
	global_load_lds_dwordx4 v[146:147], off
	v_lshl_add_u64 v[146:147], v[220:221], 0, s[10:11]
	s_mov_b32 m0, s42
	s_nop 0
	global_load_lds_dwordx4 v[146:147], off
	s_waitcnt vmcnt(8)
	s_waitcnt lgkmcnt(0)
	s_barrier
	s_waitcnt lgkmcnt(0)
	v_mfma_f32_16x16x32_bf16 v[60:63], v[152:155], v[184:187], v[60:63]
	v_mfma_f32_16x16x32_bf16 v[56:59], v[160:163], v[184:187], v[56:59]
	v_mfma_f32_16x16x32_bf16 v[52:55], v[152:155], v[192:195], v[52:55]
	v_mfma_f32_16x16x32_bf16 v[44:47], v[160:163], v[192:195], v[44:47]
	v_mfma_f32_16x16x32_bf16 v[36:39], v[152:155], v[200:203], v[36:39]
	v_mfma_f32_16x16x32_bf16 v[28:31], v[160:163], v[200:203], v[28:31]
	v_mfma_f32_16x16x32_bf16 v[20:23], v[152:155], v[208:211], v[20:23]
	v_mfma_f32_16x16x32_bf16 v[12:15], v[160:163], v[208:211], v[12:15]
	v_mfma_f32_16x16x32_bf16 v[60:63], v[156:159], v[188:191], v[60:63]
	v_mfma_f32_16x16x32_bf16 v[56:59], v[164:167], v[188:191], v[56:59]
	v_mfma_f32_16x16x32_bf16 v[52:55], v[156:159], v[196:199], v[52:55]
	v_mfma_f32_16x16x32_bf16 v[44:47], v[164:167], v[196:199], v[44:47]
	v_mfma_f32_16x16x32_bf16 v[36:39], v[156:159], v[204:207], v[36:39]
	v_mfma_f32_16x16x32_bf16 v[28:31], v[164:167], v[204:207], v[28:31]
	v_mfma_f32_16x16x32_bf16 v[20:23], v[156:159], v[212:215], v[20:23]
	v_mfma_f32_16x16x32_bf16 v[12:15], v[164:167], v[212:215], v[12:15]
	v_mfma_f32_16x16x32_bf16 v[48:51], v[168:171], v[184:187], v[48:51]
	v_mfma_f32_16x16x32_bf16 v[40:43], v[176:179], v[184:187], v[40:43]
	v_mfma_f32_16x16x32_bf16 v[32:35], v[168:171], v[192:195], v[32:35]
	v_mfma_f32_16x16x32_bf16 v[24:27], v[176:179], v[192:195], v[24:27]
	v_mfma_f32_16x16x32_bf16 v[16:19], v[168:171], v[200:203], v[16:19]
	v_mfma_f32_16x16x32_bf16 v[8:11], v[176:179], v[200:203], v[8:11]
	v_mfma_f32_16x16x32_bf16 v[4:7], v[168:171], v[208:211], v[4:7]
	v_mfma_f32_16x16x32_bf16 v[0:3], v[176:179], v[208:211], v[0:3]
	v_mfma_f32_16x16x32_bf16 v[48:51], v[172:175], v[188:191], v[48:51]
	v_mfma_f32_16x16x32_bf16 v[40:43], v[180:183], v[188:191], v[40:43]
	v_mfma_f32_16x16x32_bf16 v[32:35], v[172:175], v[196:199], v[32:35]
	v_mfma_f32_16x16x32_bf16 v[24:27], v[180:183], v[196:199], v[24:27]
	v_mfma_f32_16x16x32_bf16 v[16:19], v[172:175], v[204:207], v[16:19]
	v_mfma_f32_16x16x32_bf16 v[8:11], v[180:183], v[204:207], v[8:11]
	v_mfma_f32_16x16x32_bf16 v[4:7], v[172:175], v[212:215], v[4:7]
	v_mfma_f32_16x16x32_bf16 v[0:3], v[180:183], v[212:215], v[0:3]
	s_add_i32 s57, s57, 2
	s_add_u32 s55, s55, 0x100
	s_addc_u32 s56, s56, 0
	s_add_u32 s24, s24, 0x100
	s_addc_u32 s25, s25, 0
	s_cmp_lt_u32 s57, 14
	s_barrier
.LBB10_20:
	ds_read_b128 v[152:155], v149
	ds_read_b128 v[156:159], v149 offset:1024
	ds_read_b128 v[160:163], v149 offset:2048
	ds_read_b128 v[164:167], v149 offset:3072
	ds_read_b128 v[168:171], v150
	ds_read_b128 v[172:175], v150 offset:1024
	ds_read_b128 v[176:179], v150 offset:2048
	ds_read_b128 v[180:183], v150 offset:3072
	s_add_u32 s26, s24, 0xfffc0080
	s_addc_u32 s27, s25, -1
	s_cmp_eq_u32 s57, 12
	s_cselect_b32 s29, s17, s27
	s_cselect_b32 s28, s53, s26
	s_cselect_b32 s27, s15, s56
	s_cselect_b32 s26, s54, s55
	v_lshl_add_u64 v[146:147], s[24:25], 0, v[140:141]
	s_add_i32 m0, s35, 0xc000
	ds_read_b128 v[184:187], v151
	ds_read_b128 v[188:191], v151 offset:1024
	ds_read_b128 v[192:195], v151 offset:2048
	ds_read_b128 v[196:199], v151 offset:3072
	ds_read_b128 v[200:203], v151 offset:4096
	ds_read_b128 v[204:207], v151 offset:5120
	ds_read_b128 v[208:211], v151 offset:6144
	ds_read_b128 v[212:215], v151 offset:7168
	global_load_lds_dwordx4 v[146:147], off
	v_lshl_add_u64 v[146:147], s[24:25], 0, v[138:139]
	s_add_i32 m0, s35, 0xe000
	s_nop 0
	global_load_lds_dwordx4 v[146:147], off
	s_waitcnt vmcnt(8)
	s_waitcnt lgkmcnt(0)
	s_barrier
	s_waitcnt lgkmcnt(0)
	v_mfma_f32_16x16x32_bf16 v[124:127], v[152:155], v[184:187], v[124:127]
	v_mfma_f32_16x16x32_bf16 v[120:123], v[160:163], v[184:187], v[120:123]
	v_mfma_f32_16x16x32_bf16 v[116:119], v[152:155], v[192:195], v[116:119]
	v_mfma_f32_16x16x32_bf16 v[108:111], v[160:163], v[192:195], v[108:111]
	v_mfma_f32_16x16x32_bf16 v[100:103], v[152:155], v[200:203], v[100:103]
	v_mfma_f32_16x16x32_bf16 v[92:95], v[160:163], v[200:203], v[92:95]
	v_mfma_f32_16x16x32_bf16 v[84:87], v[152:155], v[208:211], v[84:87]
	v_mfma_f32_16x16x32_bf16 v[76:79], v[160:163], v[208:211], v[76:79]
	v_mfma_f32_16x16x32_bf16 v[124:127], v[156:159], v[188:191], v[124:127]
	v_mfma_f32_16x16x32_bf16 v[120:123], v[164:167], v[188:191], v[120:123]
	v_mfma_f32_16x16x32_bf16 v[116:119], v[156:159], v[196:199], v[116:119]
	v_mfma_f32_16x16x32_bf16 v[108:111], v[164:167], v[196:199], v[108:111]
	v_mfma_f32_16x16x32_bf16 v[100:103], v[156:159], v[204:207], v[100:103]
	v_mfma_f32_16x16x32_bf16 v[92:95], v[164:167], v[204:207], v[92:95]
	v_mfma_f32_16x16x32_bf16 v[84:87], v[156:159], v[212:215], v[84:87]
	v_mfma_f32_16x16x32_bf16 v[76:79], v[164:167], v[212:215], v[76:79]
	v_mfma_f32_16x16x32_bf16 v[112:115], v[168:171], v[184:187], v[112:115]
	v_mfma_f32_16x16x32_bf16 v[104:107], v[176:179], v[184:187], v[104:107]
	v_mfma_f32_16x16x32_bf16 v[96:99], v[168:171], v[192:195], v[96:99]
	v_mfma_f32_16x16x32_bf16 v[88:91], v[176:179], v[192:195], v[88:91]
	v_mfma_f32_16x16x32_bf16 v[80:83], v[168:171], v[200:203], v[80:83]
	v_mfma_f32_16x16x32_bf16 v[72:75], v[176:179], v[200:203], v[72:75]
	v_mfma_f32_16x16x32_bf16 v[68:71], v[168:171], v[208:211], v[68:71]
	v_mfma_f32_16x16x32_bf16 v[64:67], v[176:179], v[208:211], v[64:67]
	v_mfma_f32_16x16x32_bf16 v[112:115], v[172:175], v[188:191], v[112:115]
	v_mfma_f32_16x16x32_bf16 v[104:107], v[180:183], v[188:191], v[104:107]
	v_mfma_f32_16x16x32_bf16 v[96:99], v[172:175], v[196:199], v[96:99]
	v_mfma_f32_16x16x32_bf16 v[88:91], v[180:183], v[196:199], v[88:91]
	v_mfma_f32_16x16x32_bf16 v[80:83], v[172:175], v[204:207], v[80:83]
	v_mfma_f32_16x16x32_bf16 v[72:75], v[180:183], v[204:207], v[72:75]
	v_mfma_f32_16x16x32_bf16 v[68:71], v[172:175], v[212:215], v[68:71]
	v_mfma_f32_16x16x32_bf16 v[64:67], v[180:183], v[212:215], v[64:67]
	s_barrier
	s_add_i32 s58, s46, s31
	v_lshl_add_u64 v[146:147], s[26:27], 0, v[130:131]
	s_mov_b32 m0, s58
	ds_read_b128 v[184:187], v151 offset:16384
	ds_read_b128 v[188:191], v151 offset:17408
	ds_read_b128 v[192:195], v151 offset:18432
	ds_read_b128 v[196:199], v151 offset:19456
	ds_read_b128 v[200:203], v151 offset:20480
	ds_read_b128 v[204:207], v151 offset:21504
	ds_read_b128 v[208:211], v151 offset:22528
	ds_read_b128 v[212:215], v151 offset:23552
	global_load_lds_dwordx4 v[146:147], off
	s_add_i32 m0, s58, 0x2000
	s_add_u32 s58, s26, 0x40000
	v_lshl_add_u64 v[216:217], s[26:27], 0, v[134:135]
	s_addc_u32 s59, s27, 0
	s_add_i32 s60, s47, s31
	global_load_lds_dwordx4 v[216:217], off
	v_lshl_add_u64 v[218:219], s[58:59], 0, v[130:131]
	s_mov_b32 m0, s60
	v_lshl_add_u64 v[220:221], s[28:29], 0, v[132:133]
	global_load_lds_dwordx4 v[218:219], off
	v_lshl_add_u64 v[218:219], s[58:59], 0, v[134:135]
	s_add_i32 m0, s60, 0x2000
	s_nop 0
	global_load_lds_dwordx4 v[218:219], off
	v_lshl_add_u64 v[218:219], s[28:29], 0, v[128:129]
	s_mov_b32 m0, s35
	s_nop 0
	global_load_lds_dwordx4 v[218:219], off
	s_mov_b32 m0, s36
	s_nop 0
	global_load_lds_dwordx4 v[220:221], off
	s_waitcnt vmcnt(8)
	s_waitcnt lgkmcnt(0)
	s_barrier
	s_waitcnt lgkmcnt(0)
	v_mfma_f32_16x16x32_bf16 v[60:63], v[152:155], v[184:187], v[60:63]
	v_mfma_f32_16x16x32_bf16 v[56:59], v[160:163], v[184:187], v[56:59]
	v_mfma_f32_16x16x32_bf16 v[52:55], v[152:155], v[192:195], v[52:55]
	v_mfma_f32_16x16x32_bf16 v[44:47], v[160:163], v[192:195], v[44:47]
	v_mfma_f32_16x16x32_bf16 v[36:39], v[152:155], v[200:203], v[36:39]
	v_mfma_f32_16x16x32_bf16 v[28:31], v[160:163], v[200:203], v[28:31]
	v_mfma_f32_16x16x32_bf16 v[20:23], v[152:155], v[208:211], v[20:23]
	v_mfma_f32_16x16x32_bf16 v[12:15], v[160:163], v[208:211], v[12:15]
	v_mfma_f32_16x16x32_bf16 v[60:63], v[156:159], v[188:191], v[60:63]
	v_mfma_f32_16x16x32_bf16 v[56:59], v[164:167], v[188:191], v[56:59]
	v_mfma_f32_16x16x32_bf16 v[52:55], v[156:159], v[196:199], v[52:55]
	v_mfma_f32_16x16x32_bf16 v[44:47], v[164:167], v[196:199], v[44:47]
	v_mfma_f32_16x16x32_bf16 v[36:39], v[156:159], v[204:207], v[36:39]
	v_mfma_f32_16x16x32_bf16 v[28:31], v[164:167], v[204:207], v[28:31]
	v_mfma_f32_16x16x32_bf16 v[20:23], v[156:159], v[212:215], v[20:23]
	v_mfma_f32_16x16x32_bf16 v[12:15], v[164:167], v[212:215], v[12:15]
	v_mfma_f32_16x16x32_bf16 v[48:51], v[168:171], v[184:187], v[48:51]
	v_mfma_f32_16x16x32_bf16 v[40:43], v[176:179], v[184:187], v[40:43]
	v_mfma_f32_16x16x32_bf16 v[32:35], v[168:171], v[192:195], v[32:35]
	v_mfma_f32_16x16x32_bf16 v[24:27], v[176:179], v[192:195], v[24:27]
	v_mfma_f32_16x16x32_bf16 v[16:19], v[168:171], v[200:203], v[16:19]
	v_mfma_f32_16x16x32_bf16 v[8:11], v[176:179], v[200:203], v[8:11]
	v_mfma_f32_16x16x32_bf16 v[4:7], v[168:171], v[208:211], v[4:7]
	v_mfma_f32_16x16x32_bf16 v[0:3], v[176:179], v[208:211], v[0:3]
	v_mfma_f32_16x16x32_bf16 v[48:51], v[172:175], v[188:191], v[48:51]
	v_mfma_f32_16x16x32_bf16 v[40:43], v[180:183], v[188:191], v[40:43]
	v_mfma_f32_16x16x32_bf16 v[32:35], v[172:175], v[196:199], v[32:35]
	v_mfma_f32_16x16x32_bf16 v[24:27], v[180:183], v[196:199], v[24:27]
	v_mfma_f32_16x16x32_bf16 v[16:19], v[172:175], v[204:207], v[16:19]
	v_mfma_f32_16x16x32_bf16 v[8:11], v[180:183], v[204:207], v[8:11]
	v_mfma_f32_16x16x32_bf16 v[4:7], v[172:175], v[212:215], v[4:7]
	v_mfma_f32_16x16x32_bf16 v[0:3], v[180:183], v[212:215], v[0:3]
	s_barrier
	s_add_i32 s58, 0, 0x18000
	s_add_i32 s59, 0, 0x1c000
	v_add_u32_e32 v164, s58, v148
	v_add_u32_e32 v180, s59, v148
	ds_read_b128 v[152:155], v164
	ds_read_b128 v[156:159], v164 offset:1024
	ds_read_b128 v[160:163], v164 offset:2048
	ds_read_b128 v[164:167], v164 offset:3072
	ds_read_b128 v[168:171], v180
	ds_read_b128 v[172:175], v180 offset:1024
	ds_read_b128 v[176:179], v180 offset:2048
	ds_read_b128 v[180:183], v180 offset:3072
	s_add_u32 s28, s28, 0x40000
	s_addc_u32 s29, s29, 0
	s_mov_b32 m0, s37
	v_lshl_add_u64 v[222:223], s[28:29], 0, v[128:129]
	ds_read_b128 v[184:187], v151 offset:32768
	ds_read_b128 v[188:191], v151 offset:33792
	ds_read_b128 v[192:195], v151 offset:34816
	ds_read_b128 v[196:199], v151 offset:35840
	ds_read_b128 v[200:203], v151 offset:36864
	ds_read_b128 v[204:207], v151 offset:37888
	ds_read_b128 v[208:211], v151 offset:38912
	ds_read_b128 v[212:215], v151 offset:39936
	global_load_lds_dwordx4 v[222:223], off
	v_lshl_add_u64 v[222:223], s[28:29], 0, v[132:133]
	s_mov_b32 m0, s38
	s_nop 0
	global_load_lds_dwordx4 v[222:223], off
	s_waitcnt vmcnt(8)
	s_waitcnt lgkmcnt(0)
	s_barrier
	s_waitcnt lgkmcnt(0)
	v_mfma_f32_16x16x32_bf16 v[124:127], v[152:155], v[184:187], v[124:127]
	v_mfma_f32_16x16x32_bf16 v[120:123], v[160:163], v[184:187], v[120:123]
	v_mfma_f32_16x16x32_bf16 v[116:119], v[152:155], v[192:195], v[116:119]
	v_mfma_f32_16x16x32_bf16 v[108:111], v[160:163], v[192:195], v[108:111]
	v_mfma_f32_16x16x32_bf16 v[100:103], v[152:155], v[200:203], v[100:103]
	v_mfma_f32_16x16x32_bf16 v[92:95], v[160:163], v[200:203], v[92:95]
	v_mfma_f32_16x16x32_bf16 v[84:87], v[152:155], v[208:211], v[84:87]
	v_mfma_f32_16x16x32_bf16 v[76:79], v[160:163], v[208:211], v[76:79]
	v_mfma_f32_16x16x32_bf16 v[124:127], v[156:159], v[188:191], v[124:127]
	v_mfma_f32_16x16x32_bf16 v[120:123], v[164:167], v[188:191], v[120:123]
	v_mfma_f32_16x16x32_bf16 v[116:119], v[156:159], v[196:199], v[116:119]
	v_mfma_f32_16x16x32_bf16 v[108:111], v[164:167], v[196:199], v[108:111]
	v_mfma_f32_16x16x32_bf16 v[100:103], v[156:159], v[204:207], v[100:103]
	v_mfma_f32_16x16x32_bf16 v[92:95], v[164:167], v[204:207], v[92:95]
	v_mfma_f32_16x16x32_bf16 v[84:87], v[156:159], v[212:215], v[84:87]
	v_mfma_f32_16x16x32_bf16 v[76:79], v[164:167], v[212:215], v[76:79]
	v_mfma_f32_16x16x32_bf16 v[112:115], v[168:171], v[184:187], v[112:115]
	v_mfma_f32_16x16x32_bf16 v[104:107], v[176:179], v[184:187], v[104:107]
	v_mfma_f32_16x16x32_bf16 v[96:99], v[168:171], v[192:195], v[96:99]
	v_mfma_f32_16x16x32_bf16 v[88:91], v[176:179], v[192:195], v[88:91]
	v_mfma_f32_16x16x32_bf16 v[80:83], v[168:171], v[200:203], v[80:83]
	v_mfma_f32_16x16x32_bf16 v[72:75], v[176:179], v[200:203], v[72:75]
	v_mfma_f32_16x16x32_bf16 v[68:71], v[168:171], v[208:211], v[68:71]
	v_mfma_f32_16x16x32_bf16 v[64:67], v[176:179], v[208:211], v[64:67]
	v_mfma_f32_16x16x32_bf16 v[112:115], v[172:175], v[188:191], v[112:115]
	v_mfma_f32_16x16x32_bf16 v[104:107], v[180:183], v[188:191], v[104:107]
	v_mfma_f32_16x16x32_bf16 v[96:99], v[172:175], v[196:199], v[96:99]
	v_mfma_f32_16x16x32_bf16 v[88:91], v[180:183], v[196:199], v[88:91]
	v_mfma_f32_16x16x32_bf16 v[80:83], v[172:175], v[204:207], v[80:83]
	v_mfma_f32_16x16x32_bf16 v[72:75], v[180:183], v[204:207], v[72:75]
	v_mfma_f32_16x16x32_bf16 v[68:71], v[172:175], v[212:215], v[68:71]
	v_mfma_f32_16x16x32_bf16 v[64:67], v[180:183], v[212:215], v[64:67]
	s_barrier
	s_add_i32 s28, s58, s31
	v_lshl_add_u64 v[146:147], v[146:147], 0, s[10:11]
	s_mov_b32 m0, s28
	ds_read_b128 v[184:187], v151 offset:49152
	ds_read_b128 v[188:191], v151 offset:50176
	ds_read_b128 v[192:195], v151 offset:51200
	ds_read_b128 v[196:199], v151 offset:52224
	ds_read_b128 v[200:203], v151 offset:53248
	ds_read_b128 v[204:207], v151 offset:54272
	ds_read_b128 v[208:211], v151 offset:55296
	ds_read_b128 v[212:215], v151 offset:56320
	global_load_lds_dwordx4 v[146:147], off
	s_add_i32 m0, s28, 0x2000
	s_add_u32 s26, s26, 0x40080
	v_lshl_add_u64 v[146:147], v[216:217], 0, s[10:11]
	s_addc_u32 s27, s27, 0
	s_add_i32 s28, s59, s31
	global_load_lds_dwordx4 v[146:147], off
	v_lshl_add_u64 v[146:147], s[26:27], 0, v[130:131]
	s_mov_b32 m0, s28
	s_nop 0
	global_load_lds_dwordx4 v[146:147], off
	v_lshl_add_u64 v[146:147], s[26:27], 0, v[134:135]
	s_add_i32 m0, s28, 0x2000
	s_nop 0
	global_load_lds_dwordx4 v[146:147], off
	v_lshl_add_u64 v[146:147], v[218:219], 0, s[10:11]
	s_mov_b32 m0, s41
	s_nop 0
	global_load_lds_dwordx4 v[146:147], off
	v_lshl_add_u64 v[146:147], v[220:221], 0, s[10:11]
	s_mov_b32 m0, s42
	s_nop 0
	global_load_lds_dwordx4 v[146:147], off
	s_waitcnt vmcnt(8)
	s_waitcnt lgkmcnt(0)
	s_barrier
	s_waitcnt lgkmcnt(0)
	v_mfma_f32_16x16x32_bf16 v[60:63], v[152:155], v[184:187], v[60:63]
	v_mfma_f32_16x16x32_bf16 v[56:59], v[160:163], v[184:187], v[56:59]
	v_mfma_f32_16x16x32_bf16 v[52:55], v[152:155], v[192:195], v[52:55]
	v_mfma_f32_16x16x32_bf16 v[44:47], v[160:163], v[192:195], v[44:47]
	v_mfma_f32_16x16x32_bf16 v[36:39], v[152:155], v[200:203], v[36:39]
	v_mfma_f32_16x16x32_bf16 v[28:31], v[160:163], v[200:203], v[28:31]
	v_mfma_f32_16x16x32_bf16 v[20:23], v[152:155], v[208:211], v[20:23]
	v_mfma_f32_16x16x32_bf16 v[12:15], v[160:163], v[208:211], v[12:15]
	v_mfma_f32_16x16x32_bf16 v[60:63], v[156:159], v[188:191], v[60:63]
	v_mfma_f32_16x16x32_bf16 v[56:59], v[164:167], v[188:191], v[56:59]
	v_mfma_f32_16x16x32_bf16 v[52:55], v[156:159], v[196:199], v[52:55]
	v_mfma_f32_16x16x32_bf16 v[44:47], v[164:167], v[196:199], v[44:47]
	v_mfma_f32_16x16x32_bf16 v[36:39], v[156:159], v[204:207], v[36:39]
	v_mfma_f32_16x16x32_bf16 v[28:31], v[164:167], v[204:207], v[28:31]
	v_mfma_f32_16x16x32_bf16 v[20:23], v[156:159], v[212:215], v[20:23]
	v_mfma_f32_16x16x32_bf16 v[12:15], v[164:167], v[212:215], v[12:15]
	v_mfma_f32_16x16x32_bf16 v[48:51], v[168:171], v[184:187], v[48:51]
	v_mfma_f32_16x16x32_bf16 v[40:43], v[176:179], v[184:187], v[40:43]
	v_mfma_f32_16x16x32_bf16 v[32:35], v[168:171], v[192:195], v[32:35]
	v_mfma_f32_16x16x32_bf16 v[24:27], v[176:179], v[192:195], v[24:27]
	v_mfma_f32_16x16x32_bf16 v[16:19], v[168:171], v[200:203], v[16:19]
	v_mfma_f32_16x16x32_bf16 v[8:11], v[176:179], v[200:203], v[8:11]
	v_mfma_f32_16x16x32_bf16 v[4:7], v[168:171], v[208:211], v[4:7]
	v_mfma_f32_16x16x32_bf16 v[0:3], v[176:179], v[208:211], v[0:3]
	v_mfma_f32_16x16x32_bf16 v[48:51], v[172:175], v[188:191], v[48:51]
	v_mfma_f32_16x16x32_bf16 v[40:43], v[180:183], v[188:191], v[40:43]
	v_mfma_f32_16x16x32_bf16 v[32:35], v[172:175], v[196:199], v[32:35]
	v_mfma_f32_16x16x32_bf16 v[24:27], v[180:183], v[196:199], v[24:27]
	v_mfma_f32_16x16x32_bf16 v[16:19], v[172:175], v[204:207], v[16:19]
	v_mfma_f32_16x16x32_bf16 v[8:11], v[180:183], v[204:207], v[8:11]
	v_mfma_f32_16x16x32_bf16 v[4:7], v[172:175], v[212:215], v[4:7]
	v_mfma_f32_16x16x32_bf16 v[0:3], v[180:183], v[212:215], v[0:3]
	s_add_i32 s57, s57, 2
	s_add_u32 s55, s55, 0x100
	s_addc_u32 s56, s56, 0
	s_add_u32 s24, s24, 0x100
	s_addc_u32 s25, s25, 0
	s_cmp_lt_u32 s57, 14
	s_barrier
	s_cbranch_scc1 .LBB10_20
	s_andn2_b64 vcc, exec, s[12:13]
	s_cbranch_vccnz .LBB10_23
	s_barrier

.LBB12_8:
	s_ashr_i32 s15, s14, 31
	v_cmp_lt_i64_e32 vcc, s[0:1], v[142:143]
	s_lshl_b64 s[0:1], s[14:15], 19
	s_add_u32 s16, s28, s0
	s_addc_u32 s17, s29, s1
	s_and_b64 s[0:1], vcc, exec
	s_cselect_b32 s15, s17, s25
	s_cselect_b32 s54, s16, s24
	s_ashr_i32 s13, s12, 31
	s_lshl_b64 s[0:1], s[12:13], 19
	s_add_u32 s18, s30, s0
	s_addc_u32 s19, s31, s1
	s_and_b64 s[0:1], vcc, exec
	s_cselect_b32 s13, s19, s23
	s_cselect_b32 s55, s18, s22
	s_add_u32 s56, s22, 0x100
	s_addc_u32 s57, s23, 0
	s_add_u32 s22, s24, 0x40080
	s_addc_u32 s23, s25, 0
	s_mov_b32 s58, -2
	ds_read_b128 v[152:155], v149
	ds_read_b128 v[156:159], v149 offset:1024
	ds_read_b128 v[160:163], v149 offset:2048
	ds_read_b128 v[164:167], v149 offset:3072
	ds_read_b128 v[168:171], v150
	ds_read_b128 v[172:175], v150 offset:1024
	ds_read_b128 v[176:179], v150 offset:2048
	ds_read_b128 v[180:183], v150 offset:3072
	s_add_u32 s24, s22, 0xfffc0080
	s_addc_u32 s25, s23, -1
	s_cmp_eq_u32 s58, 12
	s_cselect_b32 s27, s15, s25
	s_cselect_b32 s26, s54, s24
	s_cselect_b32 s25, s13, s57
	s_cselect_b32 s24, s55, s56
	v_lshl_add_u64 v[146:147], s[22:23], 0, v[140:141]
	s_add_i32 m0, s36, 0xc000
	ds_read_b128 v[184:187], v151
	ds_read_b128 v[188:191], v151 offset:1024
	ds_read_b128 v[192:195], v151 offset:2048
	ds_read_b128 v[196:199], v151 offset:3072
	ds_read_b128 v[200:203], v151 offset:4096
	ds_read_b128 v[204:207], v151 offset:5120
	ds_read_b128 v[208:211], v151 offset:6144
	ds_read_b128 v[212:215], v151 offset:7168
	global_load_lds_dwordx4 v[146:147], off
	v_lshl_add_u64 v[146:147], s[22:23], 0, v[138:139]
	s_add_i32 m0, s36, 0xe000
	s_nop 0
	global_load_lds_dwordx4 v[146:147], off
	s_waitcnt vmcnt(8)
	s_waitcnt lgkmcnt(0)
	s_barrier
	s_waitcnt lgkmcnt(0)
	v_mfma_f32_16x16x32_bf16 v[124:127], v[152:155], v[184:187], 0
	v_mfma_f32_16x16x32_bf16 v[120:123], v[160:163], v[184:187], 0
	v_mfma_f32_16x16x32_bf16 v[108:111], v[152:155], v[192:195], 0
	v_mfma_f32_16x16x32_bf16 v[104:107], v[160:163], v[192:195], 0
	v_mfma_f32_16x16x32_bf16 v[92:95], v[152:155], v[200:203], 0
	v_mfma_f32_16x16x32_bf16 v[88:91], v[160:163], v[200:203], 0
	v_mfma_f32_16x16x32_bf16 v[76:79], v[152:155], v[208:211], 0
	v_mfma_f32_16x16x32_bf16 v[72:75], v[160:163], v[208:211], 0
	v_mfma_f32_16x16x32_bf16 v[124:127], v[156:159], v[188:191], v[124:127]
	v_mfma_f32_16x16x32_bf16 v[120:123], v[164:167], v[188:191], v[120:123]
	v_mfma_f32_16x16x32_bf16 v[108:111], v[156:159], v[196:199], v[108:111]
	v_mfma_f32_16x16x32_bf16 v[104:107], v[164:167], v[196:199], v[104:107]
	v_mfma_f32_16x16x32_bf16 v[92:95], v[156:159], v[204:207], v[92:95]
	v_mfma_f32_16x16x32_bf16 v[88:91], v[164:167], v[204:207], v[88:91]
	v_mfma_f32_16x16x32_bf16 v[76:79], v[156:159], v[212:215], v[76:79]
	v_mfma_f32_16x16x32_bf16 v[72:75], v[164:167], v[212:215], v[72:75]
	v_mfma_f32_16x16x32_bf16 v[116:119], v[168:171], v[184:187], 0
	v_mfma_f32_16x16x32_bf16 v[112:115], v[176:179], v[184:187], 0
	v_mfma_f32_16x16x32_bf16 v[100:103], v[168:171], v[192:195], 0
	v_mfma_f32_16x16x32_bf16 v[96:99], v[176:179], v[192:195], 0
	v_mfma_f32_16x16x32_bf16 v[84:87], v[168:171], v[200:203], 0
	v_mfma_f32_16x16x32_bf16 v[80:83], v[176:179], v[200:203], 0
	v_mfma_f32_16x16x32_bf16 v[68:71], v[168:171], v[208:211], 0
	v_mfma_f32_16x16x32_bf16 v[64:67], v[176:179], v[208:211], 0
	v_mfma_f32_16x16x32_bf16 v[116:119], v[172:175], v[188:191], v[116:119]
	v_mfma_f32_16x16x32_bf16 v[112:115], v[180:183], v[188:191], v[112:115]
	v_mfma_f32_16x16x32_bf16 v[100:103], v[172:175], v[196:199], v[100:103]
	v_mfma_f32_16x16x32_bf16 v[96:99], v[180:183], v[196:199], v[96:99]
	v_mfma_f32_16x16x32_bf16 v[84:87], v[172:175], v[204:207], v[84:87]
	v_mfma_f32_16x16x32_bf16 v[80:83], v[180:183], v[204:207], v[80:83]
	v_mfma_f32_16x16x32_bf16 v[68:71], v[172:175], v[212:215], v[68:71]
	v_mfma_f32_16x16x32_bf16 v[64:67], v[180:183], v[212:215], v[64:67]
	s_barrier
	s_add_i32 s59, s44, s33
	v_lshl_add_u64 v[146:147], s[24:25], 0, v[132:133]
	s_mov_b32 m0, s59
	ds_read_b128 v[184:187], v151 offset:16384
	ds_read_b128 v[188:191], v151 offset:17408
	ds_read_b128 v[192:195], v151 offset:18432
	ds_read_b128 v[196:199], v151 offset:19456
	ds_read_b128 v[200:203], v151 offset:20480
	ds_read_b128 v[204:207], v151 offset:21504
	ds_read_b128 v[208:211], v151 offset:22528
	ds_read_b128 v[212:215], v151 offset:23552
	global_load_lds_dwordx4 v[146:147], off
	s_add_i32 m0, s59, 0x2000
	s_add_u32 s60, s24, 0x40000
	v_lshl_add_u64 v[216:217], s[24:25], 0, v[128:129]
	s_addc_u32 s61, s25, 0
	s_add_i32 s59, s45, s33
	global_load_lds_dwordx4 v[216:217], off
	v_lshl_add_u64 v[218:219], s[60:61], 0, v[132:133]
	s_mov_b32 m0, s59
	v_lshl_add_u64 v[220:221], s[26:27], 0, v[130:131]
	global_load_lds_dwordx4 v[218:219], off
	v_lshl_add_u64 v[218:219], s[60:61], 0, v[128:129]
	s_add_i32 m0, s59, 0x2000
	s_nop 0
	global_load_lds_dwordx4 v[218:219], off
	v_lshl_add_u64 v[218:219], s[26:27], 0, v[134:135]
	s_mov_b32 m0, s36
	s_nop 0
	global_load_lds_dwordx4 v[218:219], off
	s_mov_b32 m0, s37
	s_nop 0
	global_load_lds_dwordx4 v[220:221], off
	s_waitcnt vmcnt(8)
	s_waitcnt lgkmcnt(0)
	s_barrier
	s_waitcnt lgkmcnt(0)
	v_mfma_f32_16x16x32_bf16 v[60:63], v[152:155], v[184:187], 0
	v_mfma_f32_16x16x32_bf16 v[56:59], v[160:163], v[184:187], 0
	v_mfma_f32_16x16x32_bf16 v[44:47], v[152:155], v[192:195], 0
	v_mfma_f32_16x16x32_bf16 v[40:43], v[160:163], v[192:195], 0
	v_mfma_f32_16x16x32_bf16 v[28:31], v[152:155], v[200:203], 0
	v_mfma_f32_16x16x32_bf16 v[24:27], v[160:163], v[200:203], 0
	v_mfma_f32_16x16x32_bf16 v[12:15], v[152:155], v[208:211], 0
	v_mfma_f32_16x16x32_bf16 v[8:11], v[160:163], v[208:211], 0
	v_mfma_f32_16x16x32_bf16 v[60:63], v[156:159], v[188:191], v[60:63]
	v_mfma_f32_16x16x32_bf16 v[56:59], v[164:167], v[188:191], v[56:59]
	v_mfma_f32_16x16x32_bf16 v[44:47], v[156:159], v[196:199], v[44:47]
	v_mfma_f32_16x16x32_bf16 v[40:43], v[164:167], v[196:199], v[40:43]
	v_mfma_f32_16x16x32_bf16 v[28:31], v[156:159], v[204:207], v[28:31]
	v_mfma_f32_16x16x32_bf16 v[24:27], v[164:167], v[204:207], v[24:27]
	v_mfma_f32_16x16x32_bf16 v[12:15], v[156:159], v[212:215], v[12:15]
	v_mfma_f32_16x16x32_bf16 v[8:11], v[164:167], v[212:215], v[8:11]
	v_mfma_f32_16x16x32_bf16 v[52:55], v[168:171], v[184:187], 0
	v_mfma_f32_16x16x32_bf16 v[48:51], v[176:179], v[184:187], 0
	v_mfma_f32_16x16x32_bf16 v[36:39], v[168:171], v[192:195], 0
	v_mfma_f32_16x16x32_bf16 v[32:35], v[176:179], v[192:195], 0
	v_mfma_f32_16x16x32_bf16 v[20:23], v[168:171], v[200:203], 0
	v_mfma_f32_16x16x32_bf16 v[16:19], v[176:179], v[200:203], 0
	v_mfma_f32_16x16x32_bf16 v[4:7], v[168:171], v[208:211], 0
	v_mfma_f32_16x16x32_bf16 v[0:3], v[176:179], v[208:211], 0
	v_mfma_f32_16x16x32_bf16 v[52:55], v[172:175], v[188:191], v[52:55]
	v_mfma_f32_16x16x32_bf16 v[48:51], v[180:183], v[188:191], v[48:51]
	v_mfma_f32_16x16x32_bf16 v[36:39], v[172:175], v[196:199], v[36:39]
	v_mfma_f32_16x16x32_bf16 v[32:35], v[180:183], v[196:199], v[32:35]
	v_mfma_f32_16x16x32_bf16 v[20:23], v[172:175], v[204:207], v[20:23]
	v_mfma_f32_16x16x32_bf16 v[16:19], v[180:183], v[204:207], v[16:19]
	v_mfma_f32_16x16x32_bf16 v[4:7], v[172:175], v[212:215], v[4:7]
	v_mfma_f32_16x16x32_bf16 v[0:3], v[180:183], v[212:215], v[0:3]
	s_barrier
	s_add_i32 s59, 0, 0x18000
	s_add_i32 s60, 0, 0x1c000
	v_add_u32_e32 v164, s59, v148
	v_add_u32_e32 v180, s60, v148
	ds_read_b128 v[152:155], v164
	ds_read_b128 v[156:159], v164 offset:1024
	ds_read_b128 v[160:163], v164 offset:2048
	ds_read_b128 v[164:167], v164 offset:3072
	ds_read_b128 v[168:171], v180
	ds_read_b128 v[172:175], v180 offset:1024
	ds_read_b128 v[176:179], v180 offset:2048
	ds_read_b128 v[180:183], v180 offset:3072
	s_add_u32 s26, s26, 0x40000
	s_addc_u32 s27, s27, 0
	s_mov_b32 m0, s38
	v_lshl_add_u64 v[222:223], s[26:27], 0, v[134:135]
	ds_read_b128 v[184:187], v151 offset:32768
	ds_read_b128 v[188:191], v151 offset:33792
	ds_read_b128 v[192:195], v151 offset:34816
	ds_read_b128 v[196:199], v151 offset:35840
	ds_read_b128 v[200:203], v151 offset:36864
	ds_read_b128 v[204:207], v151 offset:37888
	ds_read_b128 v[208:211], v151 offset:38912
	ds_read_b128 v[212:215], v151 offset:39936
	global_load_lds_dwordx4 v[222:223], off
	v_lshl_add_u64 v[222:223], s[26:27], 0, v[130:131]
	s_mov_b32 m0, s39
	s_nop 0
	global_load_lds_dwordx4 v[222:223], off
	s_waitcnt vmcnt(8)
	s_waitcnt lgkmcnt(0)
	s_barrier
	s_waitcnt lgkmcnt(0)
	v_mfma_f32_16x16x32_bf16 v[124:127], v[152:155], v[184:187], v[124:127]
	v_mfma_f32_16x16x32_bf16 v[120:123], v[160:163], v[184:187], v[120:123]
	v_mfma_f32_16x16x32_bf16 v[108:111], v[152:155], v[192:195], v[108:111]
	v_mfma_f32_16x16x32_bf16 v[104:107], v[160:163], v[192:195], v[104:107]
	v_mfma_f32_16x16x32_bf16 v[92:95], v[152:155], v[200:203], v[92:95]
	v_mfma_f32_16x16x32_bf16 v[88:91], v[160:163], v[200:203], v[88:91]
	v_mfma_f32_16x16x32_bf16 v[76:79], v[152:155], v[208:211], v[76:79]
	v_mfma_f32_16x16x32_bf16 v[72:75], v[160:163], v[208:211], v[72:75]
	v_mfma_f32_16x16x32_bf16 v[124:127], v[156:159], v[188:191], v[124:127]
	v_mfma_f32_16x16x32_bf16 v[120:123], v[164:167], v[188:191], v[120:123]
	v_mfma_f32_16x16x32_bf16 v[108:111], v[156:159], v[196:199], v[108:111]
	v_mfma_f32_16x16x32_bf16 v[104:107], v[164:167], v[196:199], v[104:107]
	v_mfma_f32_16x16x32_bf16 v[92:95], v[156:159], v[204:207], v[92:95]
	v_mfma_f32_16x16x32_bf16 v[88:91], v[164:167], v[204:207], v[88:91]
	v_mfma_f32_16x16x32_bf16 v[76:79], v[156:159], v[212:215], v[76:79]
	v_mfma_f32_16x16x32_bf16 v[72:75], v[164:167], v[212:215], v[72:75]
	v_mfma_f32_16x16x32_bf16 v[116:119], v[168:171], v[184:187], v[116:119]
	v_mfma_f32_16x16x32_bf16 v[112:115], v[176:179], v[184:187], v[112:115]
	v_mfma_f32_16x16x32_bf16 v[100:103], v[168:171], v[192:195], v[100:103]
	v_mfma_f32_16x16x32_bf16 v[96:99], v[176:179], v[192:195], v[96:99]
	v_mfma_f32_16x16x32_bf16 v[84:87], v[168:171], v[200:203], v[84:87]
	v_mfma_f32_16x16x32_bf16 v[80:83], v[176:179], v[200:203], v[80:83]
	v_mfma_f32_16x16x32_bf16 v[68:71], v[168:171], v[208:211], v[68:71]
	v_mfma_f32_16x16x32_bf16 v[64:67], v[176:179], v[208:211], v[64:67]
	v_mfma_f32_16x16x32_bf16 v[116:119], v[172:175], v[188:191], v[116:119]
	v_mfma_f32_16x16x32_bf16 v[112:115], v[180:183], v[188:191], v[112:115]
	v_mfma_f32_16x16x32_bf16 v[100:103], v[172:175], v[196:199], v[100:103]
	v_mfma_f32_16x16x32_bf16 v[96:99], v[180:183], v[196:199], v[96:99]
	v_mfma_f32_16x16x32_bf16 v[84:87], v[172:175], v[204:207], v[84:87]
	v_mfma_f32_16x16x32_bf16 v[80:83], v[180:183], v[204:207], v[80:83]
	v_mfma_f32_16x16x32_bf16 v[68:71], v[172:175], v[212:215], v[68:71]
	v_mfma_f32_16x16x32_bf16 v[64:67], v[180:183], v[212:215], v[64:67]
	s_barrier
	s_add_i32 s26, s59, s33
	v_lshl_add_u64 v[146:147], v[146:147], 0, s[8:9]
	s_mov_b32 m0, s26
	ds_read_b128 v[184:187], v151 offset:49152
	ds_read_b128 v[188:191], v151 offset:50176
	ds_read_b128 v[192:195], v151 offset:51200
	ds_read_b128 v[196:199], v151 offset:52224
	ds_read_b128 v[200:203], v151 offset:53248
	ds_read_b128 v[204:207], v151 offset:54272
	ds_read_b128 v[208:211], v151 offset:55296
	ds_read_b128 v[212:215], v151 offset:56320
	global_load_lds_dwordx4 v[146:147], off
	s_add_i32 m0, s26, 0x2000
	s_add_u32 s24, s24, 0x40080
	v_lshl_add_u64 v[146:147], v[216:217], 0, s[8:9]
	s_addc_u32 s25, s25, 0
	s_add_i32 s26, s60, s33
	global_load_lds_dwordx4 v[146:147], off
	v_lshl_add_u64 v[146:147], s[24:25], 0, v[132:133]
	s_mov_b32 m0, s26
	s_nop 0
	global_load_lds_dwordx4 v[146:147], off
	v_lshl_add_u64 v[146:147], s[24:25], 0, v[128:129]
	s_add_i32 m0, s26, 0x2000
	s_nop 0
	global_load_lds_dwordx4 v[146:147], off
	v_lshl_add_u64 v[146:147], v[218:219], 0, s[8:9]
	s_mov_b32 m0, s41
	s_nop 0
	global_load_lds_dwordx4 v[146:147], off
	v_lshl_add_u64 v[146:147], v[220:221], 0, s[8:9]
	s_mov_b32 m0, s42
	s_nop 0
	global_load_lds_dwordx4 v[146:147], off
	s_waitcnt vmcnt(8)
	s_waitcnt lgkmcnt(0)
	s_barrier
	s_waitcnt lgkmcnt(0)
	v_mfma_f32_16x16x32_bf16 v[60:63], v[152:155], v[184:187], v[60:63]
	v_mfma_f32_16x16x32_bf16 v[56:59], v[160:163], v[184:187], v[56:59]
	v_mfma_f32_16x16x32_bf16 v[44:47], v[152:155], v[192:195], v[44:47]
	v_mfma_f32_16x16x32_bf16 v[40:43], v[160:163], v[192:195], v[40:43]
	v_mfma_f32_16x16x32_bf16 v[28:31], v[152:155], v[200:203], v[28:31]
	v_mfma_f32_16x16x32_bf16 v[24:27], v[160:163], v[200:203], v[24:27]
	v_mfma_f32_16x16x32_bf16 v[12:15], v[152:155], v[208:211], v[12:15]
	v_mfma_f32_16x16x32_bf16 v[8:11], v[160:163], v[208:211], v[8:11]
	v_mfma_f32_16x16x32_bf16 v[60:63], v[156:159], v[188:191], v[60:63]
	v_mfma_f32_16x16x32_bf16 v[56:59], v[164:167], v[188:191], v[56:59]
	v_mfma_f32_16x16x32_bf16 v[44:47], v[156:159], v[196:199], v[44:47]
	v_mfma_f32_16x16x32_bf16 v[40:43], v[164:167], v[196:199], v[40:43]
	v_mfma_f32_16x16x32_bf16 v[28:31], v[156:159], v[204:207], v[28:31]
	v_mfma_f32_16x16x32_bf16 v[24:27], v[164:167], v[204:207], v[24:27]
	v_mfma_f32_16x16x32_bf16 v[12:15], v[156:159], v[212:215], v[12:15]
	v_mfma_f32_16x16x32_bf16 v[8:11], v[164:167], v[212:215], v[8:11]
	v_mfma_f32_16x16x32_bf16 v[52:55], v[168:171], v[184:187], v[52:55]
	v_mfma_f32_16x16x32_bf16 v[48:51], v[176:179], v[184:187], v[48:51]
	v_mfma_f32_16x16x32_bf16 v[36:39], v[168:171], v[192:195], v[36:39]
	v_mfma_f32_16x16x32_bf16 v[32:35], v[176:179], v[192:195], v[32:35]
	v_mfma_f32_16x16x32_bf16 v[20:23], v[168:171], v[200:203], v[20:23]
	v_mfma_f32_16x16x32_bf16 v[16:19], v[176:179], v[200:203], v[16:19]
	v_mfma_f32_16x16x32_bf16 v[4:7], v[168:171], v[208:211], v[4:7]
	v_mfma_f32_16x16x32_bf16 v[0:3], v[176:179], v[208:211], v[0:3]
	v_mfma_f32_16x16x32_bf16 v[52:55], v[172:175], v[188:191], v[52:55]
	v_mfma_f32_16x16x32_bf16 v[48:51], v[180:183], v[188:191], v[48:51]
	v_mfma_f32_16x16x32_bf16 v[36:39], v[172:175], v[196:199], v[36:39]
	v_mfma_f32_16x16x32_bf16 v[32:35], v[180:183], v[196:199], v[32:35]
	v_mfma_f32_16x16x32_bf16 v[20:23], v[172:175], v[204:207], v[20:23]
	v_mfma_f32_16x16x32_bf16 v[16:19], v[180:183], v[204:207], v[16:19]
	v_mfma_f32_16x16x32_bf16 v[4:7], v[172:175], v[212:215], v[4:7]
	v_mfma_f32_16x16x32_bf16 v[0:3], v[180:183], v[212:215], v[0:3]
	s_add_i32 s58, s58, 2
	s_add_u32 s56, s56, 0x100
	s_addc_u32 s57, s57, 0
	s_add_u32 s22, s22, 0x100
	s_addc_u32 s23, s23, 0
	s_cmp_lt_u32 s58, 14
	s_barrier
.LBB12_9:
	ds_read_b128 v[152:155], v149
	ds_read_b128 v[156:159], v149 offset:1024
	ds_read_b128 v[160:163], v149 offset:2048
	ds_read_b128 v[164:167], v149 offset:3072
	ds_read_b128 v[168:171], v150
	ds_read_b128 v[172:175], v150 offset:1024
	ds_read_b128 v[176:179], v150 offset:2048
	ds_read_b128 v[180:183], v150 offset:3072
	s_add_u32 s24, s22, 0xfffc0080
	s_addc_u32 s25, s23, -1
	s_cmp_eq_u32 s58, 12
	s_cselect_b32 s27, s15, s25
	s_cselect_b32 s26, s54, s24
	s_cselect_b32 s25, s13, s57
	s_cselect_b32 s24, s55, s56
	v_lshl_add_u64 v[146:147], s[22:23], 0, v[140:141]
	s_add_i32 m0, s36, 0xc000
	ds_read_b128 v[184:187], v151
	ds_read_b128 v[188:191], v151 offset:1024
	ds_read_b128 v[192:195], v151 offset:2048
	ds_read_b128 v[196:199], v151 offset:3072
	ds_read_b128 v[200:203], v151 offset:4096
	ds_read_b128 v[204:207], v151 offset:5120
	ds_read_b128 v[208:211], v151 offset:6144
	ds_read_b128 v[212:215], v151 offset:7168
	global_load_lds_dwordx4 v[146:147], off
	v_lshl_add_u64 v[146:147], s[22:23], 0, v[138:139]
	s_add_i32 m0, s36, 0xe000
	s_nop 0
	global_load_lds_dwordx4 v[146:147], off
	s_waitcnt vmcnt(8)
	s_waitcnt lgkmcnt(0)
	s_barrier
	s_waitcnt lgkmcnt(0)
	v_mfma_f32_16x16x32_bf16 v[124:127], v[152:155], v[184:187], v[124:127]
	v_mfma_f32_16x16x32_bf16 v[120:123], v[160:163], v[184:187], v[120:123]
	v_mfma_f32_16x16x32_bf16 v[108:111], v[152:155], v[192:195], v[108:111]
	v_mfma_f32_16x16x32_bf16 v[104:107], v[160:163], v[192:195], v[104:107]
	v_mfma_f32_16x16x32_bf16 v[92:95], v[152:155], v[200:203], v[92:95]
	v_mfma_f32_16x16x32_bf16 v[88:91], v[160:163], v[200:203], v[88:91]
	v_mfma_f32_16x16x32_bf16 v[76:79], v[152:155], v[208:211], v[76:79]
	v_mfma_f32_16x16x32_bf16 v[72:75], v[160:163], v[208:211], v[72:75]
	v_mfma_f32_16x16x32_bf16 v[124:127], v[156:159], v[188:191], v[124:127]
	v_mfma_f32_16x16x32_bf16 v[120:123], v[164:167], v[188:191], v[120:123]
	v_mfma_f32_16x16x32_bf16 v[108:111], v[156:159], v[196:199], v[108:111]
	v_mfma_f32_16x16x32_bf16 v[104:107], v[164:167], v[196:199], v[104:107]
	v_mfma_f32_16x16x32_bf16 v[92:95], v[156:159], v[204:207], v[92:95]
	v_mfma_f32_16x16x32_bf16 v[88:91], v[164:167], v[204:207], v[88:91]
	v_mfma_f32_16x16x32_bf16 v[76:79], v[156:159], v[212:215], v[76:79]
	v_mfma_f32_16x16x32_bf16 v[72:75], v[164:167], v[212:215], v[72:75]
	v_mfma_f32_16x16x32_bf16 v[116:119], v[168:171], v[184:187], v[116:119]
	v_mfma_f32_16x16x32_bf16 v[112:115], v[176:179], v[184:187], v[112:115]
	v_mfma_f32_16x16x32_bf16 v[100:103], v[168:171], v[192:195], v[100:103]
	v_mfma_f32_16x16x32_bf16 v[96:99], v[176:179], v[192:195], v[96:99]
	v_mfma_f32_16x16x32_bf16 v[84:87], v[168:171], v[200:203], v[84:87]
	v_mfma_f32_16x16x32_bf16 v[80:83], v[176:179], v[200:203], v[80:83]
	v_mfma_f32_16x16x32_bf16 v[68:71], v[168:171], v[208:211], v[68:71]
	v_mfma_f32_16x16x32_bf16 v[64:67], v[176:179], v[208:211], v[64:67]
	v_mfma_f32_16x16x32_bf16 v[116:119], v[172:175], v[188:191], v[116:119]
	v_mfma_f32_16x16x32_bf16 v[112:115], v[180:183], v[188:191], v[112:115]
	v_mfma_f32_16x16x32_bf16 v[100:103], v[172:175], v[196:199], v[100:103]
	v_mfma_f32_16x16x32_bf16 v[96:99], v[180:183], v[196:199], v[96:99]
	v_mfma_f32_16x16x32_bf16 v[84:87], v[172:175], v[204:207], v[84:87]
	v_mfma_f32_16x16x32_bf16 v[80:83], v[180:183], v[204:207], v[80:83]
	v_mfma_f32_16x16x32_bf16 v[68:71], v[172:175], v[212:215], v[68:71]
	v_mfma_f32_16x16x32_bf16 v[64:67], v[180:183], v[212:215], v[64:67]
	s_barrier
	s_add_i32 s59, s44, s33
	v_lshl_add_u64 v[146:147], s[24:25], 0, v[132:133]
	s_mov_b32 m0, s59
	ds_read_b128 v[184:187], v151 offset:16384
	ds_read_b128 v[188:191], v151 offset:17408
	ds_read_b128 v[192:195], v151 offset:18432
	ds_read_b128 v[196:199], v151 offset:19456
	ds_read_b128 v[200:203], v151 offset:20480
	ds_read_b128 v[204:207], v151 offset:21504
	ds_read_b128 v[208:211], v151 offset:22528
	ds_read_b128 v[212:215], v151 offset:23552
	global_load_lds_dwordx4 v[146:147], off
	s_add_i32 m0, s59, 0x2000
	s_add_u32 s60, s24, 0x40000
	v_lshl_add_u64 v[216:217], s[24:25], 0, v[128:129]
	s_addc_u32 s61, s25, 0
	s_add_i32 s59, s45, s33
	global_load_lds_dwordx4 v[216:217], off
	v_lshl_add_u64 v[218:219], s[60:61], 0, v[132:133]
	s_mov_b32 m0, s59
	v_lshl_add_u64 v[220:221], s[26:27], 0, v[130:131]
	global_load_lds_dwordx4 v[218:219], off
	v_lshl_add_u64 v[218:219], s[60:61], 0, v[128:129]
	s_add_i32 m0, s59, 0x2000
	s_nop 0
	global_load_lds_dwordx4 v[218:219], off
	v_lshl_add_u64 v[218:219], s[26:27], 0, v[134:135]
	s_mov_b32 m0, s36
	s_nop 0
	global_load_lds_dwordx4 v[218:219], off
	s_mov_b32 m0, s37
	s_nop 0
	global_load_lds_dwordx4 v[220:221], off
	s_waitcnt vmcnt(8)
	s_waitcnt lgkmcnt(0)
	s_barrier
	s_waitcnt lgkmcnt(0)
	v_mfma_f32_16x16x32_bf16 v[60:63], v[152:155], v[184:187], v[60:63]
	v_mfma_f32_16x16x32_bf16 v[56:59], v[160:163], v[184:187], v[56:59]
	v_mfma_f32_16x16x32_bf16 v[44:47], v[152:155], v[192:195], v[44:47]
	v_mfma_f32_16x16x32_bf16 v[40:43], v[160:163], v[192:195], v[40:43]
	v_mfma_f32_16x16x32_bf16 v[28:31], v[152:155], v[200:203], v[28:31]
	v_mfma_f32_16x16x32_bf16 v[24:27], v[160:163], v[200:203], v[24:27]
	v_mfma_f32_16x16x32_bf16 v[12:15], v[152:155], v[208:211], v[12:15]
	v_mfma_f32_16x16x32_bf16 v[8:11], v[160:163], v[208:211], v[8:11]
	v_mfma_f32_16x16x32_bf16 v[60:63], v[156:159], v[188:191], v[60:63]
	v_mfma_f32_16x16x32_bf16 v[56:59], v[164:167], v[188:191], v[56:59]
	v_mfma_f32_16x16x32_bf16 v[44:47], v[156:159], v[196:199], v[44:47]
	v_mfma_f32_16x16x32_bf16 v[40:43], v[164:167], v[196:199], v[40:43]
	v_mfma_f32_16x16x32_bf16 v[28:31], v[156:159], v[204:207], v[28:31]
	v_mfma_f32_16x16x32_bf16 v[24:27], v[164:167], v[204:207], v[24:27]
	v_mfma_f32_16x16x32_bf16 v[12:15], v[156:159], v[212:215], v[12:15]
	v_mfma_f32_16x16x32_bf16 v[8:11], v[164:167], v[212:215], v[8:11]
	v_mfma_f32_16x16x32_bf16 v[52:55], v[168:171], v[184:187], v[52:55]
	v_mfma_f32_16x16x32_bf16 v[48:51], v[176:179], v[184:187], v[48:51]
	v_mfma_f32_16x16x32_bf16 v[36:39], v[168:171], v[192:195], v[36:39]
	v_mfma_f32_16x16x32_bf16 v[32:35], v[176:179], v[192:195], v[32:35]
	v_mfma_f32_16x16x32_bf16 v[20:23], v[168:171], v[200:203], v[20:23]
	v_mfma_f32_16x16x32_bf16 v[16:19], v[176:179], v[200:203], v[16:19]
	v_mfma_f32_16x16x32_bf16 v[4:7], v[168:171], v[208:211], v[4:7]
	v_mfma_f32_16x16x32_bf16 v[0:3], v[176:179], v[208:211], v[0:3]
	v_mfma_f32_16x16x32_bf16 v[52:55], v[172:175], v[188:191], v[52:55]
	v_mfma_f32_16x16x32_bf16 v[48:51], v[180:183], v[188:191], v[48:51]
	v_mfma_f32_16x16x32_bf16 v[36:39], v[172:175], v[196:199], v[36:39]
	v_mfma_f32_16x16x32_bf16 v[32:35], v[180:183], v[196:199], v[32:35]
	v_mfma_f32_16x16x32_bf16 v[20:23], v[172:175], v[204:207], v[20:23]
	v_mfma_f32_16x16x32_bf16 v[16:19], v[180:183], v[204:207], v[16:19]
	v_mfma_f32_16x16x32_bf16 v[4:7], v[172:175], v[212:215], v[4:7]
	v_mfma_f32_16x16x32_bf16 v[0:3], v[180:183], v[212:215], v[0:3]
	s_barrier
	s_add_i32 s59, 0, 0x18000
	s_add_i32 s60, 0, 0x1c000
	v_add_u32_e32 v164, s59, v148
	v_add_u32_e32 v180, s60, v148
	ds_read_b128 v[152:155], v164
	ds_read_b128 v[156:159], v164 offset:1024
	ds_read_b128 v[160:163], v164 offset:2048
	ds_read_b128 v[164:167], v164 offset:3072
	ds_read_b128 v[168:171], v180
	ds_read_b128 v[172:175], v180 offset:1024
	ds_read_b128 v[176:179], v180 offset:2048
	ds_read_b128 v[180:183], v180 offset:3072
	s_add_u32 s26, s26, 0x40000
	s_addc_u32 s27, s27, 0
	s_mov_b32 m0, s38
	v_lshl_add_u64 v[222:223], s[26:27], 0, v[134:135]
	ds_read_b128 v[184:187], v151 offset:32768
	ds_read_b128 v[188:191], v151 offset:33792
	ds_read_b128 v[192:195], v151 offset:34816
	ds_read_b128 v[196:199], v151 offset:35840
	ds_read_b128 v[200:203], v151 offset:36864
	ds_read_b128 v[204:207], v151 offset:37888
	ds_read_b128 v[208:211], v151 offset:38912
	ds_read_b128 v[212:215], v151 offset:39936
	global_load_lds_dwordx4 v[222:223], off
	v_lshl_add_u64 v[222:223], s[26:27], 0, v[130:131]
	s_mov_b32 m0, s39
	s_nop 0
	global_load_lds_dwordx4 v[222:223], off
	s_waitcnt vmcnt(8)
	s_waitcnt lgkmcnt(0)
	s_barrier
	s_waitcnt lgkmcnt(0)
	v_mfma_f32_16x16x32_bf16 v[124:127], v[152:155], v[184:187], v[124:127]
	v_mfma_f32_16x16x32_bf16 v[120:123], v[160:163], v[184:187], v[120:123]
	v_mfma_f32_16x16x32_bf16 v[108:111], v[152:155], v[192:195], v[108:111]
	v_mfma_f32_16x16x32_bf16 v[104:107], v[160:163], v[192:195], v[104:107]
	v_mfma_f32_16x16x32_bf16 v[92:95], v[152:155], v[200:203], v[92:95]
	v_mfma_f32_16x16x32_bf16 v[88:91], v[160:163], v[200:203], v[88:91]
	v_mfma_f32_16x16x32_bf16 v[76:79], v[152:155], v[208:211], v[76:79]
	v_mfma_f32_16x16x32_bf16 v[72:75], v[160:163], v[208:211], v[72:75]
	v_mfma_f32_16x16x32_bf16 v[124:127], v[156:159], v[188:191], v[124:127]
	v_mfma_f32_16x16x32_bf16 v[120:123], v[164:167], v[188:191], v[120:123]
	v_mfma_f32_16x16x32_bf16 v[108:111], v[156:159], v[196:199], v[108:111]
	v_mfma_f32_16x16x32_bf16 v[104:107], v[164:167], v[196:199], v[104:107]
	v_mfma_f32_16x16x32_bf16 v[92:95], v[156:159], v[204:207], v[92:95]
	v_mfma_f32_16x16x32_bf16 v[88:91], v[164:167], v[204:207], v[88:91]
	v_mfma_f32_16x16x32_bf16 v[76:79], v[156:159], v[212:215], v[76:79]
	v_mfma_f32_16x16x32_bf16 v[72:75], v[164:167], v[212:215], v[72:75]
	v_mfma_f32_16x16x32_bf16 v[116:119], v[168:171], v[184:187], v[116:119]
	v_mfma_f32_16x16x32_bf16 v[112:115], v[176:179], v[184:187], v[112:115]
	v_mfma_f32_16x16x32_bf16 v[100:103], v[168:171], v[192:195], v[100:103]
	v_mfma_f32_16x16x32_bf16 v[96:99], v[176:179], v[192:195], v[96:99]
	v_mfma_f32_16x16x32_bf16 v[84:87], v[168:171], v[200:203], v[84:87]
	v_mfma_f32_16x16x32_bf16 v[80:83], v[176:179], v[200:203], v[80:83]
	v_mfma_f32_16x16x32_bf16 v[68:71], v[168:171], v[208:211], v[68:71]
	v_mfma_f32_16x16x32_bf16 v[64:67], v[176:179], v[208:211], v[64:67]
	v_mfma_f32_16x16x32_bf16 v[116:119], v[172:175], v[188:191], v[116:119]
	v_mfma_f32_16x16x32_bf16 v[112:115], v[180:183], v[188:191], v[112:115]
	v_mfma_f32_16x16x32_bf16 v[100:103], v[172:175], v[196:199], v[100:103]
	v_mfma_f32_16x16x32_bf16 v[96:99], v[180:183], v[196:199], v[96:99]
	v_mfma_f32_16x16x32_bf16 v[84:87], v[172:175], v[204:207], v[84:87]
	v_mfma_f32_16x16x32_bf16 v[80:83], v[180:183], v[204:207], v[80:83]
	v_mfma_f32_16x16x32_bf16 v[68:71], v[172:175], v[212:215], v[68:71]
	v_mfma_f32_16x16x32_bf16 v[64:67], v[180:183], v[212:215], v[64:67]
	s_barrier
	s_add_i32 s26, s59, s33
	v_lshl_add_u64 v[146:147], v[146:147], 0, s[8:9]
	s_mov_b32 m0, s26
	ds_read_b128 v[184:187], v151 offset:49152
	ds_read_b128 v[188:191], v151 offset:50176
	ds_read_b128 v[192:195], v151 offset:51200
	ds_read_b128 v[196:199], v151 offset:52224
	ds_read_b128 v[200:203], v151 offset:53248
	ds_read_b128 v[204:207], v151 offset:54272
	ds_read_b128 v[208:211], v151 offset:55296
	ds_read_b128 v[212:215], v151 offset:56320
	global_load_lds_dwordx4 v[146:147], off
	s_add_i32 m0, s26, 0x2000
	s_add_u32 s24, s24, 0x40080
	v_lshl_add_u64 v[146:147], v[216:217], 0, s[8:9]
	s_addc_u32 s25, s25, 0
	s_add_i32 s26, s60, s33
	global_load_lds_dwordx4 v[146:147], off
	v_lshl_add_u64 v[146:147], s[24:25], 0, v[132:133]
	s_mov_b32 m0, s26
	s_nop 0
	global_load_lds_dwordx4 v[146:147], off
	v_lshl_add_u64 v[146:147], s[24:25], 0, v[128:129]
	s_add_i32 m0, s26, 0x2000
	s_nop 0
	global_load_lds_dwordx4 v[146:147], off
	v_lshl_add_u64 v[146:147], v[218:219], 0, s[8:9]
	s_mov_b32 m0, s41
	s_nop 0
	global_load_lds_dwordx4 v[146:147], off
	v_lshl_add_u64 v[146:147], v[220:221], 0, s[8:9]
	s_mov_b32 m0, s42
	s_nop 0
	global_load_lds_dwordx4 v[146:147], off
	s_waitcnt vmcnt(8)
	s_waitcnt lgkmcnt(0)
	s_barrier
	s_waitcnt lgkmcnt(0)
	v_mfma_f32_16x16x32_bf16 v[60:63], v[152:155], v[184:187], v[60:63]
	v_mfma_f32_16x16x32_bf16 v[56:59], v[160:163], v[184:187], v[56:59]
	v_mfma_f32_16x16x32_bf16 v[44:47], v[152:155], v[192:195], v[44:47]
	v_mfma_f32_16x16x32_bf16 v[40:43], v[160:163], v[192:195], v[40:43]
	v_mfma_f32_16x16x32_bf16 v[28:31], v[152:155], v[200:203], v[28:31]
	v_mfma_f32_16x16x32_bf16 v[24:27], v[160:163], v[200:203], v[24:27]
	v_mfma_f32_16x16x32_bf16 v[12:15], v[152:155], v[208:211], v[12:15]
	v_mfma_f32_16x16x32_bf16 v[8:11], v[160:163], v[208:211], v[8:11]
	v_mfma_f32_16x16x32_bf16 v[60:63], v[156:159], v[188:191], v[60:63]
	v_mfma_f32_16x16x32_bf16 v[56:59], v[164:167], v[188:191], v[56:59]
	v_mfma_f32_16x16x32_bf16 v[44:47], v[156:159], v[196:199], v[44:47]
	v_mfma_f32_16x16x32_bf16 v[40:43], v[164:167], v[196:199], v[40:43]
	v_mfma_f32_16x16x32_bf16 v[28:31], v[156:159], v[204:207], v[28:31]
	v_mfma_f32_16x16x32_bf16 v[24:27], v[164:167], v[204:207], v[24:27]
	v_mfma_f32_16x16x32_bf16 v[12:15], v[156:159], v[212:215], v[12:15]
	v_mfma_f32_16x16x32_bf16 v[8:11], v[164:167], v[212:215], v[8:11]
	v_mfma_f32_16x16x32_bf16 v[52:55], v[168:171], v[184:187], v[52:55]
	v_mfma_f32_16x16x32_bf16 v[48:51], v[176:179], v[184:187], v[48:51]
	v_mfma_f32_16x16x32_bf16 v[36:39], v[168:171], v[192:195], v[36:39]
	v_mfma_f32_16x16x32_bf16 v[32:35], v[176:179], v[192:195], v[32:35]
	v_mfma_f32_16x16x32_bf16 v[20:23], v[168:171], v[200:203], v[20:23]
	v_mfma_f32_16x16x32_bf16 v[16:19], v[176:179], v[200:203], v[16:19]
	v_mfma_f32_16x16x32_bf16 v[4:7], v[168:171], v[208:211], v[4:7]
	v_mfma_f32_16x16x32_bf16 v[0:3], v[176:179], v[208:211], v[0:3]
	v_mfma_f32_16x16x32_bf16 v[52:55], v[172:175], v[188:191], v[52:55]
	v_mfma_f32_16x16x32_bf16 v[48:51], v[180:183], v[188:191], v[48:51]
	v_mfma_f32_16x16x32_bf16 v[36:39], v[172:175], v[196:199], v[36:39]
	v_mfma_f32_16x16x32_bf16 v[32:35], v[180:183], v[196:199], v[32:35]
	v_mfma_f32_16x16x32_bf16 v[20:23], v[172:175], v[204:207], v[20:23]
	v_mfma_f32_16x16x32_bf16 v[16:19], v[180:183], v[204:207], v[16:19]
	v_mfma_f32_16x16x32_bf16 v[4:7], v[172:175], v[212:215], v[4:7]
	v_mfma_f32_16x16x32_bf16 v[0:3], v[180:183], v[212:215], v[0:3]
	s_add_i32 s58, s58, 2
	s_add_u32 s56, s56, 0x100
	s_addc_u32 s57, s57, 0
	s_add_u32 s22, s22, 0x100
	s_addc_u32 s23, s23, 0
	s_cmp_lt_u32 s58, 14
	s_barrier
	s_cbranch_scc1 .LBB12_9
	s_andn2_b64 vcc, exec, s[10:11]
	s_cbranch_vccnz .LBB12_12
	s_barrier

.LBB13_19:
	s_ashr_i32 s17, s16, 31
	v_cmp_lt_i64_e32 vcc, s[0:1], v[142:143]
	s_lshl_b64 s[0:1], s[16:17], 21
	s_add_u32 s18, s33, s0
	s_addc_u32 s19, s34, s1
	s_and_b64 s[0:1], vcc, exec
	s_cselect_b32 s17, s19, s27
	s_cselect_b32 s53, s18, s26
	s_ashr_i32 s15, s14, 31
	s_lshl_b64 s[0:1], s[14:15], 21
	s_add_u32 s20, s4, s0
	s_addc_u32 s21, s5, s1
	s_and_b64 s[0:1], vcc, exec
	s_cselect_b32 s15, s21, s25
	s_cselect_b32 s54, s20, s24
	s_add_u32 s55, s24, 0x100
	s_addc_u32 s56, s25, 0
	s_add_u32 s24, s26, 0x100080
	s_addc_u32 s25, s27, 0
	s_mov_b32 s57, -2
	ds_read_b128 v[152:155], v149
	ds_read_b128 v[156:159], v149 offset:1024
	ds_read_b128 v[160:163], v149 offset:2048
	ds_read_b128 v[164:167], v149 offset:3072
	ds_read_b128 v[168:171], v150
	ds_read_b128 v[172:175], v150 offset:1024
	ds_read_b128 v[176:179], v150 offset:2048
	ds_read_b128 v[180:183], v150 offset:3072
	s_add_u32 s26, s24, 0xfff00080
	s_addc_u32 s27, s25, -1
	s_cmp_eq_u32 s57, 60
	s_cselect_b32 s29, s17, s27
	s_cselect_b32 s28, s53, s26
	s_cselect_b32 s27, s15, s56
	s_cselect_b32 s26, s54, s55
	v_lshl_add_u64 v[146:147], s[24:25], 0, v[140:141]
	s_add_i32 m0, s35, 0xc000
	ds_read_b128 v[184:187], v151
	ds_read_b128 v[188:191], v151 offset:1024
	ds_read_b128 v[192:195], v151 offset:2048
	ds_read_b128 v[196:199], v151 offset:3072
	ds_read_b128 v[200:203], v151 offset:4096
	ds_read_b128 v[204:207], v151 offset:5120
	ds_read_b128 v[208:211], v151 offset:6144
	ds_read_b128 v[212:215], v151 offset:7168
	global_load_lds_dwordx4 v[146:147], off
	v_lshl_add_u64 v[146:147], s[24:25], 0, v[138:139]
	s_add_i32 m0, s35, 0xe000
	s_nop 0
	global_load_lds_dwordx4 v[146:147], off
	s_waitcnt vmcnt(8)
	s_waitcnt lgkmcnt(0)
	s_barrier
	s_waitcnt lgkmcnt(0)
	v_mfma_f32_16x16x32_bf16 v[124:127], v[152:155], v[184:187], 0
	v_mfma_f32_16x16x32_bf16 v[120:123], v[160:163], v[184:187], 0
	v_mfma_f32_16x16x32_bf16 v[116:119], v[152:155], v[192:195], 0
	v_mfma_f32_16x16x32_bf16 v[108:111], v[160:163], v[192:195], 0
	v_mfma_f32_16x16x32_bf16 v[100:103], v[152:155], v[200:203], 0
	v_mfma_f32_16x16x32_bf16 v[92:95], v[160:163], v[200:203], 0
	v_mfma_f32_16x16x32_bf16 v[84:87], v[152:155], v[208:211], 0
	v_mfma_f32_16x16x32_bf16 v[76:79], v[160:163], v[208:211], 0
	v_mfma_f32_16x16x32_bf16 v[124:127], v[156:159], v[188:191], v[124:127]
	v_mfma_f32_16x16x32_bf16 v[120:123], v[164:167], v[188:191], v[120:123]
	v_mfma_f32_16x16x32_bf16 v[116:119], v[156:159], v[196:199], v[116:119]
	v_mfma_f32_16x16x32_bf16 v[108:111], v[164:167], v[196:199], v[108:111]
	v_mfma_f32_16x16x32_bf16 v[100:103], v[156:159], v[204:207], v[100:103]
	v_mfma_f32_16x16x32_bf16 v[92:95], v[164:167], v[204:207], v[92:95]
	v_mfma_f32_16x16x32_bf16 v[84:87], v[156:159], v[212:215], v[84:87]
	v_mfma_f32_16x16x32_bf16 v[76:79], v[164:167], v[212:215], v[76:79]
	v_mfma_f32_16x16x32_bf16 v[112:115], v[168:171], v[184:187], 0
	v_mfma_f32_16x16x32_bf16 v[104:107], v[176:179], v[184:187], 0
	v_mfma_f32_16x16x32_bf16 v[96:99], v[168:171], v[192:195], 0
	v_mfma_f32_16x16x32_bf16 v[88:91], v[176:179], v[192:195], 0
	v_mfma_f32_16x16x32_bf16 v[80:83], v[168:171], v[200:203], 0
	v_mfma_f32_16x16x32_bf16 v[72:75], v[176:179], v[200:203], 0
	v_mfma_f32_16x16x32_bf16 v[68:71], v[168:171], v[208:211], 0
	v_mfma_f32_16x16x32_bf16 v[64:67], v[176:179], v[208:211], 0
	v_mfma_f32_16x16x32_bf16 v[112:115], v[172:175], v[188:191], v[112:115]
	v_mfma_f32_16x16x32_bf16 v[104:107], v[180:183], v[188:191], v[104:107]
	v_mfma_f32_16x16x32_bf16 v[96:99], v[172:175], v[196:199], v[96:99]
	v_mfma_f32_16x16x32_bf16 v[88:91], v[180:183], v[196:199], v[88:91]
	v_mfma_f32_16x16x32_bf16 v[80:83], v[172:175], v[204:207], v[80:83]
	v_mfma_f32_16x16x32_bf16 v[72:75], v[180:183], v[204:207], v[72:75]
	v_mfma_f32_16x16x32_bf16 v[68:71], v[172:175], v[212:215], v[68:71]
	v_mfma_f32_16x16x32_bf16 v[64:67], v[180:183], v[212:215], v[64:67]
	s_barrier
	s_add_i32 s58, s46, s31
	v_lshl_add_u64 v[146:147], s[26:27], 0, v[130:131]
	s_mov_b32 m0, s58
	ds_read_b128 v[184:187], v151 offset:16384
	ds_read_b128 v[188:191], v151 offset:17408
	ds_read_b128 v[192:195], v151 offset:18432
	ds_read_b128 v[196:199], v151 offset:19456
	ds_read_b128 v[200:203], v151 offset:20480
	ds_read_b128 v[204:207], v151 offset:21504
	ds_read_b128 v[208:211], v151 offset:22528
	ds_read_b128 v[212:215], v151 offset:23552
	global_load_lds_dwordx4 v[146:147], off
	s_add_i32 m0, s58, 0x2000
	s_add_u32 s58, s26, 0x100000
	v_lshl_add_u64 v[216:217], s[26:27], 0, v[134:135]
	s_addc_u32 s59, s27, 0
	s_add_i32 s60, s47, s31
	global_load_lds_dwordx4 v[216:217], off
	v_lshl_add_u64 v[218:219], s[58:59], 0, v[130:131]
	s_mov_b32 m0, s60
	v_lshl_add_u64 v[220:221], s[28:29], 0, v[132:133]
	global_load_lds_dwordx4 v[218:219], off
	v_lshl_add_u64 v[218:219], s[58:59], 0, v[134:135]
	s_add_i32 m0, s60, 0x2000
	s_nop 0
	global_load_lds_dwordx4 v[218:219], off
	v_lshl_add_u64 v[218:219], s[28:29], 0, v[128:129]
	s_mov_b32 m0, s35
	s_nop 0
	global_load_lds_dwordx4 v[218:219], off
	s_mov_b32 m0, s36
	s_nop 0
	global_load_lds_dwordx4 v[220:221], off
	s_waitcnt vmcnt(8)
	s_waitcnt lgkmcnt(0)
	s_barrier
	s_waitcnt lgkmcnt(0)
	v_mfma_f32_16x16x32_bf16 v[60:63], v[152:155], v[184:187], 0
	v_mfma_f32_16x16x32_bf16 v[56:59], v[160:163], v[184:187], 0
	v_mfma_f32_16x16x32_bf16 v[52:55], v[152:155], v[192:195], 0
	v_mfma_f32_16x16x32_bf16 v[44:47], v[160:163], v[192:195], 0
	v_mfma_f32_16x16x32_bf16 v[36:39], v[152:155], v[200:203], 0
	v_mfma_f32_16x16x32_bf16 v[28:31], v[160:163], v[200:203], 0
	v_mfma_f32_16x16x32_bf16 v[20:23], v[152:155], v[208:211], 0
	v_mfma_f32_16x16x32_bf16 v[12:15], v[160:163], v[208:211], 0
	v_mfma_f32_16x16x32_bf16 v[60:63], v[156:159], v[188:191], v[60:63]
	v_mfma_f32_16x16x32_bf16 v[56:59], v[164:167], v[188:191], v[56:59]
	v_mfma_f32_16x16x32_bf16 v[52:55], v[156:159], v[196:199], v[52:55]
	v_mfma_f32_16x16x32_bf16 v[44:47], v[164:167], v[196:199], v[44:47]
	v_mfma_f32_16x16x32_bf16 v[36:39], v[156:159], v[204:207], v[36:39]
	v_mfma_f32_16x16x32_bf16 v[28:31], v[164:167], v[204:207], v[28:31]
	v_mfma_f32_16x16x32_bf16 v[20:23], v[156:159], v[212:215], v[20:23]
	v_mfma_f32_16x16x32_bf16 v[12:15], v[164:167], v[212:215], v[12:15]
	v_mfma_f32_16x16x32_bf16 v[48:51], v[168:171], v[184:187], 0
	v_mfma_f32_16x16x32_bf16 v[40:43], v[176:179], v[184:187], 0
	v_mfma_f32_16x16x32_bf16 v[32:35], v[168:171], v[192:195], 0
	v_mfma_f32_16x16x32_bf16 v[24:27], v[176:179], v[192:195], 0
	v_mfma_f32_16x16x32_bf16 v[16:19], v[168:171], v[200:203], 0
	v_mfma_f32_16x16x32_bf16 v[8:11], v[176:179], v[200:203], 0
	v_mfma_f32_16x16x32_bf16 v[4:7], v[168:171], v[208:211], 0
	v_mfma_f32_16x16x32_bf16 v[0:3], v[176:179], v[208:211], 0
	v_mfma_f32_16x16x32_bf16 v[48:51], v[172:175], v[188:191], v[48:51]
	v_mfma_f32_16x16x32_bf16 v[40:43], v[180:183], v[188:191], v[40:43]
	v_mfma_f32_16x16x32_bf16 v[32:35], v[172:175], v[196:199], v[32:35]
	v_mfma_f32_16x16x32_bf16 v[24:27], v[180:183], v[196:199], v[24:27]
	v_mfma_f32_16x16x32_bf16 v[16:19], v[172:175], v[204:207], v[16:19]
	v_mfma_f32_16x16x32_bf16 v[8:11], v[180:183], v[204:207], v[8:11]
	v_mfma_f32_16x16x32_bf16 v[4:7], v[172:175], v[212:215], v[4:7]
	v_mfma_f32_16x16x32_bf16 v[0:3], v[180:183], v[212:215], v[0:3]
	s_barrier
	s_add_i32 s58, 0, 0x18000
	s_add_i32 s59, 0, 0x1c000
	v_add_u32_e32 v164, s58, v148
	v_add_u32_e32 v180, s59, v148
	ds_read_b128 v[152:155], v164
	ds_read_b128 v[156:159], v164 offset:1024
	ds_read_b128 v[160:163], v164 offset:2048
	ds_read_b128 v[164:167], v164 offset:3072
	ds_read_b128 v[168:171], v180
	ds_read_b128 v[172:175], v180 offset:1024
	ds_read_b128 v[176:179], v180 offset:2048
	ds_read_b128 v[180:183], v180 offset:3072
	s_add_u32 s28, s28, 0x100000
	s_addc_u32 s29, s29, 0
	s_mov_b32 m0, s37
	v_lshl_add_u64 v[222:223], s[28:29], 0, v[128:129]
	ds_read_b128 v[184:187], v151 offset:32768
	ds_read_b128 v[188:191], v151 offset:33792
	ds_read_b128 v[192:195], v151 offset:34816
	ds_read_b128 v[196:199], v151 offset:35840
	ds_read_b128 v[200:203], v151 offset:36864
	ds_read_b128 v[204:207], v151 offset:37888
	ds_read_b128 v[208:211], v151 offset:38912
	ds_read_b128 v[212:215], v151 offset:39936
	global_load_lds_dwordx4 v[222:223], off
	v_lshl_add_u64 v[222:223], s[28:29], 0, v[132:133]
	s_mov_b32 m0, s38
	s_nop 0
	global_load_lds_dwordx4 v[222:223], off
	s_waitcnt vmcnt(8)
	s_waitcnt lgkmcnt(0)
	s_barrier
	s_waitcnt lgkmcnt(0)
	v_mfma_f32_16x16x32_bf16 v[124:127], v[152:155], v[184:187], v[124:127]
	v_mfma_f32_16x16x32_bf16 v[120:123], v[160:163], v[184:187], v[120:123]
	v_mfma_f32_16x16x32_bf16 v[116:119], v[152:155], v[192:195], v[116:119]
	v_mfma_f32_16x16x32_bf16 v[108:111], v[160:163], v[192:195], v[108:111]
	v_mfma_f32_16x16x32_bf16 v[100:103], v[152:155], v[200:203], v[100:103]
	v_mfma_f32_16x16x32_bf16 v[92:95], v[160:163], v[200:203], v[92:95]
	v_mfma_f32_16x16x32_bf16 v[84:87], v[152:155], v[208:211], v[84:87]
	v_mfma_f32_16x16x32_bf16 v[76:79], v[160:163], v[208:211], v[76:79]
	v_mfma_f32_16x16x32_bf16 v[124:127], v[156:159], v[188:191], v[124:127]
	v_mfma_f32_16x16x32_bf16 v[120:123], v[164:167], v[188:191], v[120:123]
	v_mfma_f32_16x16x32_bf16 v[116:119], v[156:159], v[196:199], v[116:119]
	v_mfma_f32_16x16x32_bf16 v[108:111], v[164:167], v[196:199], v[108:111]
	v_mfma_f32_16x16x32_bf16 v[100:103], v[156:159], v[204:207], v[100:103]
	v_mfma_f32_16x16x32_bf16 v[92:95], v[164:167], v[204:207], v[92:95]
	v_mfma_f32_16x16x32_bf16 v[84:87], v[156:159], v[212:215], v[84:87]
	v_mfma_f32_16x16x32_bf16 v[76:79], v[164:167], v[212:215], v[76:79]
	v_mfma_f32_16x16x32_bf16 v[112:115], v[168:171], v[184:187], v[112:115]
	v_mfma_f32_16x16x32_bf16 v[104:107], v[176:179], v[184:187], v[104:107]
	v_mfma_f32_16x16x32_bf16 v[96:99], v[168:171], v[192:195], v[96:99]
	v_mfma_f32_16x16x32_bf16 v[88:91], v[176:179], v[192:195], v[88:91]
	v_mfma_f32_16x16x32_bf16 v[80:83], v[168:171], v[200:203], v[80:83]
	v_mfma_f32_16x16x32_bf16 v[72:75], v[176:179], v[200:203], v[72:75]
	v_mfma_f32_16x16x32_bf16 v[68:71], v[168:171], v[208:211], v[68:71]
	v_mfma_f32_16x16x32_bf16 v[64:67], v[176:179], v[208:211], v[64:67]
	v_mfma_f32_16x16x32_bf16 v[112:115], v[172:175], v[188:191], v[112:115]
	v_mfma_f32_16x16x32_bf16 v[104:107], v[180:183], v[188:191], v[104:107]
	v_mfma_f32_16x16x32_bf16 v[96:99], v[172:175], v[196:199], v[96:99]
	v_mfma_f32_16x16x32_bf16 v[88:91], v[180:183], v[196:199], v[88:91]
	v_mfma_f32_16x16x32_bf16 v[80:83], v[172:175], v[204:207], v[80:83]
	v_mfma_f32_16x16x32_bf16 v[72:75], v[180:183], v[204:207], v[72:75]
	v_mfma_f32_16x16x32_bf16 v[68:71], v[172:175], v[212:215], v[68:71]
	v_mfma_f32_16x16x32_bf16 v[64:67], v[180:183], v[212:215], v[64:67]
	s_barrier
	s_add_i32 s28, s58, s31
	v_lshl_add_u64 v[146:147], v[146:147], 0, s[10:11]
	s_mov_b32 m0, s28
	ds_read_b128 v[184:187], v151 offset:49152
	ds_read_b128 v[188:191], v151 offset:50176
	ds_read_b128 v[192:195], v151 offset:51200
	ds_read_b128 v[196:199], v151 offset:52224
	ds_read_b128 v[200:203], v151 offset:53248
	ds_read_b128 v[204:207], v151 offset:54272
	ds_read_b128 v[208:211], v151 offset:55296
	ds_read_b128 v[212:215], v151 offset:56320
	global_load_lds_dwordx4 v[146:147], off
	s_add_i32 m0, s28, 0x2000
	s_add_u32 s26, s26, 0x100080
	v_lshl_add_u64 v[146:147], v[216:217], 0, s[10:11]
	s_addc_u32 s27, s27, 0
	s_add_i32 s28, s59, s31
	global_load_lds_dwordx4 v[146:147], off
	v_lshl_add_u64 v[146:147], s[26:27], 0, v[130:131]
	s_mov_b32 m0, s28
	s_nop 0
	global_load_lds_dwordx4 v[146:147], off
	v_lshl_add_u64 v[146:147], s[26:27], 0, v[134:135]
	s_add_i32 m0, s28, 0x2000
	s_nop 0
	global_load_lds_dwordx4 v[146:147], off
	v_lshl_add_u64 v[146:147], v[218:219], 0, s[10:11]
	s_mov_b32 m0, s41
	s_nop 0
	global_load_lds_dwordx4 v[146:147], off
	v_lshl_add_u64 v[146:147], v[220:221], 0, s[10:11]
	s_mov_b32 m0, s42
	s_nop 0
	global_load_lds_dwordx4 v[146:147], off
	s_waitcnt vmcnt(8)
	s_waitcnt lgkmcnt(0)
	s_barrier
	s_waitcnt lgkmcnt(0)
	v_mfma_f32_16x16x32_bf16 v[60:63], v[152:155], v[184:187], v[60:63]
	v_mfma_f32_16x16x32_bf16 v[56:59], v[160:163], v[184:187], v[56:59]
	v_mfma_f32_16x16x32_bf16 v[52:55], v[152:155], v[192:195], v[52:55]
	v_mfma_f32_16x16x32_bf16 v[44:47], v[160:163], v[192:195], v[44:47]
	v_mfma_f32_16x16x32_bf16 v[36:39], v[152:155], v[200:203], v[36:39]
	v_mfma_f32_16x16x32_bf16 v[28:31], v[160:163], v[200:203], v[28:31]
	v_mfma_f32_16x16x32_bf16 v[20:23], v[152:155], v[208:211], v[20:23]
	v_mfma_f32_16x16x32_bf16 v[12:15], v[160:163], v[208:211], v[12:15]
	v_mfma_f32_16x16x32_bf16 v[60:63], v[156:159], v[188:191], v[60:63]
	v_mfma_f32_16x16x32_bf16 v[56:59], v[164:167], v[188:191], v[56:59]
	v_mfma_f32_16x16x32_bf16 v[52:55], v[156:159], v[196:199], v[52:55]
	v_mfma_f32_16x16x32_bf16 v[44:47], v[164:167], v[196:199], v[44:47]
	v_mfma_f32_16x16x32_bf16 v[36:39], v[156:159], v[204:207], v[36:39]
	v_mfma_f32_16x16x32_bf16 v[28:31], v[164:167], v[204:207], v[28:31]
	v_mfma_f32_16x16x32_bf16 v[20:23], v[156:159], v[212:215], v[20:23]
	v_mfma_f32_16x16x32_bf16 v[12:15], v[164:167], v[212:215], v[12:15]
	v_mfma_f32_16x16x32_bf16 v[48:51], v[168:171], v[184:187], v[48:51]
	v_mfma_f32_16x16x32_bf16 v[40:43], v[176:179], v[184:187], v[40:43]
	v_mfma_f32_16x16x32_bf16 v[32:35], v[168:171], v[192:195], v[32:35]
	v_mfma_f32_16x16x32_bf16 v[24:27], v[176:179], v[192:195], v[24:27]
	v_mfma_f32_16x16x32_bf16 v[16:19], v[168:171], v[200:203], v[16:19]
	v_mfma_f32_16x16x32_bf16 v[8:11], v[176:179], v[200:203], v[8:11]
	v_mfma_f32_16x16x32_bf16 v[4:7], v[168:171], v[208:211], v[4:7]
	v_mfma_f32_16x16x32_bf16 v[0:3], v[176:179], v[208:211], v[0:3]
	v_mfma_f32_16x16x32_bf16 v[48:51], v[172:175], v[188:191], v[48:51]
	v_mfma_f32_16x16x32_bf16 v[40:43], v[180:183], v[188:191], v[40:43]
	v_mfma_f32_16x16x32_bf16 v[32:35], v[172:175], v[196:199], v[32:35]
	v_mfma_f32_16x16x32_bf16 v[24:27], v[180:183], v[196:199], v[24:27]
	v_mfma_f32_16x16x32_bf16 v[16:19], v[172:175], v[204:207], v[16:19]
	v_mfma_f32_16x16x32_bf16 v[8:11], v[180:183], v[204:207], v[8:11]
	v_mfma_f32_16x16x32_bf16 v[4:7], v[172:175], v[212:215], v[4:7]
	v_mfma_f32_16x16x32_bf16 v[0:3], v[180:183], v[212:215], v[0:3]
	s_add_i32 s57, s57, 2
	s_add_u32 s55, s55, 0x100
	s_addc_u32 s56, s56, 0
	s_add_u32 s24, s24, 0x100
	s_addc_u32 s25, s25, 0
	s_cmp_lt_u32 s57, 62
	s_barrier
.LBB13_20:
	ds_read_b128 v[152:155], v149
	ds_read_b128 v[156:159], v149 offset:1024
	ds_read_b128 v[160:163], v149 offset:2048
	ds_read_b128 v[164:167], v149 offset:3072
	ds_read_b128 v[168:171], v150
	ds_read_b128 v[172:175], v150 offset:1024
	ds_read_b128 v[176:179], v150 offset:2048
	ds_read_b128 v[180:183], v150 offset:3072
	s_add_u32 s26, s24, 0xfff00080
	s_addc_u32 s27, s25, -1
	s_cmp_eq_u32 s57, 60
	s_cselect_b32 s29, s17, s27
	s_cselect_b32 s28, s53, s26
	s_cselect_b32 s27, s15, s56
	s_cselect_b32 s26, s54, s55
	v_lshl_add_u64 v[146:147], s[24:25], 0, v[140:141]
	s_add_i32 m0, s35, 0xc000
	ds_read_b128 v[184:187], v151
	ds_read_b128 v[188:191], v151 offset:1024
	ds_read_b128 v[192:195], v151 offset:2048
	ds_read_b128 v[196:199], v151 offset:3072
	ds_read_b128 v[200:203], v151 offset:4096
	ds_read_b128 v[204:207], v151 offset:5120
	ds_read_b128 v[208:211], v151 offset:6144
	ds_read_b128 v[212:215], v151 offset:7168
	global_load_lds_dwordx4 v[146:147], off
	v_lshl_add_u64 v[146:147], s[24:25], 0, v[138:139]
	s_add_i32 m0, s35, 0xe000
	s_nop 0
	global_load_lds_dwordx4 v[146:147], off
	s_waitcnt vmcnt(8)
	s_waitcnt lgkmcnt(0)
	s_barrier
	s_waitcnt lgkmcnt(0)
	v_mfma_f32_16x16x32_bf16 v[124:127], v[152:155], v[184:187], v[124:127]
	v_mfma_f32_16x16x32_bf16 v[120:123], v[160:163], v[184:187], v[120:123]
	v_mfma_f32_16x16x32_bf16 v[116:119], v[152:155], v[192:195], v[116:119]
	v_mfma_f32_16x16x32_bf16 v[108:111], v[160:163], v[192:195], v[108:111]
	v_mfma_f32_16x16x32_bf16 v[100:103], v[152:155], v[200:203], v[100:103]
	v_mfma_f32_16x16x32_bf16 v[92:95], v[160:163], v[200:203], v[92:95]
	v_mfma_f32_16x16x32_bf16 v[84:87], v[152:155], v[208:211], v[84:87]
	v_mfma_f32_16x16x32_bf16 v[76:79], v[160:163], v[208:211], v[76:79]
	v_mfma_f32_16x16x32_bf16 v[124:127], v[156:159], v[188:191], v[124:127]
	v_mfma_f32_16x16x32_bf16 v[120:123], v[164:167], v[188:191], v[120:123]
	v_mfma_f32_16x16x32_bf16 v[116:119], v[156:159], v[196:199], v[116:119]
	v_mfma_f32_16x16x32_bf16 v[108:111], v[164:167], v[196:199], v[108:111]
	v_mfma_f32_16x16x32_bf16 v[100:103], v[156:159], v[204:207], v[100:103]
	v_mfma_f32_16x16x32_bf16 v[92:95], v[164:167], v[204:207], v[92:95]
	v_mfma_f32_16x16x32_bf16 v[84:87], v[156:159], v[212:215], v[84:87]
	v_mfma_f32_16x16x32_bf16 v[76:79], v[164:167], v[212:215], v[76:79]
	v_mfma_f32_16x16x32_bf16 v[112:115], v[168:171], v[184:187], v[112:115]
	v_mfma_f32_16x16x32_bf16 v[104:107], v[176:179], v[184:187], v[104:107]
	v_mfma_f32_16x16x32_bf16 v[96:99], v[168:171], v[192:195], v[96:99]
	v_mfma_f32_16x16x32_bf16 v[88:91], v[176:179], v[192:195], v[88:91]
	v_mfma_f32_16x16x32_bf16 v[80:83], v[168:171], v[200:203], v[80:83]
	v_mfma_f32_16x16x32_bf16 v[72:75], v[176:179], v[200:203], v[72:75]
	v_mfma_f32_16x16x32_bf16 v[68:71], v[168:171], v[208:211], v[68:71]
	v_mfma_f32_16x16x32_bf16 v[64:67], v[176:179], v[208:211], v[64:67]
	v_mfma_f32_16x16x32_bf16 v[112:115], v[172:175], v[188:191], v[112:115]
	v_mfma_f32_16x16x32_bf16 v[104:107], v[180:183], v[188:191], v[104:107]
	v_mfma_f32_16x16x32_bf16 v[96:99], v[172:175], v[196:199], v[96:99]
	v_mfma_f32_16x16x32_bf16 v[88:91], v[180:183], v[196:199], v[88:91]
	v_mfma_f32_16x16x32_bf16 v[80:83], v[172:175], v[204:207], v[80:83]
	v_mfma_f32_16x16x32_bf16 v[72:75], v[180:183], v[204:207], v[72:75]
	v_mfma_f32_16x16x32_bf16 v[68:71], v[172:175], v[212:215], v[68:71]
	v_mfma_f32_16x16x32_bf16 v[64:67], v[180:183], v[212:215], v[64:67]
	s_barrier
	s_add_i32 s58, s46, s31
	v_lshl_add_u64 v[146:147], s[26:27], 0, v[130:131]
	s_mov_b32 m0, s58
	ds_read_b128 v[184:187], v151 offset:16384
	ds_read_b128 v[188:191], v151 offset:17408
	ds_read_b128 v[192:195], v151 offset:18432
	ds_read_b128 v[196:199], v151 offset:19456
	ds_read_b128 v[200:203], v151 offset:20480
	ds_read_b128 v[204:207], v151 offset:21504
	ds_read_b128 v[208:211], v151 offset:22528
	ds_read_b128 v[212:215], v151 offset:23552
	global_load_lds_dwordx4 v[146:147], off
	s_add_i32 m0, s58, 0x2000
	s_add_u32 s58, s26, 0x100000
	v_lshl_add_u64 v[216:217], s[26:27], 0, v[134:135]
	s_addc_u32 s59, s27, 0
	s_add_i32 s60, s47, s31
	global_load_lds_dwordx4 v[216:217], off
	v_lshl_add_u64 v[218:219], s[58:59], 0, v[130:131]
	s_mov_b32 m0, s60
	v_lshl_add_u64 v[220:221], s[28:29], 0, v[132:133]
	global_load_lds_dwordx4 v[218:219], off
	v_lshl_add_u64 v[218:219], s[58:59], 0, v[134:135]
	s_add_i32 m0, s60, 0x2000
	s_nop 0
	global_load_lds_dwordx4 v[218:219], off
	v_lshl_add_u64 v[218:219], s[28:29], 0, v[128:129]
	s_mov_b32 m0, s35
	s_nop 0
	global_load_lds_dwordx4 v[218:219], off
	s_mov_b32 m0, s36
	s_nop 0
	global_load_lds_dwordx4 v[220:221], off
	s_waitcnt vmcnt(8)
	s_waitcnt lgkmcnt(0)
	s_barrier
	s_waitcnt lgkmcnt(0)
	v_mfma_f32_16x16x32_bf16 v[60:63], v[152:155], v[184:187], v[60:63]
	v_mfma_f32_16x16x32_bf16 v[56:59], v[160:163], v[184:187], v[56:59]
	v_mfma_f32_16x16x32_bf16 v[52:55], v[152:155], v[192:195], v[52:55]
	v_mfma_f32_16x16x32_bf16 v[44:47], v[160:163], v[192:195], v[44:47]
	v_mfma_f32_16x16x32_bf16 v[36:39], v[152:155], v[200:203], v[36:39]
	v_mfma_f32_16x16x32_bf16 v[28:31], v[160:163], v[200:203], v[28:31]
	v_mfma_f32_16x16x32_bf16 v[20:23], v[152:155], v[208:211], v[20:23]
	v_mfma_f32_16x16x32_bf16 v[12:15], v[160:163], v[208:211], v[12:15]
	v_mfma_f32_16x16x32_bf16 v[60:63], v[156:159], v[188:191], v[60:63]
	v_mfma_f32_16x16x32_bf16 v[56:59], v[164:167], v[188:191], v[56:59]
	v_mfma_f32_16x16x32_bf16 v[52:55], v[156:159], v[196:199], v[52:55]
	v_mfma_f32_16x16x32_bf16 v[44:47], v[164:167], v[196:199], v[44:47]
	v_mfma_f32_16x16x32_bf16 v[36:39], v[156:159], v[204:207], v[36:39]
	v_mfma_f32_16x16x32_bf16 v[28:31], v[164:167], v[204:207], v[28:31]
	v_mfma_f32_16x16x32_bf16 v[20:23], v[156:159], v[212:215], v[20:23]
	v_mfma_f32_16x16x32_bf16 v[12:15], v[164:167], v[212:215], v[12:15]
	v_mfma_f32_16x16x32_bf16 v[48:51], v[168:171], v[184:187], v[48:51]
	v_mfma_f32_16x16x32_bf16 v[40:43], v[176:179], v[184:187], v[40:43]
	v_mfma_f32_16x16x32_bf16 v[32:35], v[168:171], v[192:195], v[32:35]
	v_mfma_f32_16x16x32_bf16 v[24:27], v[176:179], v[192:195], v[24:27]
	v_mfma_f32_16x16x32_bf16 v[16:19], v[168:171], v[200:203], v[16:19]
	v_mfma_f32_16x16x32_bf16 v[8:11], v[176:179], v[200:203], v[8:11]
	v_mfma_f32_16x16x32_bf16 v[4:7], v[168:171], v[208:211], v[4:7]
	v_mfma_f32_16x16x32_bf16 v[0:3], v[176:179], v[208:211], v[0:3]
	v_mfma_f32_16x16x32_bf16 v[48:51], v[172:175], v[188:191], v[48:51]
	v_mfma_f32_16x16x32_bf16 v[40:43], v[180:183], v[188:191], v[40:43]
	v_mfma_f32_16x16x32_bf16 v[32:35], v[172:175], v[196:199], v[32:35]
	v_mfma_f32_16x16x32_bf16 v[24:27], v[180:183], v[196:199], v[24:27]
	v_mfma_f32_16x16x32_bf16 v[16:19], v[172:175], v[204:207], v[16:19]
	v_mfma_f32_16x16x32_bf16 v[8:11], v[180:183], v[204:207], v[8:11]
	v_mfma_f32_16x16x32_bf16 v[4:7], v[172:175], v[212:215], v[4:7]
	v_mfma_f32_16x16x32_bf16 v[0:3], v[180:183], v[212:215], v[0:3]
	s_barrier
	s_add_i32 s58, 0, 0x18000
	s_add_i32 s59, 0, 0x1c000
	v_add_u32_e32 v164, s58, v148
	v_add_u32_e32 v180, s59, v148
	ds_read_b128 v[152:155], v164
	ds_read_b128 v[156:159], v164 offset:1024
	ds_read_b128 v[160:163], v164 offset:2048
	ds_read_b128 v[164:167], v164 offset:3072
	ds_read_b128 v[168:171], v180
	ds_read_b128 v[172:175], v180 offset:1024
	ds_read_b128 v[176:179], v180 offset:2048
	ds_read_b128 v[180:183], v180 offset:3072
	s_add_u32 s28, s28, 0x100000
	s_addc_u32 s29, s29, 0
	s_mov_b32 m0, s37
	v_lshl_add_u64 v[222:223], s[28:29], 0, v[128:129]
	ds_read_b128 v[184:187], v151 offset:32768
	ds_read_b128 v[188:191], v151 offset:33792
	ds_read_b128 v[192:195], v151 offset:34816
	ds_read_b128 v[196:199], v151 offset:35840
	ds_read_b128 v[200:203], v151 offset:36864
	ds_read_b128 v[204:207], v151 offset:37888
	ds_read_b128 v[208:211], v151 offset:38912
	ds_read_b128 v[212:215], v151 offset:39936
	global_load_lds_dwordx4 v[222:223], off
	v_lshl_add_u64 v[222:223], s[28:29], 0, v[132:133]
	s_mov_b32 m0, s38
	s_nop 0
	global_load_lds_dwordx4 v[222:223], off
	s_waitcnt vmcnt(8)
	s_waitcnt lgkmcnt(0)
	s_barrier
	s_waitcnt lgkmcnt(0)
	v_mfma_f32_16x16x32_bf16 v[124:127], v[152:155], v[184:187], v[124:127]
	v_mfma_f32_16x16x32_bf16 v[120:123], v[160:163], v[184:187], v[120:123]
	v_mfma_f32_16x16x32_bf16 v[116:119], v[152:155], v[192:195], v[116:119]
	v_mfma_f32_16x16x32_bf16 v[108:111], v[160:163], v[192:195], v[108:111]
	v_mfma_f32_16x16x32_bf16 v[100:103], v[152:155], v[200:203], v[100:103]
	v_mfma_f32_16x16x32_bf16 v[92:95], v[160:163], v[200:203], v[92:95]
	v_mfma_f32_16x16x32_bf16 v[84:87], v[152:155], v[208:211], v[84:87]
	v_mfma_f32_16x16x32_bf16 v[76:79], v[160:163], v[208:211], v[76:79]
	v_mfma_f32_16x16x32_bf16 v[124:127], v[156:159], v[188:191], v[124:127]
	v_mfma_f32_16x16x32_bf16 v[120:123], v[164:167], v[188:191], v[120:123]
	v_mfma_f32_16x16x32_bf16 v[116:119], v[156:159], v[196:199], v[116:119]
	v_mfma_f32_16x16x32_bf16 v[108:111], v[164:167], v[196:199], v[108:111]
	v_mfma_f32_16x16x32_bf16 v[100:103], v[156:159], v[204:207], v[100:103]
	v_mfma_f32_16x16x32_bf16 v[92:95], v[164:167], v[204:207], v[92:95]
	v_mfma_f32_16x16x32_bf16 v[84:87], v[156:159], v[212:215], v[84:87]
	v_mfma_f32_16x16x32_bf16 v[76:79], v[164:167], v[212:215], v[76:79]
	v_mfma_f32_16x16x32_bf16 v[112:115], v[168:171], v[184:187], v[112:115]
	v_mfma_f32_16x16x32_bf16 v[104:107], v[176:179], v[184:187], v[104:107]
	v_mfma_f32_16x16x32_bf16 v[96:99], v[168:171], v[192:195], v[96:99]
	v_mfma_f32_16x16x32_bf16 v[88:91], v[176:179], v[192:195], v[88:91]
	v_mfma_f32_16x16x32_bf16 v[80:83], v[168:171], v[200:203], v[80:83]
	v_mfma_f32_16x16x32_bf16 v[72:75], v[176:179], v[200:203], v[72:75]
	v_mfma_f32_16x16x32_bf16 v[68:71], v[168:171], v[208:211], v[68:71]
	v_mfma_f32_16x16x32_bf16 v[64:67], v[176:179], v[208:211], v[64:67]
	v_mfma_f32_16x16x32_bf16 v[112:115], v[172:175], v[188:191], v[112:115]
	v_mfma_f32_16x16x32_bf16 v[104:107], v[180:183], v[188:191], v[104:107]
	v_mfma_f32_16x16x32_bf16 v[96:99], v[172:175], v[196:199], v[96:99]
	v_mfma_f32_16x16x32_bf16 v[88:91], v[180:183], v[196:199], v[88:91]
	v_mfma_f32_16x16x32_bf16 v[80:83], v[172:175], v[204:207], v[80:83]
	v_mfma_f32_16x16x32_bf16 v[72:75], v[180:183], v[204:207], v[72:75]
	v_mfma_f32_16x16x32_bf16 v[68:71], v[172:175], v[212:215], v[68:71]
	v_mfma_f32_16x16x32_bf16 v[64:67], v[180:183], v[212:215], v[64:67]
	s_barrier
	s_add_i32 s28, s58, s31
	v_lshl_add_u64 v[146:147], v[146:147], 0, s[10:11]
	s_mov_b32 m0, s28
	ds_read_b128 v[184:187], v151 offset:49152
	ds_read_b128 v[188:191], v151 offset:50176
	ds_read_b128 v[192:195], v151 offset:51200
	ds_read_b128 v[196:199], v151 offset:52224
	ds_read_b128 v[200:203], v151 offset:53248
	ds_read_b128 v[204:207], v151 offset:54272
	ds_read_b128 v[208:211], v151 offset:55296
	ds_read_b128 v[212:215], v151 offset:56320
	global_load_lds_dwordx4 v[146:147], off
	s_add_i32 m0, s28, 0x2000
	s_add_u32 s26, s26, 0x100080
	v_lshl_add_u64 v[146:147], v[216:217], 0, s[10:11]
	s_addc_u32 s27, s27, 0
	s_add_i32 s28, s59, s31
	global_load_lds_dwordx4 v[146:147], off
	v_lshl_add_u64 v[146:147], s[26:27], 0, v[130:131]
	s_mov_b32 m0, s28
	s_nop 0
	global_load_lds_dwordx4 v[146:147], off
	v_lshl_add_u64 v[146:147], s[26:27], 0, v[134:135]
	s_add_i32 m0, s28, 0x2000
	s_nop 0
	global_load_lds_dwordx4 v[146:147], off
	v_lshl_add_u64 v[146:147], v[218:219], 0, s[10:11]
	s_mov_b32 m0, s41
	s_nop 0
	global_load_lds_dwordx4 v[146:147], off
	v_lshl_add_u64 v[146:147], v[220:221], 0, s[10:11]
	s_mov_b32 m0, s42
	s_nop 0
	global_load_lds_dwordx4 v[146:147], off
	s_waitcnt vmcnt(8)
	s_waitcnt lgkmcnt(0)
	s_barrier
	s_waitcnt lgkmcnt(0)
	v_mfma_f32_16x16x32_bf16 v[60:63], v[152:155], v[184:187], v[60:63]
	v_mfma_f32_16x16x32_bf16 v[56:59], v[160:163], v[184:187], v[56:59]
	v_mfma_f32_16x16x32_bf16 v[52:55], v[152:155], v[192:195], v[52:55]
	v_mfma_f32_16x16x32_bf16 v[44:47], v[160:163], v[192:195], v[44:47]
	v_mfma_f32_16x16x32_bf16 v[36:39], v[152:155], v[200:203], v[36:39]
	v_mfma_f32_16x16x32_bf16 v[28:31], v[160:163], v[200:203], v[28:31]
	v_mfma_f32_16x16x32_bf16 v[20:23], v[152:155], v[208:211], v[20:23]
	v_mfma_f32_16x16x32_bf16 v[12:15], v[160:163], v[208:211], v[12:15]
	v_mfma_f32_16x16x32_bf16 v[60:63], v[156:159], v[188:191], v[60:63]
	v_mfma_f32_16x16x32_bf16 v[56:59], v[164:167], v[188:191], v[56:59]
	v_mfma_f32_16x16x32_bf16 v[52:55], v[156:159], v[196:199], v[52:55]
	v_mfma_f32_16x16x32_bf16 v[44:47], v[164:167], v[196:199], v[44:47]
	v_mfma_f32_16x16x32_bf16 v[36:39], v[156:159], v[204:207], v[36:39]
	v_mfma_f32_16x16x32_bf16 v[28:31], v[164:167], v[204:207], v[28:31]
	v_mfma_f32_16x16x32_bf16 v[20:23], v[156:159], v[212:215], v[20:23]
	v_mfma_f32_16x16x32_bf16 v[12:15], v[164:167], v[212:215], v[12:15]
	v_mfma_f32_16x16x32_bf16 v[48:51], v[168:171], v[184:187], v[48:51]
	v_mfma_f32_16x16x32_bf16 v[40:43], v[176:179], v[184:187], v[40:43]
	v_mfma_f32_16x16x32_bf16 v[32:35], v[168:171], v[192:195], v[32:35]
	v_mfma_f32_16x16x32_bf16 v[24:27], v[176:179], v[192:195], v[24:27]
	v_mfma_f32_16x16x32_bf16 v[16:19], v[168:171], v[200:203], v[16:19]
	v_mfma_f32_16x16x32_bf16 v[8:11], v[176:179], v[200:203], v[8:11]
	v_mfma_f32_16x16x32_bf16 v[4:7], v[168:171], v[208:211], v[4:7]
	v_mfma_f32_16x16x32_bf16 v[0:3], v[176:179], v[208:211], v[0:3]
	v_mfma_f32_16x16x32_bf16 v[48:51], v[172:175], v[188:191], v[48:51]
	v_mfma_f32_16x16x32_bf16 v[40:43], v[180:183], v[188:191], v[40:43]
	v_mfma_f32_16x16x32_bf16 v[32:35], v[172:175], v[196:199], v[32:35]
	v_mfma_f32_16x16x32_bf16 v[24:27], v[180:183], v[196:199], v[24:27]
	v_mfma_f32_16x16x32_bf16 v[16:19], v[172:175], v[204:207], v[16:19]
	v_mfma_f32_16x16x32_bf16 v[8:11], v[180:183], v[204:207], v[8:11]
	v_mfma_f32_16x16x32_bf16 v[4:7], v[172:175], v[212:215], v[4:7]
	v_mfma_f32_16x16x32_bf16 v[0:3], v[180:183], v[212:215], v[0:3]
	s_add_i32 s57, s57, 2
	s_add_u32 s55, s55, 0x100
	s_addc_u32 s56, s56, 0
	s_add_u32 s24, s24, 0x100
	s_addc_u32 s25, s25, 0
	s_cmp_lt_u32 s57, 62
	s_barrier
	s_cbranch_scc1 .LBB13_20
	s_andn2_b64 vcc, exec, s[12:13]
	s_cbranch_vccnz .LBB13_23
	s_barrier
